# GEMM loops: accumulate-chain pairs in snake order over the fragment grid (consecutive pairs share one operand fragment)
# speedup vs baseline: 1.0407x; 1.0019x over previous
.LBB0_252:
	s_add_u32 s0, s0, 0x80
	s_addc_u32 s1, s1, 0
	s_add_u32 s47, s4, 0x100
	s_addc_u32 s48, s5, 0
	s_mov_b32 s4, 0
	s_waitcnt lgkmcnt(0)
	s_waitcnt vmcnt(0)
	s_add_i32 s49, s4, 2
	s_add_u32 s16, s0, 0x80
	s_addc_u32 s5, s1, 0
	s_add_i32 s65, 0, 0x10000
	ds_read_b128 v[148:151], v248
	ds_read_b128 v[152:155], v248 offset:1024
	ds_read_b128 v[156:159], v248 offset:2048
	ds_read_b128 v[160:163], v248 offset:3072
	s_cmp_eq_u32 s41, s4
	s_cselect_b32 s4, s10, s16
	s_cselect_b32 s5, s11, s5
	s_cselect_b32 s17, s13, s48
	s_cselect_b32 s16, s12, s47
	s_add_i32 m0, s26, 0xc000
	ds_read_b128 v[164:167], v146
	ds_read_b128 v[168:171], v146 offset:1024
	ds_read_b128 v[172:175], v146 offset:2048
	ds_read_b128 v[176:179], v146 offset:3072
	ds_read_b128 v[180:183], v146 offset:4096
	ds_read_b128 v[204:207], v146 offset:5120
	ds_read_b128 v[208:211], v146 offset:6144
	ds_read_b128 v[212:215], v146 offset:7168
	global_load_lds_dwordx4 v138, s[0:1]
	s_add_i32 m0, s26, 0xe000
	s_nop 0
	global_load_lds_dwordx4 v140, s[0:1]
	s_waitcnt lgkmcnt(8)
	s_barrier
	s_waitcnt lgkmcnt(0)
	v_mfma_f32_16x16x32_bf16 v[126:129], v[148:151], v[164:167], 0
	v_mfma_f32_16x16x32_bf16 v[126:129], v[152:155], v[168:171], v[126:129]
	v_mfma_f32_16x16x32_bf16 v[110:113], v[148:151], v[172:175], 0
	v_mfma_f32_16x16x32_bf16 v[110:113], v[152:155], v[176:179], v[110:113]
	v_mfma_f32_16x16x32_bf16 v[94:97], v[148:151], v[180:183], 0
	v_mfma_f32_16x16x32_bf16 v[94:97], v[152:155], v[204:207], v[94:97]
	v_mfma_f32_16x16x32_bf16 v[78:81], v[148:151], v[208:211], 0
	v_mfma_f32_16x16x32_bf16 v[78:81], v[152:155], v[212:215], v[78:81]
	v_mfma_f32_16x16x32_bf16 v[74:77], v[156:159], v[208:211], 0
	v_mfma_f32_16x16x32_bf16 v[74:77], v[160:163], v[212:215], v[74:77]
	v_mfma_f32_16x16x32_bf16 v[90:93], v[156:159], v[180:183], 0
	v_mfma_f32_16x16x32_bf16 v[90:93], v[160:163], v[204:207], v[90:93]
	v_mfma_f32_16x16x32_bf16 v[106:109], v[156:159], v[172:175], 0
	v_mfma_f32_16x16x32_bf16 v[106:109], v[160:163], v[176:179], v[106:109]
	v_mfma_f32_16x16x32_bf16 v[122:125], v[156:159], v[164:167], 0
	v_mfma_f32_16x16x32_bf16 v[122:125], v[160:163], v[168:171], v[122:125]
	s_barrier
	s_add_i32 s66, 0, 0x14000
	s_add_i32 s65, s65, s24
	ds_read_b128 v[216:219], v248 offset:16384
	ds_read_b128 v[220:223], v248 offset:17408
	ds_read_b128 v[224:227], v248 offset:18432
	ds_read_b128 v[228:231], v248 offset:19456
	s_add_u32 s70, s16, s6
	s_addc_u32 s71, s17, s7
	s_mov_b32 m0, s65
	s_nop 0
	global_load_lds_dwordx4 v132, s[16:17]
	s_add_i32 m0, s65, 0x2000
	s_nop 0
	global_load_lds_dwordx4 v136, s[16:17]
	s_barrier
	s_waitcnt lgkmcnt(0)
	v_mfma_f32_16x16x32_bf16 v[114:117], v[216:219], v[164:167], 0
	v_mfma_f32_16x16x32_bf16 v[114:117], v[220:223], v[168:171], v[114:117]
	v_mfma_f32_16x16x32_bf16 v[98:101], v[216:219], v[172:175], 0
	v_mfma_f32_16x16x32_bf16 v[98:101], v[220:223], v[176:179], v[98:101]
	v_mfma_f32_16x16x32_bf16 v[82:85], v[216:219], v[180:183], 0
	v_mfma_f32_16x16x32_bf16 v[82:85], v[220:223], v[204:207], v[82:85]
	v_mfma_f32_16x16x32_bf16 v[66:69], v[216:219], v[208:211], 0
	v_mfma_f32_16x16x32_bf16 v[66:69], v[220:223], v[212:215], v[66:69]
	v_mfma_f32_16x16x32_bf16 v[70:73], v[224:227], v[208:211], 0
	v_mfma_f32_16x16x32_bf16 v[70:73], v[228:231], v[212:215], v[70:73]
	v_mfma_f32_16x16x32_bf16 v[86:89], v[224:227], v[180:183], 0
	v_mfma_f32_16x16x32_bf16 v[86:89], v[228:231], v[204:207], v[86:89]
	v_mfma_f32_16x16x32_bf16 v[102:105], v[224:227], v[172:175], 0
	v_mfma_f32_16x16x32_bf16 v[102:105], v[228:231], v[176:179], v[102:105]
	v_mfma_f32_16x16x32_bf16 v[118:121], v[224:227], v[164:167], 0
	v_mfma_f32_16x16x32_bf16 v[118:121], v[228:231], v[168:171], v[118:121]
	s_barrier
	s_mov_b32 m0, s26
	s_add_u32 s72, s4, s6
	s_addc_u32 s73, s5, s7
	ds_read_b128 v[164:167], v146 offset:16384
	ds_read_b128 v[168:171], v146 offset:17408
	ds_read_b128 v[172:175], v146 offset:18432
	ds_read_b128 v[176:179], v146 offset:19456
	ds_read_b128 v[180:183], v146 offset:20480
	ds_read_b128 v[204:207], v146 offset:21504
	ds_read_b128 v[208:211], v146 offset:22528
	ds_read_b128 v[212:215], v146 offset:23552
	global_load_lds_dwordx4 v130, s[4:5]
	s_mov_b32 m0, s27
	s_nop 0
	global_load_lds_dwordx4 v134, s[4:5]
	s_barrier
	s_waitcnt lgkmcnt(0)
	v_mfma_f32_16x16x32_bf16 v[62:65], v[148:151], v[164:167], 0
	v_mfma_f32_16x16x32_bf16 v[62:65], v[152:155], v[168:171], v[62:65]
	v_mfma_f32_16x16x32_bf16 v[46:49], v[148:151], v[172:175], 0
	v_mfma_f32_16x16x32_bf16 v[46:49], v[152:155], v[176:179], v[46:49]
	v_mfma_f32_16x16x32_bf16 v[30:33], v[148:151], v[180:183], 0
	v_mfma_f32_16x16x32_bf16 v[30:33], v[152:155], v[204:207], v[30:33]
	v_mfma_f32_16x16x32_bf16 v[14:17], v[148:151], v[208:211], 0
	v_mfma_f32_16x16x32_bf16 v[14:17], v[152:155], v[212:215], v[14:17]
	v_mfma_f32_16x16x32_bf16 v[10:13], v[156:159], v[208:211], 0
	v_mfma_f32_16x16x32_bf16 v[10:13], v[160:163], v[212:215], v[10:13]
	v_mfma_f32_16x16x32_bf16 v[26:29], v[156:159], v[180:183], 0
	v_mfma_f32_16x16x32_bf16 v[26:29], v[160:163], v[204:207], v[26:29]
	v_mfma_f32_16x16x32_bf16 v[42:45], v[156:159], v[172:175], 0
	v_mfma_f32_16x16x32_bf16 v[42:45], v[160:163], v[176:179], v[42:45]
	v_mfma_f32_16x16x32_bf16 v[58:61], v[156:159], v[164:167], 0
	v_mfma_f32_16x16x32_bf16 v[58:61], v[160:163], v[168:171], v[58:61]
	s_barrier
	s_add_u32 s16, s16, s92
	s_addc_u32 s17, s17, 0
	s_add_i32 s65, s66, s24
	s_add_u32 s76, s16, s6
	s_addc_u32 s77, s17, s7
	s_mov_b32 m0, s65
	s_nop 0
	global_load_lds_dwordx4 v132, s[16:17]
	s_add_i32 m0, s65, 0x2000
	s_nop 0
	global_load_lds_dwordx4 v136, s[16:17]
	s_waitcnt vmcnt(6)
	s_barrier
	v_mfma_f32_16x16x32_bf16 v[50:53], v[216:219], v[164:167], 0
	v_mfma_f32_16x16x32_bf16 v[50:53], v[220:223], v[168:171], v[50:53]
	v_mfma_f32_16x16x32_bf16 v[34:37], v[216:219], v[172:175], 0
	v_mfma_f32_16x16x32_bf16 v[34:37], v[220:223], v[176:179], v[34:37]
	v_mfma_f32_16x16x32_bf16 v[18:21], v[216:219], v[180:183], 0
	v_mfma_f32_16x16x32_bf16 v[18:21], v[220:223], v[204:207], v[18:21]
	v_mfma_f32_16x16x32_bf16 v[6:9], v[216:219], v[208:211], 0
	v_mfma_f32_16x16x32_bf16 v[6:9], v[220:223], v[212:215], v[6:9]
	v_mfma_f32_16x16x32_bf16 v[2:5], v[224:227], v[208:211], 0
	v_mfma_f32_16x16x32_bf16 v[2:5], v[228:231], v[212:215], v[2:5]
	v_mfma_f32_16x16x32_bf16 v[22:25], v[224:227], v[180:183], 0
	v_mfma_f32_16x16x32_bf16 v[22:25], v[228:231], v[204:207], v[22:25]
	v_mfma_f32_16x16x32_bf16 v[38:41], v[224:227], v[172:175], 0
	v_mfma_f32_16x16x32_bf16 v[38:41], v[228:231], v[176:179], v[38:41]
	v_mfma_f32_16x16x32_bf16 v[54:57], v[224:227], v[164:167], 0
	v_mfma_f32_16x16x32_bf16 v[54:57], v[228:231], v[168:171], v[54:57]
	s_barrier
	s_add_i32 s16, 0, 0x18000
	ds_read_b128 v[148:151], v248 offset:32768
	ds_read_b128 v[152:155], v248 offset:33792
	ds_read_b128 v[156:159], v248 offset:34816
	ds_read_b128 v[160:163], v248 offset:35840
	s_add_u32 s4, s4, s92
	s_addc_u32 s5, s5, 0
	s_mov_b32 m0, s28
	ds_read_b128 v[164:167], v146 offset:32768
	ds_read_b128 v[168:171], v146 offset:33792
	ds_read_b128 v[172:175], v146 offset:34816
	ds_read_b128 v[176:179], v146 offset:35840
	ds_read_b128 v[180:183], v146 offset:36864
	ds_read_b128 v[204:207], v146 offset:37888
	ds_read_b128 v[208:211], v146 offset:38912
	ds_read_b128 v[212:215], v146 offset:39936
	global_load_lds_dwordx4 v130, s[4:5]
	s_mov_b32 m0, s29
	s_nop 0
	global_load_lds_dwordx4 v134, s[4:5]
	s_waitcnt lgkmcnt(8)
	s_barrier
	s_waitcnt lgkmcnt(0)
	v_mfma_f32_16x16x32_bf16 v[126:129], v[148:151], v[164:167], v[126:129]
	v_mfma_f32_16x16x32_bf16 v[126:129], v[152:155], v[168:171], v[126:129]
	v_mfma_f32_16x16x32_bf16 v[110:113], v[148:151], v[172:175], v[110:113]
	v_mfma_f32_16x16x32_bf16 v[110:113], v[152:155], v[176:179], v[110:113]
	v_mfma_f32_16x16x32_bf16 v[94:97], v[148:151], v[180:183], v[94:97]
	v_mfma_f32_16x16x32_bf16 v[94:97], v[152:155], v[204:207], v[94:97]
	v_mfma_f32_16x16x32_bf16 v[78:81], v[148:151], v[208:211], v[78:81]
	v_mfma_f32_16x16x32_bf16 v[78:81], v[152:155], v[212:215], v[78:81]
	v_mfma_f32_16x16x32_bf16 v[74:77], v[156:159], v[208:211], v[74:77]
	v_mfma_f32_16x16x32_bf16 v[74:77], v[160:163], v[212:215], v[74:77]
	v_mfma_f32_16x16x32_bf16 v[90:93], v[156:159], v[180:183], v[90:93]
	v_mfma_f32_16x16x32_bf16 v[90:93], v[160:163], v[204:207], v[90:93]
	v_mfma_f32_16x16x32_bf16 v[106:109], v[156:159], v[172:175], v[106:109]
	v_mfma_f32_16x16x32_bf16 v[106:109], v[160:163], v[176:179], v[106:109]
	v_mfma_f32_16x16x32_bf16 v[122:125], v[156:159], v[164:167], v[122:125]
	v_mfma_f32_16x16x32_bf16 v[122:125], v[160:163], v[168:171], v[122:125]
	s_barrier
	s_add_i32 s4, 0, 0x1c000
	s_add_i32 s5, s16, s24
	s_mov_b32 m0, s5
	ds_read_b128 v[216:219], v248 offset:49152
	ds_read_b128 v[220:223], v248 offset:50176
	ds_read_b128 v[224:227], v248 offset:51200
	ds_read_b128 v[228:231], v248 offset:52224
	global_load_lds_dwordx4 v132, s[70:71]
	s_add_i32 m0, s5, 0x2000
	s_nop 0
	global_load_lds_dwordx4 v136, s[70:71]
	s_barrier
	s_waitcnt lgkmcnt(0)
	v_mfma_f32_16x16x32_bf16 v[114:117], v[216:219], v[164:167], v[114:117]
	v_mfma_f32_16x16x32_bf16 v[114:117], v[220:223], v[168:171], v[114:117]
	v_mfma_f32_16x16x32_bf16 v[98:101], v[216:219], v[172:175], v[98:101]
	v_mfma_f32_16x16x32_bf16 v[98:101], v[220:223], v[176:179], v[98:101]
	v_mfma_f32_16x16x32_bf16 v[82:85], v[216:219], v[180:183], v[82:85]
	v_mfma_f32_16x16x32_bf16 v[82:85], v[220:223], v[204:207], v[82:85]
	v_mfma_f32_16x16x32_bf16 v[66:69], v[216:219], v[208:211], v[66:69]
	v_mfma_f32_16x16x32_bf16 v[66:69], v[220:223], v[212:215], v[66:69]
	v_mfma_f32_16x16x32_bf16 v[70:73], v[224:227], v[208:211], v[70:73]
	v_mfma_f32_16x16x32_bf16 v[70:73], v[228:231], v[212:215], v[70:73]
	v_mfma_f32_16x16x32_bf16 v[86:89], v[224:227], v[180:183], v[86:89]
	v_mfma_f32_16x16x32_bf16 v[86:89], v[228:231], v[204:207], v[86:89]
	v_mfma_f32_16x16x32_bf16 v[102:105], v[224:227], v[172:175], v[102:105]
	v_mfma_f32_16x16x32_bf16 v[102:105], v[228:231], v[176:179], v[102:105]
	v_mfma_f32_16x16x32_bf16 v[118:121], v[224:227], v[164:167], v[118:121]
	v_mfma_f32_16x16x32_bf16 v[118:121], v[228:231], v[168:171], v[118:121]
	s_barrier
	s_mov_b32 m0, s35
	ds_read_b128 v[164:167], v146 offset:49152
	ds_read_b128 v[168:171], v146 offset:50176
	ds_read_b128 v[172:175], v146 offset:51200
	ds_read_b128 v[176:179], v146 offset:52224
	ds_read_b128 v[180:183], v146 offset:53248
	ds_read_b128 v[204:207], v146 offset:54272
	ds_read_b128 v[208:211], v146 offset:55296
	ds_read_b128 v[212:215], v146 offset:56320
	global_load_lds_dwordx4 v130, s[72:73]
	s_mov_b32 m0, s40
	s_nop 0
	global_load_lds_dwordx4 v134, s[72:73]
	s_barrier
	s_waitcnt lgkmcnt(0)
	v_mfma_f32_16x16x32_bf16 v[62:65], v[148:151], v[164:167], v[62:65]
	v_mfma_f32_16x16x32_bf16 v[62:65], v[152:155], v[168:171], v[62:65]
	v_mfma_f32_16x16x32_bf16 v[46:49], v[148:151], v[172:175], v[46:49]
	v_mfma_f32_16x16x32_bf16 v[46:49], v[152:155], v[176:179], v[46:49]
	v_mfma_f32_16x16x32_bf16 v[30:33], v[148:151], v[180:183], v[30:33]
	v_mfma_f32_16x16x32_bf16 v[30:33], v[152:155], v[204:207], v[30:33]
	v_mfma_f32_16x16x32_bf16 v[14:17], v[148:151], v[208:211], v[14:17]
	v_mfma_f32_16x16x32_bf16 v[14:17], v[152:155], v[212:215], v[14:17]
	v_mfma_f32_16x16x32_bf16 v[10:13], v[156:159], v[208:211], v[10:13]
	v_mfma_f32_16x16x32_bf16 v[10:13], v[160:163], v[212:215], v[10:13]
	v_mfma_f32_16x16x32_bf16 v[26:29], v[156:159], v[180:183], v[26:29]
	v_mfma_f32_16x16x32_bf16 v[26:29], v[160:163], v[204:207], v[26:29]
	v_mfma_f32_16x16x32_bf16 v[42:45], v[156:159], v[172:175], v[42:45]
	v_mfma_f32_16x16x32_bf16 v[42:45], v[160:163], v[176:179], v[42:45]
	v_mfma_f32_16x16x32_bf16 v[58:61], v[156:159], v[164:167], v[58:61]
	v_mfma_f32_16x16x32_bf16 v[58:61], v[160:163], v[168:171], v[58:61]
	s_barrier
	s_add_i32 s4, s4, s24
	s_mov_b32 m0, s4
	s_nop 0
	global_load_lds_dwordx4 v132, s[76:77]
	s_add_i32 m0, s4, 0x2000
	s_nop 0
	global_load_lds_dwordx4 v136, s[76:77]
	s_add_u32 s0, s0, 0x100
	s_addc_u32 s1, s1, 0
	s_add_u32 s47, s47, 0x100
	s_addc_u32 s48, s48, 0
	s_cmp_ge_u32 s49, s30
	s_mov_b32 s4, s49
	s_waitcnt vmcnt(6)
	s_barrier
	v_mfma_f32_16x16x32_bf16 v[50:53], v[216:219], v[164:167], v[50:53]
	v_mfma_f32_16x16x32_bf16 v[50:53], v[220:223], v[168:171], v[50:53]
	v_mfma_f32_16x16x32_bf16 v[34:37], v[216:219], v[172:175], v[34:37]
	v_mfma_f32_16x16x32_bf16 v[34:37], v[220:223], v[176:179], v[34:37]
	v_mfma_f32_16x16x32_bf16 v[18:21], v[216:219], v[180:183], v[18:21]
	v_mfma_f32_16x16x32_bf16 v[18:21], v[220:223], v[204:207], v[18:21]
	v_mfma_f32_16x16x32_bf16 v[6:9], v[216:219], v[208:211], v[6:9]
	v_mfma_f32_16x16x32_bf16 v[6:9], v[220:223], v[212:215], v[6:9]
	v_mfma_f32_16x16x32_bf16 v[2:5], v[224:227], v[208:211], v[2:5]
	v_mfma_f32_16x16x32_bf16 v[2:5], v[228:231], v[212:215], v[2:5]
	v_mfma_f32_16x16x32_bf16 v[22:25], v[224:227], v[180:183], v[22:25]
	v_mfma_f32_16x16x32_bf16 v[22:25], v[228:231], v[204:207], v[22:25]
	v_mfma_f32_16x16x32_bf16 v[38:41], v[224:227], v[172:175], v[38:41]
	v_mfma_f32_16x16x32_bf16 v[38:41], v[228:231], v[176:179], v[38:41]
	v_mfma_f32_16x16x32_bf16 v[54:57], v[224:227], v[164:167], v[54:57]
	v_mfma_f32_16x16x32_bf16 v[54:57], v[228:231], v[168:171], v[54:57]
	s_barrier
	s_cbranch_scc1 .Lkexit_253
.LBB0_253:
	s_add_i32 s49, s4, 2
	s_add_u32 s16, s0, 0x80
	s_addc_u32 s5, s1, 0
	s_add_i32 s65, 0, 0x10000
	ds_read_b128 v[148:151], v248
	ds_read_b128 v[152:155], v248 offset:1024
	ds_read_b128 v[156:159], v248 offset:2048
	ds_read_b128 v[160:163], v248 offset:3072
	s_cmp_eq_u32 s41, s4
	s_cselect_b32 s4, s10, s16
	s_cselect_b32 s5, s11, s5
	s_cselect_b32 s17, s13, s48
	s_cselect_b32 s16, s12, s47
	s_add_i32 m0, s26, 0xc000
	ds_read_b128 v[164:167], v146
	ds_read_b128 v[168:171], v146 offset:1024
	ds_read_b128 v[172:175], v146 offset:2048
	ds_read_b128 v[176:179], v146 offset:3072
	ds_read_b128 v[180:183], v146 offset:4096
	ds_read_b128 v[204:207], v146 offset:5120
	ds_read_b128 v[208:211], v146 offset:6144
	ds_read_b128 v[212:215], v146 offset:7168
	global_load_lds_dwordx4 v138, s[0:1]
	s_add_i32 m0, s26, 0xe000
	s_nop 0
	global_load_lds_dwordx4 v140, s[0:1]
	s_waitcnt lgkmcnt(8)
	s_barrier
	s_waitcnt lgkmcnt(0)
	v_mfma_f32_16x16x32_bf16 v[126:129], v[148:151], v[164:167], v[126:129]
	v_mfma_f32_16x16x32_bf16 v[126:129], v[152:155], v[168:171], v[126:129]
	v_mfma_f32_16x16x32_bf16 v[110:113], v[148:151], v[172:175], v[110:113]
	v_mfma_f32_16x16x32_bf16 v[110:113], v[152:155], v[176:179], v[110:113]
	v_mfma_f32_16x16x32_bf16 v[94:97], v[148:151], v[180:183], v[94:97]
	v_mfma_f32_16x16x32_bf16 v[94:97], v[152:155], v[204:207], v[94:97]
	v_mfma_f32_16x16x32_bf16 v[78:81], v[148:151], v[208:211], v[78:81]
	v_mfma_f32_16x16x32_bf16 v[78:81], v[152:155], v[212:215], v[78:81]
	v_mfma_f32_16x16x32_bf16 v[74:77], v[156:159], v[208:211], v[74:77]
	v_mfma_f32_16x16x32_bf16 v[74:77], v[160:163], v[212:215], v[74:77]
	v_mfma_f32_16x16x32_bf16 v[90:93], v[156:159], v[180:183], v[90:93]
	v_mfma_f32_16x16x32_bf16 v[90:93], v[160:163], v[204:207], v[90:93]
	v_mfma_f32_16x16x32_bf16 v[106:109], v[156:159], v[172:175], v[106:109]
	v_mfma_f32_16x16x32_bf16 v[106:109], v[160:163], v[176:179], v[106:109]
	v_mfma_f32_16x16x32_bf16 v[122:125], v[156:159], v[164:167], v[122:125]
	v_mfma_f32_16x16x32_bf16 v[122:125], v[160:163], v[168:171], v[122:125]
	s_barrier
	s_add_i32 s66, 0, 0x14000
	s_add_i32 s65, s65, s24
	ds_read_b128 v[216:219], v248 offset:16384
	ds_read_b128 v[220:223], v248 offset:17408
	ds_read_b128 v[224:227], v248 offset:18432
	ds_read_b128 v[228:231], v248 offset:19456
	s_add_u32 s70, s16, s6
	s_addc_u32 s71, s17, s7
	s_mov_b32 m0, s65
	s_nop 0
	global_load_lds_dwordx4 v132, s[16:17]
	s_add_i32 m0, s65, 0x2000
	s_nop 0
	global_load_lds_dwordx4 v136, s[16:17]
	s_barrier
	s_waitcnt lgkmcnt(0)
	v_mfma_f32_16x16x32_bf16 v[114:117], v[216:219], v[164:167], v[114:117]
	v_mfma_f32_16x16x32_bf16 v[114:117], v[220:223], v[168:171], v[114:117]
	v_mfma_f32_16x16x32_bf16 v[98:101], v[216:219], v[172:175], v[98:101]
	v_mfma_f32_16x16x32_bf16 v[98:101], v[220:223], v[176:179], v[98:101]
	v_mfma_f32_16x16x32_bf16 v[82:85], v[216:219], v[180:183], v[82:85]
	v_mfma_f32_16x16x32_bf16 v[82:85], v[220:223], v[204:207], v[82:85]
	v_mfma_f32_16x16x32_bf16 v[66:69], v[216:219], v[208:211], v[66:69]
	v_mfma_f32_16x16x32_bf16 v[66:69], v[220:223], v[212:215], v[66:69]
	v_mfma_f32_16x16x32_bf16 v[70:73], v[224:227], v[208:211], v[70:73]
	v_mfma_f32_16x16x32_bf16 v[70:73], v[228:231], v[212:215], v[70:73]
	v_mfma_f32_16x16x32_bf16 v[86:89], v[224:227], v[180:183], v[86:89]
	v_mfma_f32_16x16x32_bf16 v[86:89], v[228:231], v[204:207], v[86:89]
	v_mfma_f32_16x16x32_bf16 v[102:105], v[224:227], v[172:175], v[102:105]
	v_mfma_f32_16x16x32_bf16 v[102:105], v[228:231], v[176:179], v[102:105]
	v_mfma_f32_16x16x32_bf16 v[118:121], v[224:227], v[164:167], v[118:121]
	v_mfma_f32_16x16x32_bf16 v[118:121], v[228:231], v[168:171], v[118:121]
	s_barrier
	s_mov_b32 m0, s26
	s_add_u32 s72, s4, s6
	s_addc_u32 s73, s5, s7
	ds_read_b128 v[164:167], v146 offset:16384
	ds_read_b128 v[168:171], v146 offset:17408
	ds_read_b128 v[172:175], v146 offset:18432
	ds_read_b128 v[176:179], v146 offset:19456
	ds_read_b128 v[180:183], v146 offset:20480
	ds_read_b128 v[204:207], v146 offset:21504
	ds_read_b128 v[208:211], v146 offset:22528
	ds_read_b128 v[212:215], v146 offset:23552
	global_load_lds_dwordx4 v130, s[4:5]
	s_mov_b32 m0, s27
	s_nop 0
	global_load_lds_dwordx4 v134, s[4:5]
	s_barrier
	s_waitcnt lgkmcnt(0)
	v_mfma_f32_16x16x32_bf16 v[62:65], v[148:151], v[164:167], v[62:65]
	v_mfma_f32_16x16x32_bf16 v[62:65], v[152:155], v[168:171], v[62:65]
	v_mfma_f32_16x16x32_bf16 v[46:49], v[148:151], v[172:175], v[46:49]
	v_mfma_f32_16x16x32_bf16 v[46:49], v[152:155], v[176:179], v[46:49]
	v_mfma_f32_16x16x32_bf16 v[30:33], v[148:151], v[180:183], v[30:33]
	v_mfma_f32_16x16x32_bf16 v[30:33], v[152:155], v[204:207], v[30:33]
	v_mfma_f32_16x16x32_bf16 v[14:17], v[148:151], v[208:211], v[14:17]
	v_mfma_f32_16x16x32_bf16 v[14:17], v[152:155], v[212:215], v[14:17]
	v_mfma_f32_16x16x32_bf16 v[10:13], v[156:159], v[208:211], v[10:13]
	v_mfma_f32_16x16x32_bf16 v[10:13], v[160:163], v[212:215], v[10:13]
	v_mfma_f32_16x16x32_bf16 v[26:29], v[156:159], v[180:183], v[26:29]
	v_mfma_f32_16x16x32_bf16 v[26:29], v[160:163], v[204:207], v[26:29]
	v_mfma_f32_16x16x32_bf16 v[42:45], v[156:159], v[172:175], v[42:45]
	v_mfma_f32_16x16x32_bf16 v[42:45], v[160:163], v[176:179], v[42:45]
	v_mfma_f32_16x16x32_bf16 v[58:61], v[156:159], v[164:167], v[58:61]
	v_mfma_f32_16x16x32_bf16 v[58:61], v[160:163], v[168:171], v[58:61]
	s_barrier
	s_add_u32 s16, s16, s92
	s_addc_u32 s17, s17, 0
	s_add_i32 s65, s66, s24
	s_add_u32 s76, s16, s6
	s_addc_u32 s77, s17, s7
	s_mov_b32 m0, s65
	s_nop 0
	global_load_lds_dwordx4 v132, s[16:17]
	s_add_i32 m0, s65, 0x2000
	s_nop 0
	global_load_lds_dwordx4 v136, s[16:17]
	s_waitcnt vmcnt(6)
	s_barrier
	v_mfma_f32_16x16x32_bf16 v[50:53], v[216:219], v[164:167], v[50:53]
	v_mfma_f32_16x16x32_bf16 v[50:53], v[220:223], v[168:171], v[50:53]
	v_mfma_f32_16x16x32_bf16 v[34:37], v[216:219], v[172:175], v[34:37]
	v_mfma_f32_16x16x32_bf16 v[34:37], v[220:223], v[176:179], v[34:37]
	v_mfma_f32_16x16x32_bf16 v[18:21], v[216:219], v[180:183], v[18:21]
	v_mfma_f32_16x16x32_bf16 v[18:21], v[220:223], v[204:207], v[18:21]
	v_mfma_f32_16x16x32_bf16 v[6:9], v[216:219], v[208:211], v[6:9]
	v_mfma_f32_16x16x32_bf16 v[6:9], v[220:223], v[212:215], v[6:9]
	v_mfma_f32_16x16x32_bf16 v[2:5], v[224:227], v[208:211], v[2:5]
	v_mfma_f32_16x16x32_bf16 v[2:5], v[228:231], v[212:215], v[2:5]
	v_mfma_f32_16x16x32_bf16 v[22:25], v[224:227], v[180:183], v[22:25]
	v_mfma_f32_16x16x32_bf16 v[22:25], v[228:231], v[204:207], v[22:25]
	v_mfma_f32_16x16x32_bf16 v[38:41], v[224:227], v[172:175], v[38:41]
	v_mfma_f32_16x16x32_bf16 v[38:41], v[228:231], v[176:179], v[38:41]
	v_mfma_f32_16x16x32_bf16 v[54:57], v[224:227], v[164:167], v[54:57]
	v_mfma_f32_16x16x32_bf16 v[54:57], v[228:231], v[168:171], v[54:57]
	s_barrier
	s_add_i32 s16, 0, 0x18000
	ds_read_b128 v[148:151], v248 offset:32768
	ds_read_b128 v[152:155], v248 offset:33792
	ds_read_b128 v[156:159], v248 offset:34816
	ds_read_b128 v[160:163], v248 offset:35840
	s_add_u32 s4, s4, s92
	s_addc_u32 s5, s5, 0
	s_mov_b32 m0, s28
	ds_read_b128 v[164:167], v146 offset:32768
	ds_read_b128 v[168:171], v146 offset:33792
	ds_read_b128 v[172:175], v146 offset:34816
	ds_read_b128 v[176:179], v146 offset:35840
	ds_read_b128 v[180:183], v146 offset:36864
	ds_read_b128 v[204:207], v146 offset:37888
	ds_read_b128 v[208:211], v146 offset:38912
	ds_read_b128 v[212:215], v146 offset:39936
	global_load_lds_dwordx4 v130, s[4:5]
	s_mov_b32 m0, s29
	s_nop 0
	global_load_lds_dwordx4 v134, s[4:5]
	s_waitcnt lgkmcnt(8)
	s_barrier
	s_waitcnt lgkmcnt(0)
	v_mfma_f32_16x16x32_bf16 v[126:129], v[148:151], v[164:167], v[126:129]
	v_mfma_f32_16x16x32_bf16 v[126:129], v[152:155], v[168:171], v[126:129]
	v_mfma_f32_16x16x32_bf16 v[110:113], v[148:151], v[172:175], v[110:113]
	v_mfma_f32_16x16x32_bf16 v[110:113], v[152:155], v[176:179], v[110:113]
	v_mfma_f32_16x16x32_bf16 v[94:97], v[148:151], v[180:183], v[94:97]
	v_mfma_f32_16x16x32_bf16 v[94:97], v[152:155], v[204:207], v[94:97]
	v_mfma_f32_16x16x32_bf16 v[78:81], v[148:151], v[208:211], v[78:81]
	v_mfma_f32_16x16x32_bf16 v[78:81], v[152:155], v[212:215], v[78:81]
	v_mfma_f32_16x16x32_bf16 v[74:77], v[156:159], v[208:211], v[74:77]
	v_mfma_f32_16x16x32_bf16 v[74:77], v[160:163], v[212:215], v[74:77]
	v_mfma_f32_16x16x32_bf16 v[90:93], v[156:159], v[180:183], v[90:93]
	v_mfma_f32_16x16x32_bf16 v[90:93], v[160:163], v[204:207], v[90:93]
	v_mfma_f32_16x16x32_bf16 v[106:109], v[156:159], v[172:175], v[106:109]
	v_mfma_f32_16x16x32_bf16 v[106:109], v[160:163], v[176:179], v[106:109]
	v_mfma_f32_16x16x32_bf16 v[122:125], v[156:159], v[164:167], v[122:125]
	v_mfma_f32_16x16x32_bf16 v[122:125], v[160:163], v[168:171], v[122:125]
	s_barrier
	s_add_i32 s4, 0, 0x1c000
	s_add_i32 s5, s16, s24
	s_mov_b32 m0, s5
	ds_read_b128 v[216:219], v248 offset:49152
	ds_read_b128 v[220:223], v248 offset:50176
	ds_read_b128 v[224:227], v248 offset:51200
	ds_read_b128 v[228:231], v248 offset:52224
	global_load_lds_dwordx4 v132, s[70:71]
	s_add_i32 m0, s5, 0x2000
	s_nop 0
	global_load_lds_dwordx4 v136, s[70:71]
	s_barrier
	s_waitcnt lgkmcnt(0)
	v_mfma_f32_16x16x32_bf16 v[114:117], v[216:219], v[164:167], v[114:117]
	v_mfma_f32_16x16x32_bf16 v[114:117], v[220:223], v[168:171], v[114:117]
	v_mfma_f32_16x16x32_bf16 v[98:101], v[216:219], v[172:175], v[98:101]
	v_mfma_f32_16x16x32_bf16 v[98:101], v[220:223], v[176:179], v[98:101]
	v_mfma_f32_16x16x32_bf16 v[82:85], v[216:219], v[180:183], v[82:85]
	v_mfma_f32_16x16x32_bf16 v[82:85], v[220:223], v[204:207], v[82:85]
	v_mfma_f32_16x16x32_bf16 v[66:69], v[216:219], v[208:211], v[66:69]
	v_mfma_f32_16x16x32_bf16 v[66:69], v[220:223], v[212:215], v[66:69]
	v_mfma_f32_16x16x32_bf16 v[70:73], v[224:227], v[208:211], v[70:73]
	v_mfma_f32_16x16x32_bf16 v[70:73], v[228:231], v[212:215], v[70:73]
	v_mfma_f32_16x16x32_bf16 v[86:89], v[224:227], v[180:183], v[86:89]
	v_mfma_f32_16x16x32_bf16 v[86:89], v[228:231], v[204:207], v[86:89]
	v_mfma_f32_16x16x32_bf16 v[102:105], v[224:227], v[172:175], v[102:105]
	v_mfma_f32_16x16x32_bf16 v[102:105], v[228:231], v[176:179], v[102:105]
	v_mfma_f32_16x16x32_bf16 v[118:121], v[224:227], v[164:167], v[118:121]
	v_mfma_f32_16x16x32_bf16 v[118:121], v[228:231], v[168:171], v[118:121]
	s_barrier
	s_mov_b32 m0, s35
	ds_read_b128 v[164:167], v146 offset:49152
	ds_read_b128 v[168:171], v146 offset:50176
	ds_read_b128 v[172:175], v146 offset:51200
	ds_read_b128 v[176:179], v146 offset:52224
	ds_read_b128 v[180:183], v146 offset:53248
	ds_read_b128 v[204:207], v146 offset:54272
	ds_read_b128 v[208:211], v146 offset:55296
	ds_read_b128 v[212:215], v146 offset:56320
	global_load_lds_dwordx4 v130, s[72:73]
	s_mov_b32 m0, s40
	s_nop 0
	global_load_lds_dwordx4 v134, s[72:73]
	s_barrier
	s_waitcnt lgkmcnt(0)
	v_mfma_f32_16x16x32_bf16 v[62:65], v[148:151], v[164:167], v[62:65]
	v_mfma_f32_16x16x32_bf16 v[62:65], v[152:155], v[168:171], v[62:65]
	v_mfma_f32_16x16x32_bf16 v[46:49], v[148:151], v[172:175], v[46:49]
	v_mfma_f32_16x16x32_bf16 v[46:49], v[152:155], v[176:179], v[46:49]
	v_mfma_f32_16x16x32_bf16 v[30:33], v[148:151], v[180:183], v[30:33]
	v_mfma_f32_16x16x32_bf16 v[30:33], v[152:155], v[204:207], v[30:33]
	v_mfma_f32_16x16x32_bf16 v[14:17], v[148:151], v[208:211], v[14:17]
	v_mfma_f32_16x16x32_bf16 v[14:17], v[152:155], v[212:215], v[14:17]
	v_mfma_f32_16x16x32_bf16 v[10:13], v[156:159], v[208:211], v[10:13]
	v_mfma_f32_16x16x32_bf16 v[10:13], v[160:163], v[212:215], v[10:13]
	v_mfma_f32_16x16x32_bf16 v[26:29], v[156:159], v[180:183], v[26:29]
	v_mfma_f32_16x16x32_bf16 v[26:29], v[160:163], v[204:207], v[26:29]
	v_mfma_f32_16x16x32_bf16 v[42:45], v[156:159], v[172:175], v[42:45]
	v_mfma_f32_16x16x32_bf16 v[42:45], v[160:163], v[176:179], v[42:45]
	v_mfma_f32_16x16x32_bf16 v[58:61], v[156:159], v[164:167], v[58:61]
	v_mfma_f32_16x16x32_bf16 v[58:61], v[160:163], v[168:171], v[58:61]
	s_barrier
	s_add_i32 s4, s4, s24
	s_mov_b32 m0, s4
	s_nop 0
	global_load_lds_dwordx4 v132, s[76:77]
	s_add_i32 m0, s4, 0x2000
	s_nop 0
	global_load_lds_dwordx4 v136, s[76:77]
	s_add_u32 s0, s0, 0x100
	s_addc_u32 s1, s1, 0
	s_add_u32 s47, s47, 0x100
	s_addc_u32 s48, s48, 0
	s_cmp_ge_u32 s49, s30
	s_mov_b32 s4, s49
	s_waitcnt vmcnt(6)
	s_barrier
	v_mfma_f32_16x16x32_bf16 v[50:53], v[216:219], v[164:167], v[50:53]
	v_mfma_f32_16x16x32_bf16 v[50:53], v[220:223], v[168:171], v[50:53]
	v_mfma_f32_16x16x32_bf16 v[34:37], v[216:219], v[172:175], v[34:37]
	v_mfma_f32_16x16x32_bf16 v[34:37], v[220:223], v[176:179], v[34:37]
	v_mfma_f32_16x16x32_bf16 v[18:21], v[216:219], v[180:183], v[18:21]
	v_mfma_f32_16x16x32_bf16 v[18:21], v[220:223], v[204:207], v[18:21]
	v_mfma_f32_16x16x32_bf16 v[6:9], v[216:219], v[208:211], v[6:9]
	v_mfma_f32_16x16x32_bf16 v[6:9], v[220:223], v[212:215], v[6:9]
	v_mfma_f32_16x16x32_bf16 v[2:5], v[224:227], v[208:211], v[2:5]
	v_mfma_f32_16x16x32_bf16 v[2:5], v[228:231], v[212:215], v[2:5]
	v_mfma_f32_16x16x32_bf16 v[22:25], v[224:227], v[180:183], v[22:25]
	v_mfma_f32_16x16x32_bf16 v[22:25], v[228:231], v[204:207], v[22:25]
	v_mfma_f32_16x16x32_bf16 v[38:41], v[224:227], v[172:175], v[38:41]
	v_mfma_f32_16x16x32_bf16 v[38:41], v[228:231], v[176:179], v[38:41]
	v_mfma_f32_16x16x32_bf16 v[54:57], v[224:227], v[164:167], v[54:57]
	v_mfma_f32_16x16x32_bf16 v[54:57], v[228:231], v[168:171], v[54:57]
	s_barrier
	s_cbranch_scc0 .LBB0_253

.LBB0_281:
	s_add_u32 s0, s0, 0x80
	s_addc_u32 s1, s1, 0
	s_add_u32 s20, s4, 0x100
	s_addc_u32 s21, s5, 0
	s_mov_b32 s4, 0
	s_waitcnt lgkmcnt(0)
	s_add_i32 s22, s4, 2
	s_add_u32 s10, s0, 0x80
	s_addc_u32 s5, s1, 0
	s_add_i32 s23, 0, 0x10000
	ds_read_b128 v[142:145], v248
	ds_read_b128 v[146:149], v248 offset:1024
	ds_read_b128 v[150:153], v248 offset:2048
	ds_read_b128 v[154:157], v248 offset:3072
	s_cmp_eq_u32 s44, s4
	s_cselect_b32 s4, s16, s10
	s_cselect_b32 s5, s17, s5
	s_cselect_b32 s11, s13, s21
	s_cselect_b32 s10, s12, s20
	s_add_i32 m0, s29, 0xc000
	ds_read_b128 v[158:161], v166
	ds_read_b128 v[168:171], v166 offset:1024
	ds_read_b128 v[172:175], v166 offset:2048
	ds_read_b128 v[176:179], v166 offset:3072
	ds_read_b128 v[180:183], v166 offset:4096
	ds_read_b128 v[204:207], v166 offset:5120
	ds_read_b128 v[208:211], v166 offset:6144
	ds_read_b128 v[212:215], v166 offset:7168
	global_load_lds_dwordx4 v138, s[0:1]
	s_add_i32 m0, s29, 0xe000
	s_nop 0
	global_load_lds_dwordx4 v140, s[0:1]
	s_waitcnt lgkmcnt(8)
	s_barrier
	s_waitcnt lgkmcnt(0)
	v_mfma_f32_16x16x32_bf16 v[126:129], v[142:145], v[158:161], 0
	v_mfma_f32_16x16x32_bf16 v[126:129], v[146:149], v[168:171], v[126:129]
	v_mfma_f32_16x16x32_bf16 v[110:113], v[142:145], v[172:175], 0
	v_mfma_f32_16x16x32_bf16 v[110:113], v[146:149], v[176:179], v[110:113]
	v_mfma_f32_16x16x32_bf16 v[94:97], v[142:145], v[180:183], 0
	v_mfma_f32_16x16x32_bf16 v[94:97], v[146:149], v[204:207], v[94:97]
	v_mfma_f32_16x16x32_bf16 v[78:81], v[142:145], v[208:211], 0
	v_mfma_f32_16x16x32_bf16 v[78:81], v[146:149], v[212:215], v[78:81]
	v_mfma_f32_16x16x32_bf16 v[74:77], v[150:153], v[208:211], 0
	v_mfma_f32_16x16x32_bf16 v[74:77], v[154:157], v[212:215], v[74:77]
	v_mfma_f32_16x16x32_bf16 v[90:93], v[150:153], v[180:183], 0
	v_mfma_f32_16x16x32_bf16 v[90:93], v[154:157], v[204:207], v[90:93]
	v_mfma_f32_16x16x32_bf16 v[106:109], v[150:153], v[172:175], 0
	v_mfma_f32_16x16x32_bf16 v[106:109], v[154:157], v[176:179], v[106:109]
	v_mfma_f32_16x16x32_bf16 v[122:125], v[150:153], v[158:161], 0
	v_mfma_f32_16x16x32_bf16 v[122:125], v[154:157], v[168:171], v[122:125]
	s_barrier
	s_add_i32 s24, 0, 0x14000
	s_add_i32 s23, s23, s28
	ds_read_b128 v[216:219], v248 offset:16384
	ds_read_b128 v[220:223], v248 offset:17408
	ds_read_b128 v[224:227], v248 offset:18432
	ds_read_b128 v[228:231], v248 offset:19456
	s_add_u32 s70, s10, s6
	s_addc_u32 s71, s11, s7
	s_mov_b32 m0, s23
	s_nop 0
	global_load_lds_dwordx4 v132, s[10:11]
	s_add_i32 m0, s23, 0x2000
	s_nop 0
	global_load_lds_dwordx4 v136, s[10:11]
	s_barrier
	s_waitcnt lgkmcnt(0)
	v_mfma_f32_16x16x32_bf16 v[118:121], v[216:219], v[158:161], 0
	v_mfma_f32_16x16x32_bf16 v[118:121], v[220:223], v[168:171], v[118:121]
	v_mfma_f32_16x16x32_bf16 v[102:105], v[216:219], v[172:175], 0
	v_mfma_f32_16x16x32_bf16 v[102:105], v[220:223], v[176:179], v[102:105]
	v_mfma_f32_16x16x32_bf16 v[86:89], v[216:219], v[180:183], 0
	v_mfma_f32_16x16x32_bf16 v[86:89], v[220:223], v[204:207], v[86:89]
	v_mfma_f32_16x16x32_bf16 v[70:73], v[216:219], v[208:211], 0
	v_mfma_f32_16x16x32_bf16 v[70:73], v[220:223], v[212:215], v[70:73]
	v_mfma_f32_16x16x32_bf16 v[66:69], v[224:227], v[208:211], 0
	v_mfma_f32_16x16x32_bf16 v[66:69], v[228:231], v[212:215], v[66:69]
	v_mfma_f32_16x16x32_bf16 v[82:85], v[224:227], v[180:183], 0
	v_mfma_f32_16x16x32_bf16 v[82:85], v[228:231], v[204:207], v[82:85]
	v_mfma_f32_16x16x32_bf16 v[98:101], v[224:227], v[172:175], 0
	v_mfma_f32_16x16x32_bf16 v[98:101], v[228:231], v[176:179], v[98:101]
	v_mfma_f32_16x16x32_bf16 v[114:117], v[224:227], v[158:161], 0
	v_mfma_f32_16x16x32_bf16 v[114:117], v[228:231], v[168:171], v[114:117]
	s_barrier
	s_mov_b32 m0, s29
	s_add_u32 s72, s4, s6
	s_addc_u32 s73, s5, s7
	ds_read_b128 v[158:161], v166 offset:16384
	ds_read_b128 v[168:171], v166 offset:17408
	ds_read_b128 v[172:175], v166 offset:18432
	ds_read_b128 v[176:179], v166 offset:19456
	ds_read_b128 v[180:183], v166 offset:20480
	ds_read_b128 v[204:207], v166 offset:21504
	ds_read_b128 v[208:211], v166 offset:22528
	ds_read_b128 v[212:215], v166 offset:23552
	global_load_lds_dwordx4 v130, s[4:5]
	s_mov_b32 m0, s30
	s_nop 0
	global_load_lds_dwordx4 v134, s[4:5]
	s_barrier
	s_waitcnt lgkmcnt(0)
	v_mfma_f32_16x16x32_bf16 v[62:65], v[142:145], v[158:161], 0
	v_mfma_f32_16x16x32_bf16 v[62:65], v[146:149], v[168:171], v[62:65]
	v_mfma_f32_16x16x32_bf16 v[46:49], v[142:145], v[172:175], 0
	v_mfma_f32_16x16x32_bf16 v[46:49], v[146:149], v[176:179], v[46:49]
	v_mfma_f32_16x16x32_bf16 v[30:33], v[142:145], v[180:183], 0
	v_mfma_f32_16x16x32_bf16 v[30:33], v[146:149], v[204:207], v[30:33]
	v_mfma_f32_16x16x32_bf16 v[14:17], v[142:145], v[208:211], 0
	v_mfma_f32_16x16x32_bf16 v[14:17], v[146:149], v[212:215], v[14:17]
	v_mfma_f32_16x16x32_bf16 v[10:13], v[150:153], v[208:211], 0
	v_mfma_f32_16x16x32_bf16 v[10:13], v[154:157], v[212:215], v[10:13]
	v_mfma_f32_16x16x32_bf16 v[26:29], v[150:153], v[180:183], 0
	v_mfma_f32_16x16x32_bf16 v[26:29], v[154:157], v[204:207], v[26:29]
	v_mfma_f32_16x16x32_bf16 v[42:45], v[150:153], v[172:175], 0
	v_mfma_f32_16x16x32_bf16 v[42:45], v[154:157], v[176:179], v[42:45]
	v_mfma_f32_16x16x32_bf16 v[58:61], v[150:153], v[158:161], 0
	v_mfma_f32_16x16x32_bf16 v[58:61], v[154:157], v[168:171], v[58:61]
	s_barrier
	s_add_u32 s10, s10, s92
	s_addc_u32 s11, s11, 0
	s_add_i32 s23, s24, s28
	s_add_u32 s80, s10, s6
	s_addc_u32 s81, s11, s7
	s_mov_b32 m0, s23
	s_nop 0
	global_load_lds_dwordx4 v132, s[10:11]
	s_add_i32 m0, s23, 0x2000
	s_nop 0
	global_load_lds_dwordx4 v136, s[10:11]
	s_waitcnt vmcnt(6)
	s_barrier
	v_mfma_f32_16x16x32_bf16 v[54:57], v[216:219], v[158:161], 0
	v_mfma_f32_16x16x32_bf16 v[54:57], v[220:223], v[168:171], v[54:57]
	v_mfma_f32_16x16x32_bf16 v[38:41], v[216:219], v[172:175], 0
	v_mfma_f32_16x16x32_bf16 v[38:41], v[220:223], v[176:179], v[38:41]
	v_mfma_f32_16x16x32_bf16 v[22:25], v[216:219], v[180:183], 0
	v_mfma_f32_16x16x32_bf16 v[22:25], v[220:223], v[204:207], v[22:25]
	v_mfma_f32_16x16x32_bf16 v[6:9], v[216:219], v[208:211], 0
	v_mfma_f32_16x16x32_bf16 v[6:9], v[220:223], v[212:215], v[6:9]
	v_mfma_f32_16x16x32_bf16 v[2:5], v[224:227], v[208:211], 0
	v_mfma_f32_16x16x32_bf16 v[2:5], v[228:231], v[212:215], v[2:5]
	v_mfma_f32_16x16x32_bf16 v[18:21], v[224:227], v[180:183], 0
	v_mfma_f32_16x16x32_bf16 v[18:21], v[228:231], v[204:207], v[18:21]
	v_mfma_f32_16x16x32_bf16 v[34:37], v[224:227], v[172:175], 0
	v_mfma_f32_16x16x32_bf16 v[34:37], v[228:231], v[176:179], v[34:37]
	v_mfma_f32_16x16x32_bf16 v[50:53], v[224:227], v[158:161], 0
	v_mfma_f32_16x16x32_bf16 v[50:53], v[228:231], v[168:171], v[50:53]
	s_barrier
	s_add_i32 s10, 0, 0x18000
	ds_read_b128 v[142:145], v248 offset:32768
	ds_read_b128 v[146:149], v248 offset:33792
	ds_read_b128 v[150:153], v248 offset:34816
	ds_read_b128 v[154:157], v248 offset:35840
	s_add_u32 s4, s4, s92
	s_addc_u32 s5, s5, 0
	s_mov_b32 m0, s31
	ds_read_b128 v[158:161], v166 offset:32768
	ds_read_b128 v[168:171], v166 offset:33792
	ds_read_b128 v[172:175], v166 offset:34816
	ds_read_b128 v[176:179], v166 offset:35840
	ds_read_b128 v[180:183], v166 offset:36864
	ds_read_b128 v[204:207], v166 offset:37888
	ds_read_b128 v[208:211], v166 offset:38912
	ds_read_b128 v[212:215], v166 offset:39936
	global_load_lds_dwordx4 v130, s[4:5]
	s_mov_b32 m0, s34
	s_nop 0
	global_load_lds_dwordx4 v134, s[4:5]
	s_waitcnt lgkmcnt(8)
	s_barrier
	s_waitcnt lgkmcnt(0)
	v_mfma_f32_16x16x32_bf16 v[126:129], v[142:145], v[158:161], v[126:129]
	v_mfma_f32_16x16x32_bf16 v[126:129], v[146:149], v[168:171], v[126:129]
	v_mfma_f32_16x16x32_bf16 v[110:113], v[142:145], v[172:175], v[110:113]
	v_mfma_f32_16x16x32_bf16 v[110:113], v[146:149], v[176:179], v[110:113]
	v_mfma_f32_16x16x32_bf16 v[94:97], v[142:145], v[180:183], v[94:97]
	v_mfma_f32_16x16x32_bf16 v[94:97], v[146:149], v[204:207], v[94:97]
	v_mfma_f32_16x16x32_bf16 v[78:81], v[142:145], v[208:211], v[78:81]
	v_mfma_f32_16x16x32_bf16 v[78:81], v[146:149], v[212:215], v[78:81]
	v_mfma_f32_16x16x32_bf16 v[74:77], v[150:153], v[208:211], v[74:77]
	v_mfma_f32_16x16x32_bf16 v[74:77], v[154:157], v[212:215], v[74:77]
	v_mfma_f32_16x16x32_bf16 v[90:93], v[150:153], v[180:183], v[90:93]
	v_mfma_f32_16x16x32_bf16 v[90:93], v[154:157], v[204:207], v[90:93]
	v_mfma_f32_16x16x32_bf16 v[106:109], v[150:153], v[172:175], v[106:109]
	v_mfma_f32_16x16x32_bf16 v[106:109], v[154:157], v[176:179], v[106:109]
	v_mfma_f32_16x16x32_bf16 v[122:125], v[150:153], v[158:161], v[122:125]
	v_mfma_f32_16x16x32_bf16 v[122:125], v[154:157], v[168:171], v[122:125]
	s_barrier
	s_add_i32 s4, 0, 0x1c000
	s_add_i32 s5, s10, s28
	s_mov_b32 m0, s5
	ds_read_b128 v[216:219], v248 offset:49152
	ds_read_b128 v[220:223], v248 offset:50176
	ds_read_b128 v[224:227], v248 offset:51200
	ds_read_b128 v[228:231], v248 offset:52224
	global_load_lds_dwordx4 v132, s[70:71]
	s_add_i32 m0, s5, 0x2000
	s_nop 0
	global_load_lds_dwordx4 v136, s[70:71]
	s_barrier
	s_waitcnt lgkmcnt(0)
	v_mfma_f32_16x16x32_bf16 v[118:121], v[216:219], v[158:161], v[118:121]
	v_mfma_f32_16x16x32_bf16 v[118:121], v[220:223], v[168:171], v[118:121]
	v_mfma_f32_16x16x32_bf16 v[102:105], v[216:219], v[172:175], v[102:105]
	v_mfma_f32_16x16x32_bf16 v[102:105], v[220:223], v[176:179], v[102:105]
	v_mfma_f32_16x16x32_bf16 v[86:89], v[216:219], v[180:183], v[86:89]
	v_mfma_f32_16x16x32_bf16 v[86:89], v[220:223], v[204:207], v[86:89]
	v_mfma_f32_16x16x32_bf16 v[70:73], v[216:219], v[208:211], v[70:73]
	v_mfma_f32_16x16x32_bf16 v[70:73], v[220:223], v[212:215], v[70:73]
	v_mfma_f32_16x16x32_bf16 v[66:69], v[224:227], v[208:211], v[66:69]
	v_mfma_f32_16x16x32_bf16 v[66:69], v[228:231], v[212:215], v[66:69]
	v_mfma_f32_16x16x32_bf16 v[82:85], v[224:227], v[180:183], v[82:85]
	v_mfma_f32_16x16x32_bf16 v[82:85], v[228:231], v[204:207], v[82:85]
	v_mfma_f32_16x16x32_bf16 v[98:101], v[224:227], v[172:175], v[98:101]
	v_mfma_f32_16x16x32_bf16 v[98:101], v[228:231], v[176:179], v[98:101]
	v_mfma_f32_16x16x32_bf16 v[114:117], v[224:227], v[158:161], v[114:117]
	v_mfma_f32_16x16x32_bf16 v[114:117], v[228:231], v[168:171], v[114:117]
	s_barrier
	s_mov_b32 m0, s42
	ds_read_b128 v[158:161], v166 offset:49152
	ds_read_b128 v[168:171], v166 offset:50176
	ds_read_b128 v[172:175], v166 offset:51200
	ds_read_b128 v[176:179], v166 offset:52224
	ds_read_b128 v[180:183], v166 offset:53248
	ds_read_b128 v[204:207], v166 offset:54272
	ds_read_b128 v[208:211], v166 offset:55296
	ds_read_b128 v[212:215], v166 offset:56320
	global_load_lds_dwordx4 v130, s[72:73]
	s_mov_b32 m0, s43
	s_nop 0
	global_load_lds_dwordx4 v134, s[72:73]
	s_barrier
	s_waitcnt lgkmcnt(0)
	v_mfma_f32_16x16x32_bf16 v[62:65], v[142:145], v[158:161], v[62:65]
	v_mfma_f32_16x16x32_bf16 v[62:65], v[146:149], v[168:171], v[62:65]
	v_mfma_f32_16x16x32_bf16 v[46:49], v[142:145], v[172:175], v[46:49]
	v_mfma_f32_16x16x32_bf16 v[46:49], v[146:149], v[176:179], v[46:49]
	v_mfma_f32_16x16x32_bf16 v[30:33], v[142:145], v[180:183], v[30:33]
	v_mfma_f32_16x16x32_bf16 v[30:33], v[146:149], v[204:207], v[30:33]
	v_mfma_f32_16x16x32_bf16 v[14:17], v[142:145], v[208:211], v[14:17]
	v_mfma_f32_16x16x32_bf16 v[14:17], v[146:149], v[212:215], v[14:17]
	v_mfma_f32_16x16x32_bf16 v[10:13], v[150:153], v[208:211], v[10:13]
	v_mfma_f32_16x16x32_bf16 v[10:13], v[154:157], v[212:215], v[10:13]
	v_mfma_f32_16x16x32_bf16 v[26:29], v[150:153], v[180:183], v[26:29]
	v_mfma_f32_16x16x32_bf16 v[26:29], v[154:157], v[204:207], v[26:29]
	v_mfma_f32_16x16x32_bf16 v[42:45], v[150:153], v[172:175], v[42:45]
	v_mfma_f32_16x16x32_bf16 v[42:45], v[154:157], v[176:179], v[42:45]
	v_mfma_f32_16x16x32_bf16 v[58:61], v[150:153], v[158:161], v[58:61]
	v_mfma_f32_16x16x32_bf16 v[58:61], v[154:157], v[168:171], v[58:61]
	s_barrier
	s_add_i32 s4, s4, s28
	s_mov_b32 m0, s4
	s_nop 0
	global_load_lds_dwordx4 v132, s[80:81]
	s_add_i32 m0, s4, 0x2000
	s_nop 0
	global_load_lds_dwordx4 v136, s[80:81]
	s_add_u32 s0, s0, 0x100
	s_addc_u32 s1, s1, 0
	s_add_u32 s20, s20, 0x100
	s_addc_u32 s21, s21, 0
	s_cmp_ge_u32 s22, s35
	s_mov_b32 s4, s22
	s_waitcnt vmcnt(6)
	s_barrier
	v_mfma_f32_16x16x32_bf16 v[54:57], v[216:219], v[158:161], v[54:57]
	v_mfma_f32_16x16x32_bf16 v[54:57], v[220:223], v[168:171], v[54:57]
	v_mfma_f32_16x16x32_bf16 v[38:41], v[216:219], v[172:175], v[38:41]
	v_mfma_f32_16x16x32_bf16 v[38:41], v[220:223], v[176:179], v[38:41]
	v_mfma_f32_16x16x32_bf16 v[22:25], v[216:219], v[180:183], v[22:25]
	v_mfma_f32_16x16x32_bf16 v[22:25], v[220:223], v[204:207], v[22:25]
	v_mfma_f32_16x16x32_bf16 v[6:9], v[216:219], v[208:211], v[6:9]
	v_mfma_f32_16x16x32_bf16 v[6:9], v[220:223], v[212:215], v[6:9]
	v_mfma_f32_16x16x32_bf16 v[2:5], v[224:227], v[208:211], v[2:5]
	v_mfma_f32_16x16x32_bf16 v[2:5], v[228:231], v[212:215], v[2:5]
	v_mfma_f32_16x16x32_bf16 v[18:21], v[224:227], v[180:183], v[18:21]
	v_mfma_f32_16x16x32_bf16 v[18:21], v[228:231], v[204:207], v[18:21]
	v_mfma_f32_16x16x32_bf16 v[34:37], v[224:227], v[172:175], v[34:37]
	v_mfma_f32_16x16x32_bf16 v[34:37], v[228:231], v[176:179], v[34:37]
	v_mfma_f32_16x16x32_bf16 v[50:53], v[224:227], v[158:161], v[50:53]
	v_mfma_f32_16x16x32_bf16 v[50:53], v[228:231], v[168:171], v[50:53]
	s_barrier
	s_cbranch_scc1 .Lkexit_282
.LBB0_282:
	s_add_i32 s22, s4, 2
	s_add_u32 s10, s0, 0x80
	s_addc_u32 s5, s1, 0
	s_add_i32 s23, 0, 0x10000
	ds_read_b128 v[142:145], v248
	ds_read_b128 v[146:149], v248 offset:1024
	ds_read_b128 v[150:153], v248 offset:2048
	ds_read_b128 v[154:157], v248 offset:3072
	s_cmp_eq_u32 s44, s4
	s_cselect_b32 s4, s16, s10
	s_cselect_b32 s5, s17, s5
	s_cselect_b32 s11, s13, s21
	s_cselect_b32 s10, s12, s20
	s_add_i32 m0, s29, 0xc000
	ds_read_b128 v[158:161], v166
	ds_read_b128 v[168:171], v166 offset:1024
	ds_read_b128 v[172:175], v166 offset:2048
	ds_read_b128 v[176:179], v166 offset:3072
	ds_read_b128 v[180:183], v166 offset:4096
	ds_read_b128 v[204:207], v166 offset:5120
	ds_read_b128 v[208:211], v166 offset:6144
	ds_read_b128 v[212:215], v166 offset:7168
	global_load_lds_dwordx4 v138, s[0:1]
	s_add_i32 m0, s29, 0xe000
	s_nop 0
	global_load_lds_dwordx4 v140, s[0:1]
	s_waitcnt lgkmcnt(8)
	s_barrier
	s_waitcnt lgkmcnt(0)
	v_mfma_f32_16x16x32_bf16 v[126:129], v[142:145], v[158:161], v[126:129]
	v_mfma_f32_16x16x32_bf16 v[126:129], v[146:149], v[168:171], v[126:129]
	v_mfma_f32_16x16x32_bf16 v[110:113], v[142:145], v[172:175], v[110:113]
	v_mfma_f32_16x16x32_bf16 v[110:113], v[146:149], v[176:179], v[110:113]
	v_mfma_f32_16x16x32_bf16 v[94:97], v[142:145], v[180:183], v[94:97]
	v_mfma_f32_16x16x32_bf16 v[94:97], v[146:149], v[204:207], v[94:97]
	v_mfma_f32_16x16x32_bf16 v[78:81], v[142:145], v[208:211], v[78:81]
	v_mfma_f32_16x16x32_bf16 v[78:81], v[146:149], v[212:215], v[78:81]
	v_mfma_f32_16x16x32_bf16 v[74:77], v[150:153], v[208:211], v[74:77]
	v_mfma_f32_16x16x32_bf16 v[74:77], v[154:157], v[212:215], v[74:77]
	v_mfma_f32_16x16x32_bf16 v[90:93], v[150:153], v[180:183], v[90:93]
	v_mfma_f32_16x16x32_bf16 v[90:93], v[154:157], v[204:207], v[90:93]
	v_mfma_f32_16x16x32_bf16 v[106:109], v[150:153], v[172:175], v[106:109]
	v_mfma_f32_16x16x32_bf16 v[106:109], v[154:157], v[176:179], v[106:109]
	v_mfma_f32_16x16x32_bf16 v[122:125], v[150:153], v[158:161], v[122:125]
	v_mfma_f32_16x16x32_bf16 v[122:125], v[154:157], v[168:171], v[122:125]
	s_barrier
	s_add_i32 s24, 0, 0x14000
	s_add_i32 s23, s23, s28
	ds_read_b128 v[216:219], v248 offset:16384
	ds_read_b128 v[220:223], v248 offset:17408
	ds_read_b128 v[224:227], v248 offset:18432
	ds_read_b128 v[228:231], v248 offset:19456
	s_add_u32 s70, s10, s6
	s_addc_u32 s71, s11, s7
	s_mov_b32 m0, s23
	s_nop 0
	global_load_lds_dwordx4 v132, s[10:11]
	s_add_i32 m0, s23, 0x2000
	s_nop 0
	global_load_lds_dwordx4 v136, s[10:11]
	s_barrier
	s_waitcnt lgkmcnt(0)
	v_mfma_f32_16x16x32_bf16 v[118:121], v[216:219], v[158:161], v[118:121]
	v_mfma_f32_16x16x32_bf16 v[118:121], v[220:223], v[168:171], v[118:121]
	v_mfma_f32_16x16x32_bf16 v[102:105], v[216:219], v[172:175], v[102:105]
	v_mfma_f32_16x16x32_bf16 v[102:105], v[220:223], v[176:179], v[102:105]
	v_mfma_f32_16x16x32_bf16 v[86:89], v[216:219], v[180:183], v[86:89]
	v_mfma_f32_16x16x32_bf16 v[86:89], v[220:223], v[204:207], v[86:89]
	v_mfma_f32_16x16x32_bf16 v[70:73], v[216:219], v[208:211], v[70:73]
	v_mfma_f32_16x16x32_bf16 v[70:73], v[220:223], v[212:215], v[70:73]
	v_mfma_f32_16x16x32_bf16 v[66:69], v[224:227], v[208:211], v[66:69]
	v_mfma_f32_16x16x32_bf16 v[66:69], v[228:231], v[212:215], v[66:69]
	v_mfma_f32_16x16x32_bf16 v[82:85], v[224:227], v[180:183], v[82:85]
	v_mfma_f32_16x16x32_bf16 v[82:85], v[228:231], v[204:207], v[82:85]
	v_mfma_f32_16x16x32_bf16 v[98:101], v[224:227], v[172:175], v[98:101]
	v_mfma_f32_16x16x32_bf16 v[98:101], v[228:231], v[176:179], v[98:101]
	v_mfma_f32_16x16x32_bf16 v[114:117], v[224:227], v[158:161], v[114:117]
	v_mfma_f32_16x16x32_bf16 v[114:117], v[228:231], v[168:171], v[114:117]
	s_barrier
	s_mov_b32 m0, s29
	s_add_u32 s72, s4, s6
	s_addc_u32 s73, s5, s7
	ds_read_b128 v[158:161], v166 offset:16384
	ds_read_b128 v[168:171], v166 offset:17408
	ds_read_b128 v[172:175], v166 offset:18432
	ds_read_b128 v[176:179], v166 offset:19456
	ds_read_b128 v[180:183], v166 offset:20480
	ds_read_b128 v[204:207], v166 offset:21504
	ds_read_b128 v[208:211], v166 offset:22528
	ds_read_b128 v[212:215], v166 offset:23552
	global_load_lds_dwordx4 v130, s[4:5]
	s_mov_b32 m0, s30
	s_nop 0
	global_load_lds_dwordx4 v134, s[4:5]
	s_barrier
	s_waitcnt lgkmcnt(0)
	v_mfma_f32_16x16x32_bf16 v[62:65], v[142:145], v[158:161], v[62:65]
	v_mfma_f32_16x16x32_bf16 v[62:65], v[146:149], v[168:171], v[62:65]
	v_mfma_f32_16x16x32_bf16 v[46:49], v[142:145], v[172:175], v[46:49]
	v_mfma_f32_16x16x32_bf16 v[46:49], v[146:149], v[176:179], v[46:49]
	v_mfma_f32_16x16x32_bf16 v[30:33], v[142:145], v[180:183], v[30:33]
	v_mfma_f32_16x16x32_bf16 v[30:33], v[146:149], v[204:207], v[30:33]
	v_mfma_f32_16x16x32_bf16 v[14:17], v[142:145], v[208:211], v[14:17]
	v_mfma_f32_16x16x32_bf16 v[14:17], v[146:149], v[212:215], v[14:17]
	v_mfma_f32_16x16x32_bf16 v[10:13], v[150:153], v[208:211], v[10:13]
	v_mfma_f32_16x16x32_bf16 v[10:13], v[154:157], v[212:215], v[10:13]
	v_mfma_f32_16x16x32_bf16 v[26:29], v[150:153], v[180:183], v[26:29]
	v_mfma_f32_16x16x32_bf16 v[26:29], v[154:157], v[204:207], v[26:29]
	v_mfma_f32_16x16x32_bf16 v[42:45], v[150:153], v[172:175], v[42:45]
	v_mfma_f32_16x16x32_bf16 v[42:45], v[154:157], v[176:179], v[42:45]
	v_mfma_f32_16x16x32_bf16 v[58:61], v[150:153], v[158:161], v[58:61]
	v_mfma_f32_16x16x32_bf16 v[58:61], v[154:157], v[168:171], v[58:61]
	s_barrier
	s_add_u32 s10, s10, s92
	s_addc_u32 s11, s11, 0
	s_add_i32 s23, s24, s28
	s_add_u32 s80, s10, s6
	s_addc_u32 s81, s11, s7
	s_mov_b32 m0, s23
	s_nop 0
	global_load_lds_dwordx4 v132, s[10:11]
	s_add_i32 m0, s23, 0x2000
	s_nop 0
	global_load_lds_dwordx4 v136, s[10:11]
	s_waitcnt vmcnt(6)
	s_barrier
	v_mfma_f32_16x16x32_bf16 v[54:57], v[216:219], v[158:161], v[54:57]
	v_mfma_f32_16x16x32_bf16 v[54:57], v[220:223], v[168:171], v[54:57]
	v_mfma_f32_16x16x32_bf16 v[38:41], v[216:219], v[172:175], v[38:41]
	v_mfma_f32_16x16x32_bf16 v[38:41], v[220:223], v[176:179], v[38:41]
	v_mfma_f32_16x16x32_bf16 v[22:25], v[216:219], v[180:183], v[22:25]
	v_mfma_f32_16x16x32_bf16 v[22:25], v[220:223], v[204:207], v[22:25]
	v_mfma_f32_16x16x32_bf16 v[6:9], v[216:219], v[208:211], v[6:9]
	v_mfma_f32_16x16x32_bf16 v[6:9], v[220:223], v[212:215], v[6:9]
	v_mfma_f32_16x16x32_bf16 v[2:5], v[224:227], v[208:211], v[2:5]
	v_mfma_f32_16x16x32_bf16 v[2:5], v[228:231], v[212:215], v[2:5]
	v_mfma_f32_16x16x32_bf16 v[18:21], v[224:227], v[180:183], v[18:21]
	v_mfma_f32_16x16x32_bf16 v[18:21], v[228:231], v[204:207], v[18:21]
	v_mfma_f32_16x16x32_bf16 v[34:37], v[224:227], v[172:175], v[34:37]
	v_mfma_f32_16x16x32_bf16 v[34:37], v[228:231], v[176:179], v[34:37]
	v_mfma_f32_16x16x32_bf16 v[50:53], v[224:227], v[158:161], v[50:53]
	v_mfma_f32_16x16x32_bf16 v[50:53], v[228:231], v[168:171], v[50:53]
	s_barrier
	s_add_i32 s10, 0, 0x18000
	ds_read_b128 v[142:145], v248 offset:32768
	ds_read_b128 v[146:149], v248 offset:33792
	ds_read_b128 v[150:153], v248 offset:34816
	ds_read_b128 v[154:157], v248 offset:35840
	s_add_u32 s4, s4, s92
	s_addc_u32 s5, s5, 0
	s_mov_b32 m0, s31
	ds_read_b128 v[158:161], v166 offset:32768
	ds_read_b128 v[168:171], v166 offset:33792
	ds_read_b128 v[172:175], v166 offset:34816
	ds_read_b128 v[176:179], v166 offset:35840
	ds_read_b128 v[180:183], v166 offset:36864
	ds_read_b128 v[204:207], v166 offset:37888
	ds_read_b128 v[208:211], v166 offset:38912
	ds_read_b128 v[212:215], v166 offset:39936
	global_load_lds_dwordx4 v130, s[4:5]
	s_mov_b32 m0, s34
	s_nop 0
	global_load_lds_dwordx4 v134, s[4:5]
	s_waitcnt lgkmcnt(8)
	s_barrier
	s_waitcnt lgkmcnt(0)
	v_mfma_f32_16x16x32_bf16 v[126:129], v[142:145], v[158:161], v[126:129]
	v_mfma_f32_16x16x32_bf16 v[126:129], v[146:149], v[168:171], v[126:129]
	v_mfma_f32_16x16x32_bf16 v[110:113], v[142:145], v[172:175], v[110:113]
	v_mfma_f32_16x16x32_bf16 v[110:113], v[146:149], v[176:179], v[110:113]
	v_mfma_f32_16x16x32_bf16 v[94:97], v[142:145], v[180:183], v[94:97]
	v_mfma_f32_16x16x32_bf16 v[94:97], v[146:149], v[204:207], v[94:97]
	v_mfma_f32_16x16x32_bf16 v[78:81], v[142:145], v[208:211], v[78:81]
	v_mfma_f32_16x16x32_bf16 v[78:81], v[146:149], v[212:215], v[78:81]
	v_mfma_f32_16x16x32_bf16 v[74:77], v[150:153], v[208:211], v[74:77]
	v_mfma_f32_16x16x32_bf16 v[74:77], v[154:157], v[212:215], v[74:77]
	v_mfma_f32_16x16x32_bf16 v[90:93], v[150:153], v[180:183], v[90:93]
	v_mfma_f32_16x16x32_bf16 v[90:93], v[154:157], v[204:207], v[90:93]
	v_mfma_f32_16x16x32_bf16 v[106:109], v[150:153], v[172:175], v[106:109]
	v_mfma_f32_16x16x32_bf16 v[106:109], v[154:157], v[176:179], v[106:109]
	v_mfma_f32_16x16x32_bf16 v[122:125], v[150:153], v[158:161], v[122:125]
	v_mfma_f32_16x16x32_bf16 v[122:125], v[154:157], v[168:171], v[122:125]
	s_barrier
	s_add_i32 s4, 0, 0x1c000
	s_add_i32 s5, s10, s28
	s_mov_b32 m0, s5
	ds_read_b128 v[216:219], v248 offset:49152
	ds_read_b128 v[220:223], v248 offset:50176
	ds_read_b128 v[224:227], v248 offset:51200
	ds_read_b128 v[228:231], v248 offset:52224
	global_load_lds_dwordx4 v132, s[70:71]
	s_add_i32 m0, s5, 0x2000
	s_nop 0
	global_load_lds_dwordx4 v136, s[70:71]
	s_barrier
	s_waitcnt lgkmcnt(0)
	v_mfma_f32_16x16x32_bf16 v[118:121], v[216:219], v[158:161], v[118:121]
	v_mfma_f32_16x16x32_bf16 v[118:121], v[220:223], v[168:171], v[118:121]
	v_mfma_f32_16x16x32_bf16 v[102:105], v[216:219], v[172:175], v[102:105]
	v_mfma_f32_16x16x32_bf16 v[102:105], v[220:223], v[176:179], v[102:105]
	v_mfma_f32_16x16x32_bf16 v[86:89], v[216:219], v[180:183], v[86:89]
	v_mfma_f32_16x16x32_bf16 v[86:89], v[220:223], v[204:207], v[86:89]
	v_mfma_f32_16x16x32_bf16 v[70:73], v[216:219], v[208:211], v[70:73]
	v_mfma_f32_16x16x32_bf16 v[70:73], v[220:223], v[212:215], v[70:73]
	v_mfma_f32_16x16x32_bf16 v[66:69], v[224:227], v[208:211], v[66:69]
	v_mfma_f32_16x16x32_bf16 v[66:69], v[228:231], v[212:215], v[66:69]
	v_mfma_f32_16x16x32_bf16 v[82:85], v[224:227], v[180:183], v[82:85]
	v_mfma_f32_16x16x32_bf16 v[82:85], v[228:231], v[204:207], v[82:85]
	v_mfma_f32_16x16x32_bf16 v[98:101], v[224:227], v[172:175], v[98:101]
	v_mfma_f32_16x16x32_bf16 v[98:101], v[228:231], v[176:179], v[98:101]
	v_mfma_f32_16x16x32_bf16 v[114:117], v[224:227], v[158:161], v[114:117]
	v_mfma_f32_16x16x32_bf16 v[114:117], v[228:231], v[168:171], v[114:117]
	s_barrier
	s_mov_b32 m0, s42
	ds_read_b128 v[158:161], v166 offset:49152
	ds_read_b128 v[168:171], v166 offset:50176
	ds_read_b128 v[172:175], v166 offset:51200
	ds_read_b128 v[176:179], v166 offset:52224
	ds_read_b128 v[180:183], v166 offset:53248
	ds_read_b128 v[204:207], v166 offset:54272
	ds_read_b128 v[208:211], v166 offset:55296
	ds_read_b128 v[212:215], v166 offset:56320
	global_load_lds_dwordx4 v130, s[72:73]
	s_mov_b32 m0, s43
	s_nop 0
	global_load_lds_dwordx4 v134, s[72:73]
	s_barrier
	s_waitcnt lgkmcnt(0)
	v_mfma_f32_16x16x32_bf16 v[62:65], v[142:145], v[158:161], v[62:65]
	v_mfma_f32_16x16x32_bf16 v[62:65], v[146:149], v[168:171], v[62:65]
	v_mfma_f32_16x16x32_bf16 v[46:49], v[142:145], v[172:175], v[46:49]
	v_mfma_f32_16x16x32_bf16 v[46:49], v[146:149], v[176:179], v[46:49]
	v_mfma_f32_16x16x32_bf16 v[30:33], v[142:145], v[180:183], v[30:33]
	v_mfma_f32_16x16x32_bf16 v[30:33], v[146:149], v[204:207], v[30:33]
	v_mfma_f32_16x16x32_bf16 v[14:17], v[142:145], v[208:211], v[14:17]
	v_mfma_f32_16x16x32_bf16 v[14:17], v[146:149], v[212:215], v[14:17]
	v_mfma_f32_16x16x32_bf16 v[10:13], v[150:153], v[208:211], v[10:13]
	v_mfma_f32_16x16x32_bf16 v[10:13], v[154:157], v[212:215], v[10:13]
	v_mfma_f32_16x16x32_bf16 v[26:29], v[150:153], v[180:183], v[26:29]
	v_mfma_f32_16x16x32_bf16 v[26:29], v[154:157], v[204:207], v[26:29]
	v_mfma_f32_16x16x32_bf16 v[42:45], v[150:153], v[172:175], v[42:45]
	v_mfma_f32_16x16x32_bf16 v[42:45], v[154:157], v[176:179], v[42:45]
	v_mfma_f32_16x16x32_bf16 v[58:61], v[150:153], v[158:161], v[58:61]
	v_mfma_f32_16x16x32_bf16 v[58:61], v[154:157], v[168:171], v[58:61]
	s_barrier
	s_add_i32 s4, s4, s28
	s_mov_b32 m0, s4
	s_nop 0
	global_load_lds_dwordx4 v132, s[80:81]
	s_add_i32 m0, s4, 0x2000
	s_nop 0
	global_load_lds_dwordx4 v136, s[80:81]
	s_add_u32 s0, s0, 0x100
	s_addc_u32 s1, s1, 0
	s_add_u32 s20, s20, 0x100
	s_addc_u32 s21, s21, 0
	s_cmp_ge_u32 s22, s35
	s_mov_b32 s4, s22
	s_waitcnt vmcnt(6)
	s_barrier
	v_mfma_f32_16x16x32_bf16 v[54:57], v[216:219], v[158:161], v[54:57]
	v_mfma_f32_16x16x32_bf16 v[54:57], v[220:223], v[168:171], v[54:57]
	v_mfma_f32_16x16x32_bf16 v[38:41], v[216:219], v[172:175], v[38:41]
	v_mfma_f32_16x16x32_bf16 v[38:41], v[220:223], v[176:179], v[38:41]
	v_mfma_f32_16x16x32_bf16 v[22:25], v[216:219], v[180:183], v[22:25]
	v_mfma_f32_16x16x32_bf16 v[22:25], v[220:223], v[204:207], v[22:25]
	v_mfma_f32_16x16x32_bf16 v[6:9], v[216:219], v[208:211], v[6:9]
	v_mfma_f32_16x16x32_bf16 v[6:9], v[220:223], v[212:215], v[6:9]
	v_mfma_f32_16x16x32_bf16 v[2:5], v[224:227], v[208:211], v[2:5]
	v_mfma_f32_16x16x32_bf16 v[2:5], v[228:231], v[212:215], v[2:5]
	v_mfma_f32_16x16x32_bf16 v[18:21], v[224:227], v[180:183], v[18:21]
	v_mfma_f32_16x16x32_bf16 v[18:21], v[228:231], v[204:207], v[18:21]
	v_mfma_f32_16x16x32_bf16 v[34:37], v[224:227], v[172:175], v[34:37]
	v_mfma_f32_16x16x32_bf16 v[34:37], v[228:231], v[176:179], v[34:37]
	v_mfma_f32_16x16x32_bf16 v[50:53], v[224:227], v[158:161], v[50:53]
	v_mfma_f32_16x16x32_bf16 v[50:53], v[228:231], v[168:171], v[50:53]
	s_barrier
	s_cbranch_scc0 .LBB0_282

.LBB0_346:
	s_add_u32 s0, s0, 0x80
	s_addc_u32 s1, s1, 0
	s_add_u32 s12, s4, 0x100
	s_addc_u32 s13, s5, 0
	s_mov_b32 s4, 0
	s_waitcnt lgkmcnt(0)
	s_waitcnt vmcnt(0)
	s_add_i32 s15, s4, 2
	s_add_u32 s10, s0, 0x80
	s_addc_u32 s5, s1, 0
	s_add_i32 s16, 0, 0x10000
	ds_read_b128 v[130:133], v248
	ds_read_b128 v[134:137], v248 offset:1024
	ds_read_b128 v[138:141], v248 offset:2048
	ds_read_b128 v[142:145], v248 offset:3072
	s_cmp_eq_u32 s79, s4
	s_cselect_b32 s4, s44, s10
	s_cselect_b32 s5, s45, s5
	s_cselect_b32 s11, s47, s13
	s_cselect_b32 s10, s46, s12
	s_add_i32 m0, s71, 0xc000
	ds_read_b128 v[158:161], v206
	ds_read_b128 v[162:165], v206 offset:1024
	ds_read_b128 v[166:169], v206 offset:2048
	ds_read_b128 v[170:173], v206 offset:3072
	ds_read_b128 v[174:177], v206 offset:4096
	ds_read_b128 v[178:181], v206 offset:5120
	ds_read_b128 v[182:185], v206 offset:6144
	ds_read_b128 v[208:211], v206 offset:7168
	global_load_lds_dwordx4 v154, s[0:1]
	s_add_i32 m0, s71, 0xe000
	s_nop 0
	global_load_lds_dwordx4 v156, s[0:1]
	s_waitcnt lgkmcnt(8)
	s_barrier
	s_waitcnt lgkmcnt(0)
	v_mfma_f32_16x16x32_bf16 v[126:129], v[130:133], v[158:161], 0
	v_mfma_f32_16x16x32_bf16 v[126:129], v[134:137], v[162:165], v[126:129]
	v_mfma_f32_16x16x32_bf16 v[110:113], v[130:133], v[166:169], 0
	v_mfma_f32_16x16x32_bf16 v[110:113], v[134:137], v[170:173], v[110:113]
	v_mfma_f32_16x16x32_bf16 v[94:97], v[130:133], v[174:177], 0
	v_mfma_f32_16x16x32_bf16 v[94:97], v[134:137], v[178:181], v[94:97]
	v_mfma_f32_16x16x32_bf16 v[78:81], v[130:133], v[182:185], 0
	v_mfma_f32_16x16x32_bf16 v[78:81], v[134:137], v[208:211], v[78:81]
	v_mfma_f32_16x16x32_bf16 v[74:77], v[138:141], v[182:185], 0
	v_mfma_f32_16x16x32_bf16 v[74:77], v[142:145], v[208:211], v[74:77]
	v_mfma_f32_16x16x32_bf16 v[90:93], v[138:141], v[174:177], 0
	v_mfma_f32_16x16x32_bf16 v[90:93], v[142:145], v[178:181], v[90:93]
	v_mfma_f32_16x16x32_bf16 v[106:109], v[138:141], v[166:169], 0
	v_mfma_f32_16x16x32_bf16 v[106:109], v[142:145], v[170:173], v[106:109]
	v_mfma_f32_16x16x32_bf16 v[122:125], v[138:141], v[158:161], 0
	v_mfma_f32_16x16x32_bf16 v[122:125], v[142:145], v[162:165], v[122:125]
	s_barrier
	s_add_i32 s17, 0, 0x14000
	s_add_i32 s16, s16, s70
	s_add_u32 s2, s10, s6
	s_addc_u32 s3, s11, s7
	s_mov_b32 m0, s16
	ds_read_b128 v[212:215], v248 offset:16384
	ds_read_b128 v[216:219], v248 offset:17408
	ds_read_b128 v[220:223], v248 offset:18432
	ds_read_b128 v[224:227], v248 offset:19456
	global_load_lds_dwordx4 v148, s[10:11]
	s_add_i32 m0, s16, 0x2000
	s_nop 0
	global_load_lds_dwordx4 v152, s[10:11]
	s_barrier
	s_waitcnt lgkmcnt(0)
	v_mfma_f32_16x16x32_bf16 v[118:121], v[212:215], v[158:161], 0
	v_mfma_f32_16x16x32_bf16 v[118:121], v[216:219], v[162:165], v[118:121]
	v_mfma_f32_16x16x32_bf16 v[102:105], v[212:215], v[166:169], 0
	v_mfma_f32_16x16x32_bf16 v[102:105], v[216:219], v[170:173], v[102:105]
	v_mfma_f32_16x16x32_bf16 v[86:89], v[212:215], v[174:177], 0
	v_mfma_f32_16x16x32_bf16 v[86:89], v[216:219], v[178:181], v[86:89]
	v_mfma_f32_16x16x32_bf16 v[70:73], v[212:215], v[182:185], 0
	v_mfma_f32_16x16x32_bf16 v[70:73], v[216:219], v[208:211], v[70:73]
	v_mfma_f32_16x16x32_bf16 v[66:69], v[220:223], v[182:185], 0
	v_mfma_f32_16x16x32_bf16 v[66:69], v[224:227], v[208:211], v[66:69]
	v_mfma_f32_16x16x32_bf16 v[82:85], v[220:223], v[174:177], 0
	v_mfma_f32_16x16x32_bf16 v[82:85], v[224:227], v[178:181], v[82:85]
	v_mfma_f32_16x16x32_bf16 v[98:101], v[220:223], v[166:169], 0
	v_mfma_f32_16x16x32_bf16 v[98:101], v[224:227], v[170:173], v[98:101]
	v_mfma_f32_16x16x32_bf16 v[114:117], v[220:223], v[158:161], 0
	v_mfma_f32_16x16x32_bf16 v[114:117], v[224:227], v[162:165], v[114:117]
	s_barrier
	s_mov_b32 m0, s71
	s_add_u32 s98, s4, s6
	s_addc_u32 s99, s5, s7
	ds_read_b128 v[158:161], v206 offset:16384
	ds_read_b128 v[162:165], v206 offset:17408
	ds_read_b128 v[166:169], v206 offset:18432
	ds_read_b128 v[170:173], v206 offset:19456
	ds_read_b128 v[174:177], v206 offset:20480
	ds_read_b128 v[178:181], v206 offset:21504
	ds_read_b128 v[182:185], v206 offset:22528
	ds_read_b128 v[208:211], v206 offset:23552
	global_load_lds_dwordx4 v146, s[4:5]
	s_mov_b32 m0, s72
	s_nop 0
	global_load_lds_dwordx4 v150, s[4:5]
	s_barrier
	s_waitcnt lgkmcnt(0)
	v_mfma_f32_16x16x32_bf16 v[62:65], v[130:133], v[158:161], 0
	v_mfma_f32_16x16x32_bf16 v[62:65], v[134:137], v[162:165], v[62:65]
	v_mfma_f32_16x16x32_bf16 v[46:49], v[130:133], v[166:169], 0
	v_mfma_f32_16x16x32_bf16 v[46:49], v[134:137], v[170:173], v[46:49]
	v_mfma_f32_16x16x32_bf16 v[30:33], v[130:133], v[174:177], 0
	v_mfma_f32_16x16x32_bf16 v[30:33], v[134:137], v[178:181], v[30:33]
	v_mfma_f32_16x16x32_bf16 v[14:17], v[130:133], v[182:185], 0
	v_mfma_f32_16x16x32_bf16 v[14:17], v[134:137], v[208:211], v[14:17]
	v_mfma_f32_16x16x32_bf16 v[10:13], v[138:141], v[182:185], 0
	v_mfma_f32_16x16x32_bf16 v[10:13], v[142:145], v[208:211], v[10:13]
	v_mfma_f32_16x16x32_bf16 v[26:29], v[138:141], v[174:177], 0
	v_mfma_f32_16x16x32_bf16 v[26:29], v[142:145], v[178:181], v[26:29]
	v_mfma_f32_16x16x32_bf16 v[42:45], v[138:141], v[166:169], 0
	v_mfma_f32_16x16x32_bf16 v[42:45], v[142:145], v[170:173], v[42:45]
	v_mfma_f32_16x16x32_bf16 v[58:61], v[138:141], v[158:161], 0
	v_mfma_f32_16x16x32_bf16 v[58:61], v[142:145], v[162:165], v[58:61]
	s_barrier
	s_add_u32 s10, s10, s92
	s_addc_u32 s11, s11, 0
	s_add_i32 s16, s17, s70
	v_lshl_add_u64 v[236:237], s[10:11], 0, v[148:149]
	s_mov_b32 m0, s16
	v_lshl_add_u64 v[238:239], s[10:11], 0, v[152:153]
	global_load_lds_dwordx4 v[236:237], off
	s_add_i32 m0, s16, 0x2000
	s_nop 0
	global_load_lds_dwordx4 v[238:239], off
	s_waitcnt vmcnt(6)
	s_barrier
	v_mfma_f32_16x16x32_bf16 v[54:57], v[212:215], v[158:161], 0
	v_mfma_f32_16x16x32_bf16 v[54:57], v[216:219], v[162:165], v[54:57]
	v_mfma_f32_16x16x32_bf16 v[38:41], v[212:215], v[166:169], 0
	v_mfma_f32_16x16x32_bf16 v[38:41], v[216:219], v[170:173], v[38:41]
	v_mfma_f32_16x16x32_bf16 v[22:25], v[212:215], v[174:177], 0
	v_mfma_f32_16x16x32_bf16 v[22:25], v[216:219], v[178:181], v[22:25]
	v_mfma_f32_16x16x32_bf16 v[6:9], v[212:215], v[182:185], 0
	v_mfma_f32_16x16x32_bf16 v[6:9], v[216:219], v[208:211], v[6:9]
	v_mfma_f32_16x16x32_bf16 v[2:5], v[220:223], v[182:185], 0
	v_mfma_f32_16x16x32_bf16 v[2:5], v[224:227], v[208:211], v[2:5]
	v_mfma_f32_16x16x32_bf16 v[18:21], v[220:223], v[174:177], 0
	v_mfma_f32_16x16x32_bf16 v[18:21], v[224:227], v[178:181], v[18:21]
	v_mfma_f32_16x16x32_bf16 v[34:37], v[220:223], v[166:169], 0
	v_mfma_f32_16x16x32_bf16 v[34:37], v[224:227], v[170:173], v[34:37]
	v_mfma_f32_16x16x32_bf16 v[50:53], v[220:223], v[158:161], 0
	v_mfma_f32_16x16x32_bf16 v[50:53], v[224:227], v[162:165], v[50:53]
	s_barrier
	s_add_i32 s10, 0, 0x18000
	ds_read_b128 v[130:133], v248 offset:32768
	ds_read_b128 v[134:137], v248 offset:33792
	ds_read_b128 v[138:141], v248 offset:34816
	ds_read_b128 v[142:145], v248 offset:35840
	s_add_u32 s4, s4, s92
	s_addc_u32 s5, s5, 0
	s_mov_b32 m0, s73
	ds_read_b128 v[158:161], v206 offset:32768
	ds_read_b128 v[162:165], v206 offset:33792
	ds_read_b128 v[166:169], v206 offset:34816
	ds_read_b128 v[170:173], v206 offset:35840
	ds_read_b128 v[174:177], v206 offset:36864
	ds_read_b128 v[178:181], v206 offset:37888
	ds_read_b128 v[182:185], v206 offset:38912
	ds_read_b128 v[208:211], v206 offset:39936
	global_load_lds_dwordx4 v146, s[4:5]
	s_mov_b32 m0, s74
	s_nop 0
	global_load_lds_dwordx4 v150, s[4:5]
	s_waitcnt lgkmcnt(8)
	s_barrier
	s_waitcnt lgkmcnt(0)
	v_mfma_f32_16x16x32_bf16 v[126:129], v[130:133], v[158:161], v[126:129]
	v_mfma_f32_16x16x32_bf16 v[126:129], v[134:137], v[162:165], v[126:129]
	v_mfma_f32_16x16x32_bf16 v[110:113], v[130:133], v[166:169], v[110:113]
	v_mfma_f32_16x16x32_bf16 v[110:113], v[134:137], v[170:173], v[110:113]
	v_mfma_f32_16x16x32_bf16 v[94:97], v[130:133], v[174:177], v[94:97]
	v_mfma_f32_16x16x32_bf16 v[94:97], v[134:137], v[178:181], v[94:97]
	v_mfma_f32_16x16x32_bf16 v[78:81], v[130:133], v[182:185], v[78:81]
	v_mfma_f32_16x16x32_bf16 v[78:81], v[134:137], v[208:211], v[78:81]
	v_mfma_f32_16x16x32_bf16 v[74:77], v[138:141], v[182:185], v[74:77]
	v_mfma_f32_16x16x32_bf16 v[74:77], v[142:145], v[208:211], v[74:77]
	v_mfma_f32_16x16x32_bf16 v[90:93], v[138:141], v[174:177], v[90:93]
	v_mfma_f32_16x16x32_bf16 v[90:93], v[142:145], v[178:181], v[90:93]
	v_mfma_f32_16x16x32_bf16 v[106:109], v[138:141], v[166:169], v[106:109]
	v_mfma_f32_16x16x32_bf16 v[106:109], v[142:145], v[170:173], v[106:109]
	v_mfma_f32_16x16x32_bf16 v[122:125], v[138:141], v[158:161], v[122:125]
	v_mfma_f32_16x16x32_bf16 v[122:125], v[142:145], v[162:165], v[122:125]
	s_barrier
	s_add_i32 s4, 0, 0x1c000
	s_add_i32 s5, s10, s70
	s_mov_b32 m0, s5
	ds_read_b128 v[212:215], v248 offset:49152
	ds_read_b128 v[216:219], v248 offset:50176
	ds_read_b128 v[220:223], v248 offset:51200
	ds_read_b128 v[224:227], v248 offset:52224
	global_load_lds_dwordx4 v148, s[2:3]
	s_add_i32 m0, s5, 0x2000
	s_nop 0
	global_load_lds_dwordx4 v152, s[2:3]
	s_barrier
	s_waitcnt lgkmcnt(0)
	v_mfma_f32_16x16x32_bf16 v[118:121], v[212:215], v[158:161], v[118:121]
	v_mfma_f32_16x16x32_bf16 v[118:121], v[216:219], v[162:165], v[118:121]
	v_mfma_f32_16x16x32_bf16 v[102:105], v[212:215], v[166:169], v[102:105]
	v_mfma_f32_16x16x32_bf16 v[102:105], v[216:219], v[170:173], v[102:105]
	v_mfma_f32_16x16x32_bf16 v[86:89], v[212:215], v[174:177], v[86:89]
	v_mfma_f32_16x16x32_bf16 v[86:89], v[216:219], v[178:181], v[86:89]
	v_mfma_f32_16x16x32_bf16 v[70:73], v[212:215], v[182:185], v[70:73]
	v_mfma_f32_16x16x32_bf16 v[70:73], v[216:219], v[208:211], v[70:73]
	v_mfma_f32_16x16x32_bf16 v[66:69], v[220:223], v[182:185], v[66:69]
	v_mfma_f32_16x16x32_bf16 v[66:69], v[224:227], v[208:211], v[66:69]
	v_mfma_f32_16x16x32_bf16 v[82:85], v[220:223], v[174:177], v[82:85]
	v_mfma_f32_16x16x32_bf16 v[82:85], v[224:227], v[178:181], v[82:85]
	v_mfma_f32_16x16x32_bf16 v[98:101], v[220:223], v[166:169], v[98:101]
	v_mfma_f32_16x16x32_bf16 v[98:101], v[224:227], v[170:173], v[98:101]
	v_mfma_f32_16x16x32_bf16 v[114:117], v[220:223], v[158:161], v[114:117]
	v_mfma_f32_16x16x32_bf16 v[114:117], v[224:227], v[162:165], v[114:117]
	s_barrier
	s_mov_b32 m0, s77
	ds_read_b128 v[158:161], v206 offset:49152
	ds_read_b128 v[162:165], v206 offset:50176
	ds_read_b128 v[166:169], v206 offset:51200
	ds_read_b128 v[170:173], v206 offset:52224
	ds_read_b128 v[174:177], v206 offset:53248
	ds_read_b128 v[178:181], v206 offset:54272
	ds_read_b128 v[182:185], v206 offset:55296
	ds_read_b128 v[208:211], v206 offset:56320
	global_load_lds_dwordx4 v146, s[98:99]
	s_mov_b32 m0, s78
	s_nop 0
	global_load_lds_dwordx4 v150, s[98:99]
	s_barrier
	s_waitcnt lgkmcnt(0)
	v_mfma_f32_16x16x32_bf16 v[62:65], v[130:133], v[158:161], v[62:65]
	v_mfma_f32_16x16x32_bf16 v[62:65], v[134:137], v[162:165], v[62:65]
	v_mfma_f32_16x16x32_bf16 v[46:49], v[130:133], v[166:169], v[46:49]
	v_mfma_f32_16x16x32_bf16 v[46:49], v[134:137], v[170:173], v[46:49]
	v_mfma_f32_16x16x32_bf16 v[30:33], v[130:133], v[174:177], v[30:33]
	v_mfma_f32_16x16x32_bf16 v[30:33], v[134:137], v[178:181], v[30:33]
	v_mfma_f32_16x16x32_bf16 v[14:17], v[130:133], v[182:185], v[14:17]
	v_mfma_f32_16x16x32_bf16 v[14:17], v[134:137], v[208:211], v[14:17]
	v_mfma_f32_16x16x32_bf16 v[10:13], v[138:141], v[182:185], v[10:13]
	v_mfma_f32_16x16x32_bf16 v[10:13], v[142:145], v[208:211], v[10:13]
	v_mfma_f32_16x16x32_bf16 v[26:29], v[138:141], v[174:177], v[26:29]
	v_mfma_f32_16x16x32_bf16 v[26:29], v[142:145], v[178:181], v[26:29]
	v_mfma_f32_16x16x32_bf16 v[42:45], v[138:141], v[166:169], v[42:45]
	v_mfma_f32_16x16x32_bf16 v[42:45], v[142:145], v[170:173], v[42:45]
	v_mfma_f32_16x16x32_bf16 v[58:61], v[138:141], v[158:161], v[58:61]
	v_mfma_f32_16x16x32_bf16 v[58:61], v[142:145], v[162:165], v[58:61]
	s_barrier
	s_add_i32 s4, s4, s70
	v_lshl_add_u64 v[130:131], v[236:237], 0, s[6:7]
	s_mov_b32 m0, s4
	s_nop 0
	global_load_lds_dwordx4 v[130:131], off
	v_lshl_add_u64 v[130:131], v[238:239], 0, s[6:7]
	s_add_i32 m0, s4, 0x2000
	s_nop 0
	global_load_lds_dwordx4 v[130:131], off
	s_add_u32 s0, s0, 0x100
	s_addc_u32 s1, s1, 0
	s_add_u32 s12, s12, 0x100
	s_addc_u32 s13, s13, 0
	s_cmp_ge_u32 s15, s75
	s_mov_b32 s4, s15
	s_waitcnt vmcnt(6)
	s_barrier
	v_mfma_f32_16x16x32_bf16 v[54:57], v[212:215], v[158:161], v[54:57]
	v_mfma_f32_16x16x32_bf16 v[54:57], v[216:219], v[162:165], v[54:57]
	v_mfma_f32_16x16x32_bf16 v[38:41], v[212:215], v[166:169], v[38:41]
	v_mfma_f32_16x16x32_bf16 v[38:41], v[216:219], v[170:173], v[38:41]
	v_mfma_f32_16x16x32_bf16 v[22:25], v[212:215], v[174:177], v[22:25]
	v_mfma_f32_16x16x32_bf16 v[22:25], v[216:219], v[178:181], v[22:25]
	v_mfma_f32_16x16x32_bf16 v[6:9], v[212:215], v[182:185], v[6:9]
	v_mfma_f32_16x16x32_bf16 v[6:9], v[216:219], v[208:211], v[6:9]
	v_mfma_f32_16x16x32_bf16 v[2:5], v[220:223], v[182:185], v[2:5]
	v_mfma_f32_16x16x32_bf16 v[2:5], v[224:227], v[208:211], v[2:5]
	v_mfma_f32_16x16x32_bf16 v[18:21], v[220:223], v[174:177], v[18:21]
	v_mfma_f32_16x16x32_bf16 v[18:21], v[224:227], v[178:181], v[18:21]
	v_mfma_f32_16x16x32_bf16 v[34:37], v[220:223], v[166:169], v[34:37]
	v_mfma_f32_16x16x32_bf16 v[34:37], v[224:227], v[170:173], v[34:37]
	v_mfma_f32_16x16x32_bf16 v[50:53], v[220:223], v[158:161], v[50:53]
	v_mfma_f32_16x16x32_bf16 v[50:53], v[224:227], v[162:165], v[50:53]
	s_barrier
	s_cbranch_scc1 .Lkexit_347
.LBB0_347:
	s_add_i32 s15, s4, 2
	s_add_u32 s10, s0, 0x80
	s_addc_u32 s5, s1, 0
	s_add_i32 s16, 0, 0x10000
	ds_read_b128 v[130:133], v248
	ds_read_b128 v[134:137], v248 offset:1024
	ds_read_b128 v[138:141], v248 offset:2048
	ds_read_b128 v[142:145], v248 offset:3072
	s_cmp_eq_u32 s79, s4
	s_cselect_b32 s4, s44, s10
	s_cselect_b32 s5, s45, s5
	s_cselect_b32 s11, s47, s13
	s_cselect_b32 s10, s46, s12
	s_add_i32 m0, s71, 0xc000
	ds_read_b128 v[158:161], v206
	ds_read_b128 v[162:165], v206 offset:1024
	ds_read_b128 v[166:169], v206 offset:2048
	ds_read_b128 v[170:173], v206 offset:3072
	ds_read_b128 v[174:177], v206 offset:4096
	ds_read_b128 v[178:181], v206 offset:5120
	ds_read_b128 v[182:185], v206 offset:6144
	ds_read_b128 v[208:211], v206 offset:7168
	global_load_lds_dwordx4 v154, s[0:1]
	s_add_i32 m0, s71, 0xe000
	s_nop 0
	global_load_lds_dwordx4 v156, s[0:1]
	s_waitcnt lgkmcnt(8)
	s_barrier
	s_waitcnt lgkmcnt(0)
	v_mfma_f32_16x16x32_bf16 v[126:129], v[130:133], v[158:161], v[126:129]
	v_mfma_f32_16x16x32_bf16 v[126:129], v[134:137], v[162:165], v[126:129]
	v_mfma_f32_16x16x32_bf16 v[110:113], v[130:133], v[166:169], v[110:113]
	v_mfma_f32_16x16x32_bf16 v[110:113], v[134:137], v[170:173], v[110:113]
	v_mfma_f32_16x16x32_bf16 v[94:97], v[130:133], v[174:177], v[94:97]
	v_mfma_f32_16x16x32_bf16 v[94:97], v[134:137], v[178:181], v[94:97]
	v_mfma_f32_16x16x32_bf16 v[78:81], v[130:133], v[182:185], v[78:81]
	v_mfma_f32_16x16x32_bf16 v[78:81], v[134:137], v[208:211], v[78:81]
	v_mfma_f32_16x16x32_bf16 v[74:77], v[138:141], v[182:185], v[74:77]
	v_mfma_f32_16x16x32_bf16 v[74:77], v[142:145], v[208:211], v[74:77]
	v_mfma_f32_16x16x32_bf16 v[90:93], v[138:141], v[174:177], v[90:93]
	v_mfma_f32_16x16x32_bf16 v[90:93], v[142:145], v[178:181], v[90:93]
	v_mfma_f32_16x16x32_bf16 v[106:109], v[138:141], v[166:169], v[106:109]
	v_mfma_f32_16x16x32_bf16 v[106:109], v[142:145], v[170:173], v[106:109]
	v_mfma_f32_16x16x32_bf16 v[122:125], v[138:141], v[158:161], v[122:125]
	v_mfma_f32_16x16x32_bf16 v[122:125], v[142:145], v[162:165], v[122:125]
	s_barrier
	s_add_i32 s17, 0, 0x14000
	s_add_i32 s16, s16, s70
	s_add_u32 s2, s10, s6
	s_addc_u32 s3, s11, s7
	s_mov_b32 m0, s16
	ds_read_b128 v[212:215], v248 offset:16384
	ds_read_b128 v[216:219], v248 offset:17408
	ds_read_b128 v[220:223], v248 offset:18432
	ds_read_b128 v[224:227], v248 offset:19456
	global_load_lds_dwordx4 v148, s[10:11]
	s_add_i32 m0, s16, 0x2000
	s_nop 0
	global_load_lds_dwordx4 v152, s[10:11]
	s_barrier
	s_waitcnt lgkmcnt(0)
	v_mfma_f32_16x16x32_bf16 v[118:121], v[212:215], v[158:161], v[118:121]
	v_mfma_f32_16x16x32_bf16 v[118:121], v[216:219], v[162:165], v[118:121]
	v_mfma_f32_16x16x32_bf16 v[102:105], v[212:215], v[166:169], v[102:105]
	v_mfma_f32_16x16x32_bf16 v[102:105], v[216:219], v[170:173], v[102:105]
	v_mfma_f32_16x16x32_bf16 v[86:89], v[212:215], v[174:177], v[86:89]
	v_mfma_f32_16x16x32_bf16 v[86:89], v[216:219], v[178:181], v[86:89]
	v_mfma_f32_16x16x32_bf16 v[70:73], v[212:215], v[182:185], v[70:73]
	v_mfma_f32_16x16x32_bf16 v[70:73], v[216:219], v[208:211], v[70:73]
	v_mfma_f32_16x16x32_bf16 v[66:69], v[220:223], v[182:185], v[66:69]
	v_mfma_f32_16x16x32_bf16 v[66:69], v[224:227], v[208:211], v[66:69]
	v_mfma_f32_16x16x32_bf16 v[82:85], v[220:223], v[174:177], v[82:85]
	v_mfma_f32_16x16x32_bf16 v[82:85], v[224:227], v[178:181], v[82:85]
	v_mfma_f32_16x16x32_bf16 v[98:101], v[220:223], v[166:169], v[98:101]
	v_mfma_f32_16x16x32_bf16 v[98:101], v[224:227], v[170:173], v[98:101]
	v_mfma_f32_16x16x32_bf16 v[114:117], v[220:223], v[158:161], v[114:117]
	v_mfma_f32_16x16x32_bf16 v[114:117], v[224:227], v[162:165], v[114:117]
	s_barrier
	s_mov_b32 m0, s71
	s_add_u32 s98, s4, s6
	s_addc_u32 s99, s5, s7
	ds_read_b128 v[158:161], v206 offset:16384
	ds_read_b128 v[162:165], v206 offset:17408
	ds_read_b128 v[166:169], v206 offset:18432
	ds_read_b128 v[170:173], v206 offset:19456
	ds_read_b128 v[174:177], v206 offset:20480
	ds_read_b128 v[178:181], v206 offset:21504
	ds_read_b128 v[182:185], v206 offset:22528
	ds_read_b128 v[208:211], v206 offset:23552
	global_load_lds_dwordx4 v146, s[4:5]
	s_mov_b32 m0, s72
	s_nop 0
	global_load_lds_dwordx4 v150, s[4:5]
	s_barrier
	s_waitcnt lgkmcnt(0)
	v_mfma_f32_16x16x32_bf16 v[62:65], v[130:133], v[158:161], v[62:65]
	v_mfma_f32_16x16x32_bf16 v[62:65], v[134:137], v[162:165], v[62:65]
	v_mfma_f32_16x16x32_bf16 v[46:49], v[130:133], v[166:169], v[46:49]
	v_mfma_f32_16x16x32_bf16 v[46:49], v[134:137], v[170:173], v[46:49]
	v_mfma_f32_16x16x32_bf16 v[30:33], v[130:133], v[174:177], v[30:33]
	v_mfma_f32_16x16x32_bf16 v[30:33], v[134:137], v[178:181], v[30:33]
	v_mfma_f32_16x16x32_bf16 v[14:17], v[130:133], v[182:185], v[14:17]
	v_mfma_f32_16x16x32_bf16 v[14:17], v[134:137], v[208:211], v[14:17]
	v_mfma_f32_16x16x32_bf16 v[10:13], v[138:141], v[182:185], v[10:13]
	v_mfma_f32_16x16x32_bf16 v[10:13], v[142:145], v[208:211], v[10:13]
	v_mfma_f32_16x16x32_bf16 v[26:29], v[138:141], v[174:177], v[26:29]
	v_mfma_f32_16x16x32_bf16 v[26:29], v[142:145], v[178:181], v[26:29]
	v_mfma_f32_16x16x32_bf16 v[42:45], v[138:141], v[166:169], v[42:45]
	v_mfma_f32_16x16x32_bf16 v[42:45], v[142:145], v[170:173], v[42:45]
	v_mfma_f32_16x16x32_bf16 v[58:61], v[138:141], v[158:161], v[58:61]
	v_mfma_f32_16x16x32_bf16 v[58:61], v[142:145], v[162:165], v[58:61]
	s_barrier
	s_add_u32 s10, s10, s92
	s_addc_u32 s11, s11, 0
	s_add_i32 s16, s17, s70
	v_lshl_add_u64 v[236:237], s[10:11], 0, v[148:149]
	s_mov_b32 m0, s16
	v_lshl_add_u64 v[238:239], s[10:11], 0, v[152:153]
	global_load_lds_dwordx4 v[236:237], off
	s_add_i32 m0, s16, 0x2000
	s_nop 0
	global_load_lds_dwordx4 v[238:239], off
	s_waitcnt vmcnt(6)
	s_barrier
	v_mfma_f32_16x16x32_bf16 v[54:57], v[212:215], v[158:161], v[54:57]
	v_mfma_f32_16x16x32_bf16 v[54:57], v[216:219], v[162:165], v[54:57]
	v_mfma_f32_16x16x32_bf16 v[38:41], v[212:215], v[166:169], v[38:41]
	v_mfma_f32_16x16x32_bf16 v[38:41], v[216:219], v[170:173], v[38:41]
	v_mfma_f32_16x16x32_bf16 v[22:25], v[212:215], v[174:177], v[22:25]
	v_mfma_f32_16x16x32_bf16 v[22:25], v[216:219], v[178:181], v[22:25]
	v_mfma_f32_16x16x32_bf16 v[6:9], v[212:215], v[182:185], v[6:9]
	v_mfma_f32_16x16x32_bf16 v[6:9], v[216:219], v[208:211], v[6:9]
	v_mfma_f32_16x16x32_bf16 v[2:5], v[220:223], v[182:185], v[2:5]
	v_mfma_f32_16x16x32_bf16 v[2:5], v[224:227], v[208:211], v[2:5]
	v_mfma_f32_16x16x32_bf16 v[18:21], v[220:223], v[174:177], v[18:21]
	v_mfma_f32_16x16x32_bf16 v[18:21], v[224:227], v[178:181], v[18:21]
	v_mfma_f32_16x16x32_bf16 v[34:37], v[220:223], v[166:169], v[34:37]
	v_mfma_f32_16x16x32_bf16 v[34:37], v[224:227], v[170:173], v[34:37]
	v_mfma_f32_16x16x32_bf16 v[50:53], v[220:223], v[158:161], v[50:53]
	v_mfma_f32_16x16x32_bf16 v[50:53], v[224:227], v[162:165], v[50:53]
	s_barrier
	s_add_i32 s10, 0, 0x18000
	ds_read_b128 v[130:133], v248 offset:32768
	ds_read_b128 v[134:137], v248 offset:33792
	ds_read_b128 v[138:141], v248 offset:34816
	ds_read_b128 v[142:145], v248 offset:35840
	s_add_u32 s4, s4, s92
	s_addc_u32 s5, s5, 0
	s_mov_b32 m0, s73
	ds_read_b128 v[158:161], v206 offset:32768
	ds_read_b128 v[162:165], v206 offset:33792
	ds_read_b128 v[166:169], v206 offset:34816
	ds_read_b128 v[170:173], v206 offset:35840
	ds_read_b128 v[174:177], v206 offset:36864
	ds_read_b128 v[178:181], v206 offset:37888
	ds_read_b128 v[182:185], v206 offset:38912
	ds_read_b128 v[208:211], v206 offset:39936
	global_load_lds_dwordx4 v146, s[4:5]
	s_mov_b32 m0, s74
	s_nop 0
	global_load_lds_dwordx4 v150, s[4:5]
	s_waitcnt lgkmcnt(8)
	s_barrier
	s_waitcnt lgkmcnt(0)
	v_mfma_f32_16x16x32_bf16 v[126:129], v[130:133], v[158:161], v[126:129]
	v_mfma_f32_16x16x32_bf16 v[126:129], v[134:137], v[162:165], v[126:129]
	v_mfma_f32_16x16x32_bf16 v[110:113], v[130:133], v[166:169], v[110:113]
	v_mfma_f32_16x16x32_bf16 v[110:113], v[134:137], v[170:173], v[110:113]
	v_mfma_f32_16x16x32_bf16 v[94:97], v[130:133], v[174:177], v[94:97]
	v_mfma_f32_16x16x32_bf16 v[94:97], v[134:137], v[178:181], v[94:97]
	v_mfma_f32_16x16x32_bf16 v[78:81], v[130:133], v[182:185], v[78:81]
	v_mfma_f32_16x16x32_bf16 v[78:81], v[134:137], v[208:211], v[78:81]
	v_mfma_f32_16x16x32_bf16 v[74:77], v[138:141], v[182:185], v[74:77]
	v_mfma_f32_16x16x32_bf16 v[74:77], v[142:145], v[208:211], v[74:77]
	v_mfma_f32_16x16x32_bf16 v[90:93], v[138:141], v[174:177], v[90:93]
	v_mfma_f32_16x16x32_bf16 v[90:93], v[142:145], v[178:181], v[90:93]
	v_mfma_f32_16x16x32_bf16 v[106:109], v[138:141], v[166:169], v[106:109]
	v_mfma_f32_16x16x32_bf16 v[106:109], v[142:145], v[170:173], v[106:109]
	v_mfma_f32_16x16x32_bf16 v[122:125], v[138:141], v[158:161], v[122:125]
	v_mfma_f32_16x16x32_bf16 v[122:125], v[142:145], v[162:165], v[122:125]
	s_barrier
	s_add_i32 s4, 0, 0x1c000
	s_add_i32 s5, s10, s70
	s_mov_b32 m0, s5
	ds_read_b128 v[212:215], v248 offset:49152
	ds_read_b128 v[216:219], v248 offset:50176
	ds_read_b128 v[220:223], v248 offset:51200
	ds_read_b128 v[224:227], v248 offset:52224
	global_load_lds_dwordx4 v148, s[2:3]
	s_add_i32 m0, s5, 0x2000
	s_nop 0
	global_load_lds_dwordx4 v152, s[2:3]
	s_barrier
	s_waitcnt lgkmcnt(0)
	v_mfma_f32_16x16x32_bf16 v[118:121], v[212:215], v[158:161], v[118:121]
	v_mfma_f32_16x16x32_bf16 v[118:121], v[216:219], v[162:165], v[118:121]
	v_mfma_f32_16x16x32_bf16 v[102:105], v[212:215], v[166:169], v[102:105]
	v_mfma_f32_16x16x32_bf16 v[102:105], v[216:219], v[170:173], v[102:105]
	v_mfma_f32_16x16x32_bf16 v[86:89], v[212:215], v[174:177], v[86:89]
	v_mfma_f32_16x16x32_bf16 v[86:89], v[216:219], v[178:181], v[86:89]
	v_mfma_f32_16x16x32_bf16 v[70:73], v[212:215], v[182:185], v[70:73]
	v_mfma_f32_16x16x32_bf16 v[70:73], v[216:219], v[208:211], v[70:73]
	v_mfma_f32_16x16x32_bf16 v[66:69], v[220:223], v[182:185], v[66:69]
	v_mfma_f32_16x16x32_bf16 v[66:69], v[224:227], v[208:211], v[66:69]
	v_mfma_f32_16x16x32_bf16 v[82:85], v[220:223], v[174:177], v[82:85]
	v_mfma_f32_16x16x32_bf16 v[82:85], v[224:227], v[178:181], v[82:85]
	v_mfma_f32_16x16x32_bf16 v[98:101], v[220:223], v[166:169], v[98:101]
	v_mfma_f32_16x16x32_bf16 v[98:101], v[224:227], v[170:173], v[98:101]
	v_mfma_f32_16x16x32_bf16 v[114:117], v[220:223], v[158:161], v[114:117]
	v_mfma_f32_16x16x32_bf16 v[114:117], v[224:227], v[162:165], v[114:117]
	s_barrier
	s_mov_b32 m0, s77
	ds_read_b128 v[158:161], v206 offset:49152
	ds_read_b128 v[162:165], v206 offset:50176
	ds_read_b128 v[166:169], v206 offset:51200
	ds_read_b128 v[170:173], v206 offset:52224
	ds_read_b128 v[174:177], v206 offset:53248
	ds_read_b128 v[178:181], v206 offset:54272
	ds_read_b128 v[182:185], v206 offset:55296
	ds_read_b128 v[208:211], v206 offset:56320
	global_load_lds_dwordx4 v146, s[98:99]
	s_mov_b32 m0, s78
	s_nop 0
	global_load_lds_dwordx4 v150, s[98:99]
	s_barrier
	s_waitcnt lgkmcnt(0)
	v_mfma_f32_16x16x32_bf16 v[62:65], v[130:133], v[158:161], v[62:65]
	v_mfma_f32_16x16x32_bf16 v[62:65], v[134:137], v[162:165], v[62:65]
	v_mfma_f32_16x16x32_bf16 v[46:49], v[130:133], v[166:169], v[46:49]
	v_mfma_f32_16x16x32_bf16 v[46:49], v[134:137], v[170:173], v[46:49]
	v_mfma_f32_16x16x32_bf16 v[30:33], v[130:133], v[174:177], v[30:33]
	v_mfma_f32_16x16x32_bf16 v[30:33], v[134:137], v[178:181], v[30:33]
	v_mfma_f32_16x16x32_bf16 v[14:17], v[130:133], v[182:185], v[14:17]
	v_mfma_f32_16x16x32_bf16 v[14:17], v[134:137], v[208:211], v[14:17]
	v_mfma_f32_16x16x32_bf16 v[10:13], v[138:141], v[182:185], v[10:13]
	v_mfma_f32_16x16x32_bf16 v[10:13], v[142:145], v[208:211], v[10:13]
	v_mfma_f32_16x16x32_bf16 v[26:29], v[138:141], v[174:177], v[26:29]
	v_mfma_f32_16x16x32_bf16 v[26:29], v[142:145], v[178:181], v[26:29]
	v_mfma_f32_16x16x32_bf16 v[42:45], v[138:141], v[166:169], v[42:45]
	v_mfma_f32_16x16x32_bf16 v[42:45], v[142:145], v[170:173], v[42:45]
	v_mfma_f32_16x16x32_bf16 v[58:61], v[138:141], v[158:161], v[58:61]
	v_mfma_f32_16x16x32_bf16 v[58:61], v[142:145], v[162:165], v[58:61]
	s_barrier
	s_add_i32 s4, s4, s70
	v_lshl_add_u64 v[130:131], v[236:237], 0, s[6:7]
	s_mov_b32 m0, s4
	s_nop 0
	global_load_lds_dwordx4 v[130:131], off
	v_lshl_add_u64 v[130:131], v[238:239], 0, s[6:7]
	s_add_i32 m0, s4, 0x2000
	s_nop 0
	global_load_lds_dwordx4 v[130:131], off
	s_add_u32 s0, s0, 0x100
	s_addc_u32 s1, s1, 0
	s_add_u32 s12, s12, 0x100
	s_addc_u32 s13, s13, 0
	s_cmp_ge_u32 s15, s75
	s_mov_b32 s4, s15
	s_waitcnt vmcnt(6)
	s_barrier
	v_mfma_f32_16x16x32_bf16 v[54:57], v[212:215], v[158:161], v[54:57]
	v_mfma_f32_16x16x32_bf16 v[54:57], v[216:219], v[162:165], v[54:57]
	v_mfma_f32_16x16x32_bf16 v[38:41], v[212:215], v[166:169], v[38:41]
	v_mfma_f32_16x16x32_bf16 v[38:41], v[216:219], v[170:173], v[38:41]
	v_mfma_f32_16x16x32_bf16 v[22:25], v[212:215], v[174:177], v[22:25]
	v_mfma_f32_16x16x32_bf16 v[22:25], v[216:219], v[178:181], v[22:25]
	v_mfma_f32_16x16x32_bf16 v[6:9], v[212:215], v[182:185], v[6:9]
	v_mfma_f32_16x16x32_bf16 v[6:9], v[216:219], v[208:211], v[6:9]
	v_mfma_f32_16x16x32_bf16 v[2:5], v[220:223], v[182:185], v[2:5]
	v_mfma_f32_16x16x32_bf16 v[2:5], v[224:227], v[208:211], v[2:5]
	v_mfma_f32_16x16x32_bf16 v[18:21], v[220:223], v[174:177], v[18:21]
	v_mfma_f32_16x16x32_bf16 v[18:21], v[224:227], v[178:181], v[18:21]
	v_mfma_f32_16x16x32_bf16 v[34:37], v[220:223], v[166:169], v[34:37]
	v_mfma_f32_16x16x32_bf16 v[34:37], v[224:227], v[170:173], v[34:37]
	v_mfma_f32_16x16x32_bf16 v[50:53], v[220:223], v[158:161], v[50:53]
	v_mfma_f32_16x16x32_bf16 v[50:53], v[224:227], v[162:165], v[50:53]
	s_barrier
	s_cbranch_scc0 .LBB0_347

.LBB0_663:
	s_add_u32 s0, s0, 0x80
	s_addc_u32 s1, s1, 0
	s_add_u32 s49, s4, 0x100
	s_addc_u32 s65, s5, 0
	s_mov_b32 s4, 0
	s_waitcnt lgkmcnt(0)
	s_waitcnt vmcnt(0)
	s_add_i32 s66, s4, 2
	s_add_u32 s18, s0, 0x80
	s_addc_u32 s5, s1, 0
	s_add_i32 s68, 0, 0x10000
	ds_read_b128 v[142:145], v248
	ds_read_b128 v[146:149], v248 offset:1024
	ds_read_b128 v[156:159], v248 offset:2048
	ds_read_b128 v[160:163], v248 offset:3072
	s_cmp_eq_u32 s43, s4
	s_cselect_b32 s4, s10, s18
	s_cselect_b32 s5, s11, s5
	s_cselect_b32 s19, s13, s65
	s_cselect_b32 s18, s12, s49
	s_add_i32 m0, s28, 0xc000
	ds_read_b128 v[164:167], v154
	ds_read_b128 v[168:171], v154 offset:1024
	ds_read_b128 v[172:175], v154 offset:2048
	ds_read_b128 v[176:179], v154 offset:3072
	ds_read_b128 v[180:183], v154 offset:4096
	ds_read_b128 v[204:207], v154 offset:5120
	ds_read_b128 v[208:211], v154 offset:6144
	ds_read_b128 v[212:215], v154 offset:7168
	global_load_lds_dwordx4 v138, s[0:1]
	s_add_i32 m0, s28, 0xe000
	s_nop 0
	global_load_lds_dwordx4 v140, s[0:1]
	s_waitcnt lgkmcnt(8)
	s_barrier
	s_waitcnt lgkmcnt(0)
	v_mfma_f32_16x16x32_bf16 v[126:129], v[142:145], v[164:167], 0
	v_mfma_f32_16x16x32_bf16 v[126:129], v[146:149], v[168:171], v[126:129]
	v_mfma_f32_16x16x32_bf16 v[110:113], v[142:145], v[172:175], 0
	v_mfma_f32_16x16x32_bf16 v[110:113], v[146:149], v[176:179], v[110:113]
	v_mfma_f32_16x16x32_bf16 v[94:97], v[142:145], v[180:183], 0
	v_mfma_f32_16x16x32_bf16 v[94:97], v[146:149], v[204:207], v[94:97]
	v_mfma_f32_16x16x32_bf16 v[78:81], v[142:145], v[208:211], 0
	v_mfma_f32_16x16x32_bf16 v[78:81], v[146:149], v[212:215], v[78:81]
	v_mfma_f32_16x16x32_bf16 v[74:77], v[156:159], v[208:211], 0
	v_mfma_f32_16x16x32_bf16 v[74:77], v[160:163], v[212:215], v[74:77]
	v_mfma_f32_16x16x32_bf16 v[90:93], v[156:159], v[180:183], 0
	v_mfma_f32_16x16x32_bf16 v[90:93], v[160:163], v[204:207], v[90:93]
	v_mfma_f32_16x16x32_bf16 v[106:109], v[156:159], v[172:175], 0
	v_mfma_f32_16x16x32_bf16 v[106:109], v[160:163], v[176:179], v[106:109]
	v_mfma_f32_16x16x32_bf16 v[122:125], v[156:159], v[164:167], 0
	v_mfma_f32_16x16x32_bf16 v[122:125], v[160:163], v[168:171], v[122:125]
	s_barrier
	s_add_i32 s69, 0, 0x14000
	s_add_i32 s68, s68, s25
	ds_read_b128 v[216:219], v248 offset:16384
	ds_read_b128 v[220:223], v248 offset:17408
	ds_read_b128 v[224:227], v248 offset:18432
	ds_read_b128 v[228:231], v248 offset:19456
	s_add_u32 s70, s18, s6
	s_addc_u32 s71, s19, s7
	s_mov_b32 m0, s68
	s_nop 0
	global_load_lds_dwordx4 v132, s[18:19]
	s_add_i32 m0, s68, 0x2000
	s_nop 0
	global_load_lds_dwordx4 v136, s[18:19]
	s_barrier
	s_waitcnt lgkmcnt(0)
	v_mfma_f32_16x16x32_bf16 v[118:121], v[216:219], v[164:167], 0
	v_mfma_f32_16x16x32_bf16 v[118:121], v[220:223], v[168:171], v[118:121]
	v_mfma_f32_16x16x32_bf16 v[102:105], v[216:219], v[172:175], 0
	v_mfma_f32_16x16x32_bf16 v[102:105], v[220:223], v[176:179], v[102:105]
	v_mfma_f32_16x16x32_bf16 v[86:89], v[216:219], v[180:183], 0
	v_mfma_f32_16x16x32_bf16 v[86:89], v[220:223], v[204:207], v[86:89]
	v_mfma_f32_16x16x32_bf16 v[70:73], v[216:219], v[208:211], 0
	v_mfma_f32_16x16x32_bf16 v[70:73], v[220:223], v[212:215], v[70:73]
	v_mfma_f32_16x16x32_bf16 v[66:69], v[224:227], v[208:211], 0
	v_mfma_f32_16x16x32_bf16 v[66:69], v[228:231], v[212:215], v[66:69]
	v_mfma_f32_16x16x32_bf16 v[82:85], v[224:227], v[180:183], 0
	v_mfma_f32_16x16x32_bf16 v[82:85], v[228:231], v[204:207], v[82:85]
	v_mfma_f32_16x16x32_bf16 v[98:101], v[224:227], v[172:175], 0
	v_mfma_f32_16x16x32_bf16 v[98:101], v[228:231], v[176:179], v[98:101]
	v_mfma_f32_16x16x32_bf16 v[114:117], v[224:227], v[164:167], 0
	v_mfma_f32_16x16x32_bf16 v[114:117], v[228:231], v[168:171], v[114:117]
	s_barrier
	s_mov_b32 m0, s28
	s_add_u32 s72, s4, s6
	s_addc_u32 s73, s5, s7
	ds_read_b128 v[164:167], v154 offset:16384
	ds_read_b128 v[168:171], v154 offset:17408
	ds_read_b128 v[172:175], v154 offset:18432
	ds_read_b128 v[176:179], v154 offset:19456
	ds_read_b128 v[180:183], v154 offset:20480
	ds_read_b128 v[204:207], v154 offset:21504
	ds_read_b128 v[208:211], v154 offset:22528
	ds_read_b128 v[212:215], v154 offset:23552
	global_load_lds_dwordx4 v130, s[4:5]
	s_mov_b32 m0, s29
	s_nop 0
	global_load_lds_dwordx4 v134, s[4:5]
	s_barrier
	s_waitcnt lgkmcnt(0)
	v_mfma_f32_16x16x32_bf16 v[62:65], v[142:145], v[164:167], 0
	v_mfma_f32_16x16x32_bf16 v[62:65], v[146:149], v[168:171], v[62:65]
	v_mfma_f32_16x16x32_bf16 v[46:49], v[142:145], v[172:175], 0
	v_mfma_f32_16x16x32_bf16 v[46:49], v[146:149], v[176:179], v[46:49]
	v_mfma_f32_16x16x32_bf16 v[30:33], v[142:145], v[180:183], 0
	v_mfma_f32_16x16x32_bf16 v[30:33], v[146:149], v[204:207], v[30:33]
	v_mfma_f32_16x16x32_bf16 v[14:17], v[142:145], v[208:211], 0
	v_mfma_f32_16x16x32_bf16 v[14:17], v[146:149], v[212:215], v[14:17]
	v_mfma_f32_16x16x32_bf16 v[10:13], v[156:159], v[208:211], 0
	v_mfma_f32_16x16x32_bf16 v[10:13], v[160:163], v[212:215], v[10:13]
	v_mfma_f32_16x16x32_bf16 v[26:29], v[156:159], v[180:183], 0
	v_mfma_f32_16x16x32_bf16 v[26:29], v[160:163], v[204:207], v[26:29]
	v_mfma_f32_16x16x32_bf16 v[42:45], v[156:159], v[172:175], 0
	v_mfma_f32_16x16x32_bf16 v[42:45], v[160:163], v[176:179], v[42:45]
	v_mfma_f32_16x16x32_bf16 v[58:61], v[156:159], v[164:167], 0
	v_mfma_f32_16x16x32_bf16 v[58:61], v[160:163], v[168:171], v[58:61]
	s_barrier
	s_add_u32 s18, s18, s14
	s_addc_u32 s19, s19, 0
	s_add_i32 s68, s69, s25
	s_add_u32 s76, s18, s6
	s_addc_u32 s77, s19, s7
	s_mov_b32 m0, s68
	s_nop 0
	global_load_lds_dwordx4 v132, s[18:19]
	s_add_i32 m0, s68, 0x2000
	s_nop 0
	global_load_lds_dwordx4 v136, s[18:19]
	s_waitcnt vmcnt(6)
	s_barrier
	v_mfma_f32_16x16x32_bf16 v[54:57], v[216:219], v[164:167], 0
	v_mfma_f32_16x16x32_bf16 v[54:57], v[220:223], v[168:171], v[54:57]
	v_mfma_f32_16x16x32_bf16 v[38:41], v[216:219], v[172:175], 0
	v_mfma_f32_16x16x32_bf16 v[38:41], v[220:223], v[176:179], v[38:41]
	v_mfma_f32_16x16x32_bf16 v[22:25], v[216:219], v[180:183], 0
	v_mfma_f32_16x16x32_bf16 v[22:25], v[220:223], v[204:207], v[22:25]
	v_mfma_f32_16x16x32_bf16 v[6:9], v[216:219], v[208:211], 0
	v_mfma_f32_16x16x32_bf16 v[6:9], v[220:223], v[212:215], v[6:9]
	v_mfma_f32_16x16x32_bf16 v[2:5], v[224:227], v[208:211], 0
	v_mfma_f32_16x16x32_bf16 v[2:5], v[228:231], v[212:215], v[2:5]
	v_mfma_f32_16x16x32_bf16 v[18:21], v[224:227], v[180:183], 0
	v_mfma_f32_16x16x32_bf16 v[18:21], v[228:231], v[204:207], v[18:21]
	v_mfma_f32_16x16x32_bf16 v[34:37], v[224:227], v[172:175], 0
	v_mfma_f32_16x16x32_bf16 v[34:37], v[228:231], v[176:179], v[34:37]
	v_mfma_f32_16x16x32_bf16 v[50:53], v[224:227], v[164:167], 0
	v_mfma_f32_16x16x32_bf16 v[50:53], v[228:231], v[168:171], v[50:53]
	s_barrier
	s_add_i32 s18, 0, 0x18000
	ds_read_b128 v[142:145], v248 offset:32768
	ds_read_b128 v[146:149], v248 offset:33792
	ds_read_b128 v[156:159], v248 offset:34816
	ds_read_b128 v[160:163], v248 offset:35840
	s_add_u32 s4, s4, s14
	s_addc_u32 s5, s5, 0
	s_mov_b32 m0, s31
	ds_read_b128 v[164:167], v154 offset:32768
	ds_read_b128 v[168:171], v154 offset:33792
	ds_read_b128 v[172:175], v154 offset:34816
	ds_read_b128 v[176:179], v154 offset:35840
	ds_read_b128 v[180:183], v154 offset:36864
	ds_read_b128 v[204:207], v154 offset:37888
	ds_read_b128 v[208:211], v154 offset:38912
	ds_read_b128 v[212:215], v154 offset:39936
	global_load_lds_dwordx4 v130, s[4:5]
	s_mov_b32 m0, s34
	s_nop 0
	global_load_lds_dwordx4 v134, s[4:5]
	s_waitcnt lgkmcnt(8)
	s_barrier
	s_waitcnt lgkmcnt(0)
	v_mfma_f32_16x16x32_bf16 v[126:129], v[142:145], v[164:167], v[126:129]
	v_mfma_f32_16x16x32_bf16 v[126:129], v[146:149], v[168:171], v[126:129]
	v_mfma_f32_16x16x32_bf16 v[110:113], v[142:145], v[172:175], v[110:113]
	v_mfma_f32_16x16x32_bf16 v[110:113], v[146:149], v[176:179], v[110:113]
	v_mfma_f32_16x16x32_bf16 v[94:97], v[142:145], v[180:183], v[94:97]
	v_mfma_f32_16x16x32_bf16 v[94:97], v[146:149], v[204:207], v[94:97]
	v_mfma_f32_16x16x32_bf16 v[78:81], v[142:145], v[208:211], v[78:81]
	v_mfma_f32_16x16x32_bf16 v[78:81], v[146:149], v[212:215], v[78:81]
	v_mfma_f32_16x16x32_bf16 v[74:77], v[156:159], v[208:211], v[74:77]
	v_mfma_f32_16x16x32_bf16 v[74:77], v[160:163], v[212:215], v[74:77]
	v_mfma_f32_16x16x32_bf16 v[90:93], v[156:159], v[180:183], v[90:93]
	v_mfma_f32_16x16x32_bf16 v[90:93], v[160:163], v[204:207], v[90:93]
	v_mfma_f32_16x16x32_bf16 v[106:109], v[156:159], v[172:175], v[106:109]
	v_mfma_f32_16x16x32_bf16 v[106:109], v[160:163], v[176:179], v[106:109]
	v_mfma_f32_16x16x32_bf16 v[122:125], v[156:159], v[164:167], v[122:125]
	v_mfma_f32_16x16x32_bf16 v[122:125], v[160:163], v[168:171], v[122:125]
	s_barrier
	s_add_i32 s4, 0, 0x1c000
	s_add_i32 s5, s18, s25
	s_mov_b32 m0, s5
	ds_read_b128 v[216:219], v248 offset:49152
	ds_read_b128 v[220:223], v248 offset:50176
	ds_read_b128 v[224:227], v248 offset:51200
	ds_read_b128 v[228:231], v248 offset:52224
	global_load_lds_dwordx4 v132, s[70:71]
	s_add_i32 m0, s5, 0x2000
	s_nop 0
	global_load_lds_dwordx4 v136, s[70:71]
	s_barrier
	s_waitcnt lgkmcnt(0)
	v_mfma_f32_16x16x32_bf16 v[118:121], v[216:219], v[164:167], v[118:121]
	v_mfma_f32_16x16x32_bf16 v[118:121], v[220:223], v[168:171], v[118:121]
	v_mfma_f32_16x16x32_bf16 v[102:105], v[216:219], v[172:175], v[102:105]
	v_mfma_f32_16x16x32_bf16 v[102:105], v[220:223], v[176:179], v[102:105]
	v_mfma_f32_16x16x32_bf16 v[86:89], v[216:219], v[180:183], v[86:89]
	v_mfma_f32_16x16x32_bf16 v[86:89], v[220:223], v[204:207], v[86:89]
	v_mfma_f32_16x16x32_bf16 v[70:73], v[216:219], v[208:211], v[70:73]
	v_mfma_f32_16x16x32_bf16 v[70:73], v[220:223], v[212:215], v[70:73]
	v_mfma_f32_16x16x32_bf16 v[66:69], v[224:227], v[208:211], v[66:69]
	v_mfma_f32_16x16x32_bf16 v[66:69], v[228:231], v[212:215], v[66:69]
	v_mfma_f32_16x16x32_bf16 v[82:85], v[224:227], v[180:183], v[82:85]
	v_mfma_f32_16x16x32_bf16 v[82:85], v[228:231], v[204:207], v[82:85]
	v_mfma_f32_16x16x32_bf16 v[98:101], v[224:227], v[172:175], v[98:101]
	v_mfma_f32_16x16x32_bf16 v[98:101], v[228:231], v[176:179], v[98:101]
	v_mfma_f32_16x16x32_bf16 v[114:117], v[224:227], v[164:167], v[114:117]
	v_mfma_f32_16x16x32_bf16 v[114:117], v[228:231], v[168:171], v[114:117]
	s_barrier
	s_mov_b32 m0, s41
	ds_read_b128 v[164:167], v154 offset:49152
	ds_read_b128 v[168:171], v154 offset:50176
	ds_read_b128 v[172:175], v154 offset:51200
	ds_read_b128 v[176:179], v154 offset:52224
	ds_read_b128 v[180:183], v154 offset:53248
	ds_read_b128 v[204:207], v154 offset:54272
	ds_read_b128 v[208:211], v154 offset:55296
	ds_read_b128 v[212:215], v154 offset:56320
	global_load_lds_dwordx4 v130, s[72:73]
	s_mov_b32 m0, s42
	s_nop 0
	global_load_lds_dwordx4 v134, s[72:73]
	s_barrier
	s_waitcnt lgkmcnt(0)
	v_mfma_f32_16x16x32_bf16 v[62:65], v[142:145], v[164:167], v[62:65]
	v_mfma_f32_16x16x32_bf16 v[62:65], v[146:149], v[168:171], v[62:65]
	v_mfma_f32_16x16x32_bf16 v[46:49], v[142:145], v[172:175], v[46:49]
	v_mfma_f32_16x16x32_bf16 v[46:49], v[146:149], v[176:179], v[46:49]
	v_mfma_f32_16x16x32_bf16 v[30:33], v[142:145], v[180:183], v[30:33]
	v_mfma_f32_16x16x32_bf16 v[30:33], v[146:149], v[204:207], v[30:33]
	v_mfma_f32_16x16x32_bf16 v[14:17], v[142:145], v[208:211], v[14:17]
	v_mfma_f32_16x16x32_bf16 v[14:17], v[146:149], v[212:215], v[14:17]
	v_mfma_f32_16x16x32_bf16 v[10:13], v[156:159], v[208:211], v[10:13]
	v_mfma_f32_16x16x32_bf16 v[10:13], v[160:163], v[212:215], v[10:13]
	v_mfma_f32_16x16x32_bf16 v[26:29], v[156:159], v[180:183], v[26:29]
	v_mfma_f32_16x16x32_bf16 v[26:29], v[160:163], v[204:207], v[26:29]
	v_mfma_f32_16x16x32_bf16 v[42:45], v[156:159], v[172:175], v[42:45]
	v_mfma_f32_16x16x32_bf16 v[42:45], v[160:163], v[176:179], v[42:45]
	v_mfma_f32_16x16x32_bf16 v[58:61], v[156:159], v[164:167], v[58:61]
	v_mfma_f32_16x16x32_bf16 v[58:61], v[160:163], v[168:171], v[58:61]
	s_barrier
	s_add_i32 s4, s4, s25
	s_mov_b32 m0, s4
	s_nop 0
	global_load_lds_dwordx4 v132, s[76:77]
	s_add_i32 m0, s4, 0x2000
	s_nop 0
	global_load_lds_dwordx4 v136, s[76:77]
	s_add_u32 s0, s0, 0x100
	s_addc_u32 s1, s1, 0
	s_add_u32 s49, s49, 0x100
	s_addc_u32 s65, s65, 0
	s_cmp_ge_u32 s66, s35
	s_mov_b32 s4, s66
	s_waitcnt vmcnt(6)
	s_barrier
	v_mfma_f32_16x16x32_bf16 v[54:57], v[216:219], v[164:167], v[54:57]
	v_mfma_f32_16x16x32_bf16 v[54:57], v[220:223], v[168:171], v[54:57]
	v_mfma_f32_16x16x32_bf16 v[38:41], v[216:219], v[172:175], v[38:41]
	v_mfma_f32_16x16x32_bf16 v[38:41], v[220:223], v[176:179], v[38:41]
	v_mfma_f32_16x16x32_bf16 v[22:25], v[216:219], v[180:183], v[22:25]
	v_mfma_f32_16x16x32_bf16 v[22:25], v[220:223], v[204:207], v[22:25]
	v_mfma_f32_16x16x32_bf16 v[6:9], v[216:219], v[208:211], v[6:9]
	v_mfma_f32_16x16x32_bf16 v[6:9], v[220:223], v[212:215], v[6:9]
	v_mfma_f32_16x16x32_bf16 v[2:5], v[224:227], v[208:211], v[2:5]
	v_mfma_f32_16x16x32_bf16 v[2:5], v[228:231], v[212:215], v[2:5]
	v_mfma_f32_16x16x32_bf16 v[18:21], v[224:227], v[180:183], v[18:21]
	v_mfma_f32_16x16x32_bf16 v[18:21], v[228:231], v[204:207], v[18:21]
	v_mfma_f32_16x16x32_bf16 v[34:37], v[224:227], v[172:175], v[34:37]
	v_mfma_f32_16x16x32_bf16 v[34:37], v[228:231], v[176:179], v[34:37]
	v_mfma_f32_16x16x32_bf16 v[50:53], v[224:227], v[164:167], v[50:53]
	v_mfma_f32_16x16x32_bf16 v[50:53], v[228:231], v[168:171], v[50:53]
	s_barrier
	s_cbranch_scc1 .Lkexit_664
.LBB0_664:
	s_add_i32 s66, s4, 2
	s_add_u32 s18, s0, 0x80
	s_addc_u32 s5, s1, 0
	s_add_i32 s68, 0, 0x10000
	ds_read_b128 v[142:145], v248
	ds_read_b128 v[146:149], v248 offset:1024
	ds_read_b128 v[156:159], v248 offset:2048
	ds_read_b128 v[160:163], v248 offset:3072
	s_cmp_eq_u32 s43, s4
	s_cselect_b32 s4, s10, s18
	s_cselect_b32 s5, s11, s5
	s_cselect_b32 s19, s13, s65
	s_cselect_b32 s18, s12, s49
	s_add_i32 m0, s28, 0xc000
	ds_read_b128 v[164:167], v154
	ds_read_b128 v[168:171], v154 offset:1024
	ds_read_b128 v[172:175], v154 offset:2048
	ds_read_b128 v[176:179], v154 offset:3072
	ds_read_b128 v[180:183], v154 offset:4096
	ds_read_b128 v[204:207], v154 offset:5120
	ds_read_b128 v[208:211], v154 offset:6144
	ds_read_b128 v[212:215], v154 offset:7168
	global_load_lds_dwordx4 v138, s[0:1]
	s_add_i32 m0, s28, 0xe000
	s_nop 0
	global_load_lds_dwordx4 v140, s[0:1]
	s_waitcnt lgkmcnt(8)
	s_barrier
	s_waitcnt lgkmcnt(0)
	v_mfma_f32_16x16x32_bf16 v[126:129], v[142:145], v[164:167], v[126:129]
	v_mfma_f32_16x16x32_bf16 v[126:129], v[146:149], v[168:171], v[126:129]
	v_mfma_f32_16x16x32_bf16 v[110:113], v[142:145], v[172:175], v[110:113]
	v_mfma_f32_16x16x32_bf16 v[110:113], v[146:149], v[176:179], v[110:113]
	v_mfma_f32_16x16x32_bf16 v[94:97], v[142:145], v[180:183], v[94:97]
	v_mfma_f32_16x16x32_bf16 v[94:97], v[146:149], v[204:207], v[94:97]
	v_mfma_f32_16x16x32_bf16 v[78:81], v[142:145], v[208:211], v[78:81]
	v_mfma_f32_16x16x32_bf16 v[78:81], v[146:149], v[212:215], v[78:81]
	v_mfma_f32_16x16x32_bf16 v[74:77], v[156:159], v[208:211], v[74:77]
	v_mfma_f32_16x16x32_bf16 v[74:77], v[160:163], v[212:215], v[74:77]
	v_mfma_f32_16x16x32_bf16 v[90:93], v[156:159], v[180:183], v[90:93]
	v_mfma_f32_16x16x32_bf16 v[90:93], v[160:163], v[204:207], v[90:93]
	v_mfma_f32_16x16x32_bf16 v[106:109], v[156:159], v[172:175], v[106:109]
	v_mfma_f32_16x16x32_bf16 v[106:109], v[160:163], v[176:179], v[106:109]
	v_mfma_f32_16x16x32_bf16 v[122:125], v[156:159], v[164:167], v[122:125]
	v_mfma_f32_16x16x32_bf16 v[122:125], v[160:163], v[168:171], v[122:125]
	s_barrier
	s_add_i32 s69, 0, 0x14000
	s_add_i32 s68, s68, s25
	ds_read_b128 v[216:219], v248 offset:16384
	ds_read_b128 v[220:223], v248 offset:17408
	ds_read_b128 v[224:227], v248 offset:18432
	ds_read_b128 v[228:231], v248 offset:19456
	s_add_u32 s70, s18, s6
	s_addc_u32 s71, s19, s7
	s_mov_b32 m0, s68
	s_nop 0
	global_load_lds_dwordx4 v132, s[18:19]
	s_add_i32 m0, s68, 0x2000
	s_nop 0
	global_load_lds_dwordx4 v136, s[18:19]
	s_barrier
	s_waitcnt lgkmcnt(0)
	v_mfma_f32_16x16x32_bf16 v[118:121], v[216:219], v[164:167], v[118:121]
	v_mfma_f32_16x16x32_bf16 v[118:121], v[220:223], v[168:171], v[118:121]
	v_mfma_f32_16x16x32_bf16 v[102:105], v[216:219], v[172:175], v[102:105]
	v_mfma_f32_16x16x32_bf16 v[102:105], v[220:223], v[176:179], v[102:105]
	v_mfma_f32_16x16x32_bf16 v[86:89], v[216:219], v[180:183], v[86:89]
	v_mfma_f32_16x16x32_bf16 v[86:89], v[220:223], v[204:207], v[86:89]
	v_mfma_f32_16x16x32_bf16 v[70:73], v[216:219], v[208:211], v[70:73]
	v_mfma_f32_16x16x32_bf16 v[70:73], v[220:223], v[212:215], v[70:73]
	v_mfma_f32_16x16x32_bf16 v[66:69], v[224:227], v[208:211], v[66:69]
	v_mfma_f32_16x16x32_bf16 v[66:69], v[228:231], v[212:215], v[66:69]
	v_mfma_f32_16x16x32_bf16 v[82:85], v[224:227], v[180:183], v[82:85]
	v_mfma_f32_16x16x32_bf16 v[82:85], v[228:231], v[204:207], v[82:85]
	v_mfma_f32_16x16x32_bf16 v[98:101], v[224:227], v[172:175], v[98:101]
	v_mfma_f32_16x16x32_bf16 v[98:101], v[228:231], v[176:179], v[98:101]
	v_mfma_f32_16x16x32_bf16 v[114:117], v[224:227], v[164:167], v[114:117]
	v_mfma_f32_16x16x32_bf16 v[114:117], v[228:231], v[168:171], v[114:117]
	s_barrier
	s_mov_b32 m0, s28
	s_add_u32 s72, s4, s6
	s_addc_u32 s73, s5, s7
	ds_read_b128 v[164:167], v154 offset:16384
	ds_read_b128 v[168:171], v154 offset:17408
	ds_read_b128 v[172:175], v154 offset:18432
	ds_read_b128 v[176:179], v154 offset:19456
	ds_read_b128 v[180:183], v154 offset:20480
	ds_read_b128 v[204:207], v154 offset:21504
	ds_read_b128 v[208:211], v154 offset:22528
	ds_read_b128 v[212:215], v154 offset:23552
	global_load_lds_dwordx4 v130, s[4:5]
	s_mov_b32 m0, s29
	s_nop 0
	global_load_lds_dwordx4 v134, s[4:5]
	s_barrier
	s_waitcnt lgkmcnt(0)
	v_mfma_f32_16x16x32_bf16 v[62:65], v[142:145], v[164:167], v[62:65]
	v_mfma_f32_16x16x32_bf16 v[62:65], v[146:149], v[168:171], v[62:65]
	v_mfma_f32_16x16x32_bf16 v[46:49], v[142:145], v[172:175], v[46:49]
	v_mfma_f32_16x16x32_bf16 v[46:49], v[146:149], v[176:179], v[46:49]
	v_mfma_f32_16x16x32_bf16 v[30:33], v[142:145], v[180:183], v[30:33]
	v_mfma_f32_16x16x32_bf16 v[30:33], v[146:149], v[204:207], v[30:33]
	v_mfma_f32_16x16x32_bf16 v[14:17], v[142:145], v[208:211], v[14:17]
	v_mfma_f32_16x16x32_bf16 v[14:17], v[146:149], v[212:215], v[14:17]
	v_mfma_f32_16x16x32_bf16 v[10:13], v[156:159], v[208:211], v[10:13]
	v_mfma_f32_16x16x32_bf16 v[10:13], v[160:163], v[212:215], v[10:13]
	v_mfma_f32_16x16x32_bf16 v[26:29], v[156:159], v[180:183], v[26:29]
	v_mfma_f32_16x16x32_bf16 v[26:29], v[160:163], v[204:207], v[26:29]
	v_mfma_f32_16x16x32_bf16 v[42:45], v[156:159], v[172:175], v[42:45]
	v_mfma_f32_16x16x32_bf16 v[42:45], v[160:163], v[176:179], v[42:45]
	v_mfma_f32_16x16x32_bf16 v[58:61], v[156:159], v[164:167], v[58:61]
	v_mfma_f32_16x16x32_bf16 v[58:61], v[160:163], v[168:171], v[58:61]
	s_barrier
	s_add_u32 s18, s18, s14
	s_addc_u32 s19, s19, 0
	s_add_i32 s68, s69, s25
	s_add_u32 s76, s18, s6
	s_addc_u32 s77, s19, s7
	s_mov_b32 m0, s68
	s_nop 0
	global_load_lds_dwordx4 v132, s[18:19]
	s_add_i32 m0, s68, 0x2000
	s_nop 0
	global_load_lds_dwordx4 v136, s[18:19]
	s_waitcnt vmcnt(6)
	s_barrier
	v_mfma_f32_16x16x32_bf16 v[54:57], v[216:219], v[164:167], v[54:57]
	v_mfma_f32_16x16x32_bf16 v[54:57], v[220:223], v[168:171], v[54:57]
	v_mfma_f32_16x16x32_bf16 v[38:41], v[216:219], v[172:175], v[38:41]
	v_mfma_f32_16x16x32_bf16 v[38:41], v[220:223], v[176:179], v[38:41]
	v_mfma_f32_16x16x32_bf16 v[22:25], v[216:219], v[180:183], v[22:25]
	v_mfma_f32_16x16x32_bf16 v[22:25], v[220:223], v[204:207], v[22:25]
	v_mfma_f32_16x16x32_bf16 v[6:9], v[216:219], v[208:211], v[6:9]
	v_mfma_f32_16x16x32_bf16 v[6:9], v[220:223], v[212:215], v[6:9]
	v_mfma_f32_16x16x32_bf16 v[2:5], v[224:227], v[208:211], v[2:5]
	v_mfma_f32_16x16x32_bf16 v[2:5], v[228:231], v[212:215], v[2:5]
	v_mfma_f32_16x16x32_bf16 v[18:21], v[224:227], v[180:183], v[18:21]
	v_mfma_f32_16x16x32_bf16 v[18:21], v[228:231], v[204:207], v[18:21]
	v_mfma_f32_16x16x32_bf16 v[34:37], v[224:227], v[172:175], v[34:37]
	v_mfma_f32_16x16x32_bf16 v[34:37], v[228:231], v[176:179], v[34:37]
	v_mfma_f32_16x16x32_bf16 v[50:53], v[224:227], v[164:167], v[50:53]
	v_mfma_f32_16x16x32_bf16 v[50:53], v[228:231], v[168:171], v[50:53]
	s_barrier
	s_add_i32 s18, 0, 0x18000
	ds_read_b128 v[142:145], v248 offset:32768
	ds_read_b128 v[146:149], v248 offset:33792
	ds_read_b128 v[156:159], v248 offset:34816
	ds_read_b128 v[160:163], v248 offset:35840
	s_add_u32 s4, s4, s14
	s_addc_u32 s5, s5, 0
	s_mov_b32 m0, s31
	ds_read_b128 v[164:167], v154 offset:32768
	ds_read_b128 v[168:171], v154 offset:33792
	ds_read_b128 v[172:175], v154 offset:34816
	ds_read_b128 v[176:179], v154 offset:35840
	ds_read_b128 v[180:183], v154 offset:36864
	ds_read_b128 v[204:207], v154 offset:37888
	ds_read_b128 v[208:211], v154 offset:38912
	ds_read_b128 v[212:215], v154 offset:39936
	global_load_lds_dwordx4 v130, s[4:5]
	s_mov_b32 m0, s34
	s_nop 0
	global_load_lds_dwordx4 v134, s[4:5]
	s_waitcnt lgkmcnt(8)
	s_barrier
	s_waitcnt lgkmcnt(0)
	v_mfma_f32_16x16x32_bf16 v[126:129], v[142:145], v[164:167], v[126:129]
	v_mfma_f32_16x16x32_bf16 v[126:129], v[146:149], v[168:171], v[126:129]
	v_mfma_f32_16x16x32_bf16 v[110:113], v[142:145], v[172:175], v[110:113]
	v_mfma_f32_16x16x32_bf16 v[110:113], v[146:149], v[176:179], v[110:113]
	v_mfma_f32_16x16x32_bf16 v[94:97], v[142:145], v[180:183], v[94:97]
	v_mfma_f32_16x16x32_bf16 v[94:97], v[146:149], v[204:207], v[94:97]
	v_mfma_f32_16x16x32_bf16 v[78:81], v[142:145], v[208:211], v[78:81]
	v_mfma_f32_16x16x32_bf16 v[78:81], v[146:149], v[212:215], v[78:81]
	v_mfma_f32_16x16x32_bf16 v[74:77], v[156:159], v[208:211], v[74:77]
	v_mfma_f32_16x16x32_bf16 v[74:77], v[160:163], v[212:215], v[74:77]
	v_mfma_f32_16x16x32_bf16 v[90:93], v[156:159], v[180:183], v[90:93]
	v_mfma_f32_16x16x32_bf16 v[90:93], v[160:163], v[204:207], v[90:93]
	v_mfma_f32_16x16x32_bf16 v[106:109], v[156:159], v[172:175], v[106:109]
	v_mfma_f32_16x16x32_bf16 v[106:109], v[160:163], v[176:179], v[106:109]
	v_mfma_f32_16x16x32_bf16 v[122:125], v[156:159], v[164:167], v[122:125]
	v_mfma_f32_16x16x32_bf16 v[122:125], v[160:163], v[168:171], v[122:125]
	s_barrier
	s_add_i32 s4, 0, 0x1c000
	s_add_i32 s5, s18, s25
	s_mov_b32 m0, s5
	ds_read_b128 v[216:219], v248 offset:49152
	ds_read_b128 v[220:223], v248 offset:50176
	ds_read_b128 v[224:227], v248 offset:51200
	ds_read_b128 v[228:231], v248 offset:52224
	global_load_lds_dwordx4 v132, s[70:71]
	s_add_i32 m0, s5, 0x2000
	s_nop 0
	global_load_lds_dwordx4 v136, s[70:71]
	s_barrier
	s_waitcnt lgkmcnt(0)
	v_mfma_f32_16x16x32_bf16 v[118:121], v[216:219], v[164:167], v[118:121]
	v_mfma_f32_16x16x32_bf16 v[118:121], v[220:223], v[168:171], v[118:121]
	v_mfma_f32_16x16x32_bf16 v[102:105], v[216:219], v[172:175], v[102:105]
	v_mfma_f32_16x16x32_bf16 v[102:105], v[220:223], v[176:179], v[102:105]
	v_mfma_f32_16x16x32_bf16 v[86:89], v[216:219], v[180:183], v[86:89]
	v_mfma_f32_16x16x32_bf16 v[86:89], v[220:223], v[204:207], v[86:89]
	v_mfma_f32_16x16x32_bf16 v[70:73], v[216:219], v[208:211], v[70:73]
	v_mfma_f32_16x16x32_bf16 v[70:73], v[220:223], v[212:215], v[70:73]
	v_mfma_f32_16x16x32_bf16 v[66:69], v[224:227], v[208:211], v[66:69]
	v_mfma_f32_16x16x32_bf16 v[66:69], v[228:231], v[212:215], v[66:69]
	v_mfma_f32_16x16x32_bf16 v[82:85], v[224:227], v[180:183], v[82:85]
	v_mfma_f32_16x16x32_bf16 v[82:85], v[228:231], v[204:207], v[82:85]
	v_mfma_f32_16x16x32_bf16 v[98:101], v[224:227], v[172:175], v[98:101]
	v_mfma_f32_16x16x32_bf16 v[98:101], v[228:231], v[176:179], v[98:101]
	v_mfma_f32_16x16x32_bf16 v[114:117], v[224:227], v[164:167], v[114:117]
	v_mfma_f32_16x16x32_bf16 v[114:117], v[228:231], v[168:171], v[114:117]
	s_barrier
	s_mov_b32 m0, s41
	ds_read_b128 v[164:167], v154 offset:49152
	ds_read_b128 v[168:171], v154 offset:50176
	ds_read_b128 v[172:175], v154 offset:51200
	ds_read_b128 v[176:179], v154 offset:52224
	ds_read_b128 v[180:183], v154 offset:53248
	ds_read_b128 v[204:207], v154 offset:54272
	ds_read_b128 v[208:211], v154 offset:55296
	ds_read_b128 v[212:215], v154 offset:56320
	global_load_lds_dwordx4 v130, s[72:73]
	s_mov_b32 m0, s42
	s_nop 0
	global_load_lds_dwordx4 v134, s[72:73]
	s_barrier
	s_waitcnt lgkmcnt(0)
	v_mfma_f32_16x16x32_bf16 v[62:65], v[142:145], v[164:167], v[62:65]
	v_mfma_f32_16x16x32_bf16 v[62:65], v[146:149], v[168:171], v[62:65]
	v_mfma_f32_16x16x32_bf16 v[46:49], v[142:145], v[172:175], v[46:49]
	v_mfma_f32_16x16x32_bf16 v[46:49], v[146:149], v[176:179], v[46:49]
	v_mfma_f32_16x16x32_bf16 v[30:33], v[142:145], v[180:183], v[30:33]
	v_mfma_f32_16x16x32_bf16 v[30:33], v[146:149], v[204:207], v[30:33]
	v_mfma_f32_16x16x32_bf16 v[14:17], v[142:145], v[208:211], v[14:17]
	v_mfma_f32_16x16x32_bf16 v[14:17], v[146:149], v[212:215], v[14:17]
	v_mfma_f32_16x16x32_bf16 v[10:13], v[156:159], v[208:211], v[10:13]
	v_mfma_f32_16x16x32_bf16 v[10:13], v[160:163], v[212:215], v[10:13]
	v_mfma_f32_16x16x32_bf16 v[26:29], v[156:159], v[180:183], v[26:29]
	v_mfma_f32_16x16x32_bf16 v[26:29], v[160:163], v[204:207], v[26:29]
	v_mfma_f32_16x16x32_bf16 v[42:45], v[156:159], v[172:175], v[42:45]
	v_mfma_f32_16x16x32_bf16 v[42:45], v[160:163], v[176:179], v[42:45]
	v_mfma_f32_16x16x32_bf16 v[58:61], v[156:159], v[164:167], v[58:61]
	v_mfma_f32_16x16x32_bf16 v[58:61], v[160:163], v[168:171], v[58:61]
	s_barrier
	s_add_i32 s4, s4, s25
	s_mov_b32 m0, s4
	s_nop 0
	global_load_lds_dwordx4 v132, s[76:77]
	s_add_i32 m0, s4, 0x2000
	s_nop 0
	global_load_lds_dwordx4 v136, s[76:77]
	s_add_u32 s0, s0, 0x100
	s_addc_u32 s1, s1, 0
	s_add_u32 s49, s49, 0x100
	s_addc_u32 s65, s65, 0
	s_cmp_ge_u32 s66, s35
	s_mov_b32 s4, s66
	s_waitcnt vmcnt(6)
	s_barrier
	v_mfma_f32_16x16x32_bf16 v[54:57], v[216:219], v[164:167], v[54:57]
	v_mfma_f32_16x16x32_bf16 v[54:57], v[220:223], v[168:171], v[54:57]
	v_mfma_f32_16x16x32_bf16 v[38:41], v[216:219], v[172:175], v[38:41]
	v_mfma_f32_16x16x32_bf16 v[38:41], v[220:223], v[176:179], v[38:41]
	v_mfma_f32_16x16x32_bf16 v[22:25], v[216:219], v[180:183], v[22:25]
	v_mfma_f32_16x16x32_bf16 v[22:25], v[220:223], v[204:207], v[22:25]
	v_mfma_f32_16x16x32_bf16 v[6:9], v[216:219], v[208:211], v[6:9]
	v_mfma_f32_16x16x32_bf16 v[6:9], v[220:223], v[212:215], v[6:9]
	v_mfma_f32_16x16x32_bf16 v[2:5], v[224:227], v[208:211], v[2:5]
	v_mfma_f32_16x16x32_bf16 v[2:5], v[228:231], v[212:215], v[2:5]
	v_mfma_f32_16x16x32_bf16 v[18:21], v[224:227], v[180:183], v[18:21]
	v_mfma_f32_16x16x32_bf16 v[18:21], v[228:231], v[204:207], v[18:21]
	v_mfma_f32_16x16x32_bf16 v[34:37], v[224:227], v[172:175], v[34:37]
	v_mfma_f32_16x16x32_bf16 v[34:37], v[228:231], v[176:179], v[34:37]
	v_mfma_f32_16x16x32_bf16 v[50:53], v[224:227], v[164:167], v[50:53]
	v_mfma_f32_16x16x32_bf16 v[50:53], v[228:231], v[168:171], v[50:53]
	s_barrier
	s_cbranch_scc0 .LBB0_664

.LBB0_697:
	s_add_u32 s0, s0, 0x80
	s_addc_u32 s1, s1, 0
	s_add_u32 s48, s4, 0x100
	s_addc_u32 s49, s5, 0
	s_mov_b32 s4, 0
	s_waitcnt lgkmcnt(0)
	s_waitcnt vmcnt(0)
	s_add_i32 s65, s4, 2
	s_add_u32 s18, s0, 0x80
	s_addc_u32 s5, s1, 0
	s_add_i32 s66, 0, 0x10000
	ds_read_b128 v[142:145], v248
	ds_read_b128 v[152:155], v248 offset:1024
	ds_read_b128 v[156:159], v248 offset:2048
	ds_read_b128 v[160:163], v248 offset:3072
	s_cmp_eq_u32 s34, s4
	s_cselect_b32 s4, s10, s18
	s_cselect_b32 s5, s11, s5
	s_cselect_b32 s19, s13, s49
	s_cselect_b32 s18, s12, s48
	s_add_i32 m0, s22, 0xc000
	ds_read_b128 v[164:167], v150
	ds_read_b128 v[168:171], v150 offset:1024
	ds_read_b128 v[172:175], v150 offset:2048
	ds_read_b128 v[176:179], v150 offset:3072
	ds_read_b128 v[180:183], v150 offset:4096
	ds_read_b128 v[204:207], v150 offset:5120
	ds_read_b128 v[208:211], v150 offset:6144
	ds_read_b128 v[212:215], v150 offset:7168
	global_load_lds_dwordx4 v138, s[0:1]
	s_add_i32 m0, s22, 0xe000
	s_nop 0
	global_load_lds_dwordx4 v140, s[0:1]
	s_waitcnt lgkmcnt(8)
	s_barrier
	s_waitcnt lgkmcnt(0)
	v_mfma_f32_16x16x32_bf16 v[126:129], v[142:145], v[164:167], 0
	v_mfma_f32_16x16x32_bf16 v[126:129], v[152:155], v[168:171], v[126:129]
	v_mfma_f32_16x16x32_bf16 v[110:113], v[142:145], v[172:175], 0
	v_mfma_f32_16x16x32_bf16 v[110:113], v[152:155], v[176:179], v[110:113]
	v_mfma_f32_16x16x32_bf16 v[94:97], v[142:145], v[180:183], 0
	v_mfma_f32_16x16x32_bf16 v[94:97], v[152:155], v[204:207], v[94:97]
	v_mfma_f32_16x16x32_bf16 v[78:81], v[142:145], v[208:211], 0
	v_mfma_f32_16x16x32_bf16 v[78:81], v[152:155], v[212:215], v[78:81]
	v_mfma_f32_16x16x32_bf16 v[74:77], v[156:159], v[208:211], 0
	v_mfma_f32_16x16x32_bf16 v[74:77], v[160:163], v[212:215], v[74:77]
	v_mfma_f32_16x16x32_bf16 v[90:93], v[156:159], v[180:183], 0
	v_mfma_f32_16x16x32_bf16 v[90:93], v[160:163], v[204:207], v[90:93]
	v_mfma_f32_16x16x32_bf16 v[106:109], v[156:159], v[172:175], 0
	v_mfma_f32_16x16x32_bf16 v[106:109], v[160:163], v[176:179], v[106:109]
	v_mfma_f32_16x16x32_bf16 v[122:125], v[156:159], v[164:167], 0
	v_mfma_f32_16x16x32_bf16 v[122:125], v[160:163], v[168:171], v[122:125]
	s_barrier
	s_add_i32 s67, 0, 0x14000
	s_add_i32 s66, s66, s21
	ds_read_b128 v[216:219], v248 offset:16384
	ds_read_b128 v[220:223], v248 offset:17408
	ds_read_b128 v[224:227], v248 offset:18432
	ds_read_b128 v[228:231], v248 offset:19456
	s_add_u32 s70, s18, s6
	s_addc_u32 s71, s19, s7
	s_mov_b32 m0, s66
	s_nop 0
	global_load_lds_dwordx4 v132, s[18:19]
	s_add_i32 m0, s66, 0x2000
	s_nop 0
	global_load_lds_dwordx4 v136, s[18:19]
	s_barrier
	s_waitcnt lgkmcnt(0)
	v_mfma_f32_16x16x32_bf16 v[118:121], v[216:219], v[164:167], 0
	v_mfma_f32_16x16x32_bf16 v[118:121], v[220:223], v[168:171], v[118:121]
	v_mfma_f32_16x16x32_bf16 v[102:105], v[216:219], v[172:175], 0
	v_mfma_f32_16x16x32_bf16 v[102:105], v[220:223], v[176:179], v[102:105]
	v_mfma_f32_16x16x32_bf16 v[86:89], v[216:219], v[180:183], 0
	v_mfma_f32_16x16x32_bf16 v[86:89], v[220:223], v[204:207], v[86:89]
	v_mfma_f32_16x16x32_bf16 v[70:73], v[216:219], v[208:211], 0
	v_mfma_f32_16x16x32_bf16 v[70:73], v[220:223], v[212:215], v[70:73]
	v_mfma_f32_16x16x32_bf16 v[66:69], v[224:227], v[208:211], 0
	v_mfma_f32_16x16x32_bf16 v[66:69], v[228:231], v[212:215], v[66:69]
	v_mfma_f32_16x16x32_bf16 v[82:85], v[224:227], v[180:183], 0
	v_mfma_f32_16x16x32_bf16 v[82:85], v[228:231], v[204:207], v[82:85]
	v_mfma_f32_16x16x32_bf16 v[98:101], v[224:227], v[172:175], 0
	v_mfma_f32_16x16x32_bf16 v[98:101], v[228:231], v[176:179], v[98:101]
	v_mfma_f32_16x16x32_bf16 v[114:117], v[224:227], v[164:167], 0
	v_mfma_f32_16x16x32_bf16 v[114:117], v[228:231], v[168:171], v[114:117]
	s_barrier
	s_mov_b32 m0, s22
	s_add_u32 s72, s4, s6
	s_addc_u32 s73, s5, s7
	ds_read_b128 v[164:167], v150 offset:16384
	ds_read_b128 v[168:171], v150 offset:17408
	ds_read_b128 v[172:175], v150 offset:18432
	ds_read_b128 v[176:179], v150 offset:19456
	ds_read_b128 v[180:183], v150 offset:20480
	ds_read_b128 v[204:207], v150 offset:21504
	ds_read_b128 v[208:211], v150 offset:22528
	ds_read_b128 v[212:215], v150 offset:23552
	global_load_lds_dwordx4 v130, s[4:5]
	s_mov_b32 m0, s23
	s_nop 0
	global_load_lds_dwordx4 v134, s[4:5]
	s_barrier
	s_waitcnt lgkmcnt(0)
	v_mfma_f32_16x16x32_bf16 v[62:65], v[142:145], v[164:167], 0
	v_mfma_f32_16x16x32_bf16 v[62:65], v[152:155], v[168:171], v[62:65]
	v_mfma_f32_16x16x32_bf16 v[46:49], v[142:145], v[172:175], 0
	v_mfma_f32_16x16x32_bf16 v[46:49], v[152:155], v[176:179], v[46:49]
	v_mfma_f32_16x16x32_bf16 v[30:33], v[142:145], v[180:183], 0
	v_mfma_f32_16x16x32_bf16 v[30:33], v[152:155], v[204:207], v[30:33]
	v_mfma_f32_16x16x32_bf16 v[14:17], v[142:145], v[208:211], 0
	v_mfma_f32_16x16x32_bf16 v[14:17], v[152:155], v[212:215], v[14:17]
	v_mfma_f32_16x16x32_bf16 v[10:13], v[156:159], v[208:211], 0
	v_mfma_f32_16x16x32_bf16 v[10:13], v[160:163], v[212:215], v[10:13]
	v_mfma_f32_16x16x32_bf16 v[26:29], v[156:159], v[180:183], 0
	v_mfma_f32_16x16x32_bf16 v[26:29], v[160:163], v[204:207], v[26:29]
	v_mfma_f32_16x16x32_bf16 v[42:45], v[156:159], v[172:175], 0
	v_mfma_f32_16x16x32_bf16 v[42:45], v[160:163], v[176:179], v[42:45]
	v_mfma_f32_16x16x32_bf16 v[58:61], v[156:159], v[164:167], 0
	v_mfma_f32_16x16x32_bf16 v[58:61], v[160:163], v[168:171], v[58:61]
	s_barrier
	s_add_u32 s18, s18, s2
	s_addc_u32 s19, s19, 0
	s_add_i32 s66, s67, s21
	s_add_u32 s76, s18, s6
	s_addc_u32 s77, s19, s7
	s_mov_b32 m0, s66
	s_nop 0
	global_load_lds_dwordx4 v132, s[18:19]
	s_add_i32 m0, s66, 0x2000
	s_nop 0
	global_load_lds_dwordx4 v136, s[18:19]
	s_waitcnt vmcnt(6)
	s_barrier
	v_mfma_f32_16x16x32_bf16 v[54:57], v[216:219], v[164:167], 0
	v_mfma_f32_16x16x32_bf16 v[54:57], v[220:223], v[168:171], v[54:57]
	v_mfma_f32_16x16x32_bf16 v[38:41], v[216:219], v[172:175], 0
	v_mfma_f32_16x16x32_bf16 v[38:41], v[220:223], v[176:179], v[38:41]
	v_mfma_f32_16x16x32_bf16 v[22:25], v[216:219], v[180:183], 0
	v_mfma_f32_16x16x32_bf16 v[22:25], v[220:223], v[204:207], v[22:25]
	v_mfma_f32_16x16x32_bf16 v[6:9], v[216:219], v[208:211], 0
	v_mfma_f32_16x16x32_bf16 v[6:9], v[220:223], v[212:215], v[6:9]
	v_mfma_f32_16x16x32_bf16 v[2:5], v[224:227], v[208:211], 0
	v_mfma_f32_16x16x32_bf16 v[2:5], v[228:231], v[212:215], v[2:5]
	v_mfma_f32_16x16x32_bf16 v[18:21], v[224:227], v[180:183], 0
	v_mfma_f32_16x16x32_bf16 v[18:21], v[228:231], v[204:207], v[18:21]
	v_mfma_f32_16x16x32_bf16 v[34:37], v[224:227], v[172:175], 0
	v_mfma_f32_16x16x32_bf16 v[34:37], v[228:231], v[176:179], v[34:37]
	v_mfma_f32_16x16x32_bf16 v[50:53], v[224:227], v[164:167], 0
	v_mfma_f32_16x16x32_bf16 v[50:53], v[228:231], v[168:171], v[50:53]
	s_barrier
	s_add_i32 s18, 0, 0x18000
	ds_read_b128 v[142:145], v248 offset:32768
	ds_read_b128 v[152:155], v248 offset:33792
	ds_read_b128 v[156:159], v248 offset:34816
	ds_read_b128 v[160:163], v248 offset:35840
	s_add_u32 s4, s4, s2
	s_addc_u32 s5, s5, 0
	s_mov_b32 m0, s24
	ds_read_b128 v[164:167], v150 offset:32768
	ds_read_b128 v[168:171], v150 offset:33792
	ds_read_b128 v[172:175], v150 offset:34816
	ds_read_b128 v[176:179], v150 offset:35840
	ds_read_b128 v[180:183], v150 offset:36864
	ds_read_b128 v[204:207], v150 offset:37888
	ds_read_b128 v[208:211], v150 offset:38912
	ds_read_b128 v[212:215], v150 offset:39936
	global_load_lds_dwordx4 v130, s[4:5]
	s_mov_b32 m0, s25
	s_nop 0
	global_load_lds_dwordx4 v134, s[4:5]
	s_waitcnt lgkmcnt(8)
	s_barrier
	s_waitcnt lgkmcnt(0)
	v_mfma_f32_16x16x32_bf16 v[126:129], v[142:145], v[164:167], v[126:129]
	v_mfma_f32_16x16x32_bf16 v[126:129], v[152:155], v[168:171], v[126:129]
	v_mfma_f32_16x16x32_bf16 v[110:113], v[142:145], v[172:175], v[110:113]
	v_mfma_f32_16x16x32_bf16 v[110:113], v[152:155], v[176:179], v[110:113]
	v_mfma_f32_16x16x32_bf16 v[94:97], v[142:145], v[180:183], v[94:97]
	v_mfma_f32_16x16x32_bf16 v[94:97], v[152:155], v[204:207], v[94:97]
	v_mfma_f32_16x16x32_bf16 v[78:81], v[142:145], v[208:211], v[78:81]
	v_mfma_f32_16x16x32_bf16 v[78:81], v[152:155], v[212:215], v[78:81]
	v_mfma_f32_16x16x32_bf16 v[74:77], v[156:159], v[208:211], v[74:77]
	v_mfma_f32_16x16x32_bf16 v[74:77], v[160:163], v[212:215], v[74:77]
	v_mfma_f32_16x16x32_bf16 v[90:93], v[156:159], v[180:183], v[90:93]
	v_mfma_f32_16x16x32_bf16 v[90:93], v[160:163], v[204:207], v[90:93]
	v_mfma_f32_16x16x32_bf16 v[106:109], v[156:159], v[172:175], v[106:109]
	v_mfma_f32_16x16x32_bf16 v[106:109], v[160:163], v[176:179], v[106:109]
	v_mfma_f32_16x16x32_bf16 v[122:125], v[156:159], v[164:167], v[122:125]
	v_mfma_f32_16x16x32_bf16 v[122:125], v[160:163], v[168:171], v[122:125]
	s_barrier
	s_add_i32 s4, 0, 0x1c000
	s_add_i32 s5, s18, s21
	s_mov_b32 m0, s5
	ds_read_b128 v[216:219], v248 offset:49152
	ds_read_b128 v[220:223], v248 offset:50176
	ds_read_b128 v[224:227], v248 offset:51200
	ds_read_b128 v[228:231], v248 offset:52224
	global_load_lds_dwordx4 v132, s[70:71]
	s_add_i32 m0, s5, 0x2000
	s_nop 0
	global_load_lds_dwordx4 v136, s[70:71]
	s_barrier
	s_waitcnt lgkmcnt(0)
	v_mfma_f32_16x16x32_bf16 v[118:121], v[216:219], v[164:167], v[118:121]
	v_mfma_f32_16x16x32_bf16 v[118:121], v[220:223], v[168:171], v[118:121]
	v_mfma_f32_16x16x32_bf16 v[102:105], v[216:219], v[172:175], v[102:105]
	v_mfma_f32_16x16x32_bf16 v[102:105], v[220:223], v[176:179], v[102:105]
	v_mfma_f32_16x16x32_bf16 v[86:89], v[216:219], v[180:183], v[86:89]
	v_mfma_f32_16x16x32_bf16 v[86:89], v[220:223], v[204:207], v[86:89]
	v_mfma_f32_16x16x32_bf16 v[70:73], v[216:219], v[208:211], v[70:73]
	v_mfma_f32_16x16x32_bf16 v[70:73], v[220:223], v[212:215], v[70:73]
	v_mfma_f32_16x16x32_bf16 v[66:69], v[224:227], v[208:211], v[66:69]
	v_mfma_f32_16x16x32_bf16 v[66:69], v[228:231], v[212:215], v[66:69]
	v_mfma_f32_16x16x32_bf16 v[82:85], v[224:227], v[180:183], v[82:85]
	v_mfma_f32_16x16x32_bf16 v[82:85], v[228:231], v[204:207], v[82:85]
	v_mfma_f32_16x16x32_bf16 v[98:101], v[224:227], v[172:175], v[98:101]
	v_mfma_f32_16x16x32_bf16 v[98:101], v[228:231], v[176:179], v[98:101]
	v_mfma_f32_16x16x32_bf16 v[114:117], v[224:227], v[164:167], v[114:117]
	v_mfma_f32_16x16x32_bf16 v[114:117], v[228:231], v[168:171], v[114:117]
	s_barrier
	s_mov_b32 m0, s30
	ds_read_b128 v[164:167], v150 offset:49152
	ds_read_b128 v[168:171], v150 offset:50176
	ds_read_b128 v[172:175], v150 offset:51200
	ds_read_b128 v[176:179], v150 offset:52224
	ds_read_b128 v[180:183], v150 offset:53248
	ds_read_b128 v[204:207], v150 offset:54272
	ds_read_b128 v[208:211], v150 offset:55296
	ds_read_b128 v[212:215], v150 offset:56320
	global_load_lds_dwordx4 v130, s[72:73]
	s_mov_b32 m0, s31
	s_nop 0
	global_load_lds_dwordx4 v134, s[72:73]
	s_barrier
	s_waitcnt lgkmcnt(0)
	v_mfma_f32_16x16x32_bf16 v[62:65], v[142:145], v[164:167], v[62:65]
	v_mfma_f32_16x16x32_bf16 v[62:65], v[152:155], v[168:171], v[62:65]
	v_mfma_f32_16x16x32_bf16 v[46:49], v[142:145], v[172:175], v[46:49]
	v_mfma_f32_16x16x32_bf16 v[46:49], v[152:155], v[176:179], v[46:49]
	v_mfma_f32_16x16x32_bf16 v[30:33], v[142:145], v[180:183], v[30:33]
	v_mfma_f32_16x16x32_bf16 v[30:33], v[152:155], v[204:207], v[30:33]
	v_mfma_f32_16x16x32_bf16 v[14:17], v[142:145], v[208:211], v[14:17]
	v_mfma_f32_16x16x32_bf16 v[14:17], v[152:155], v[212:215], v[14:17]
	v_mfma_f32_16x16x32_bf16 v[10:13], v[156:159], v[208:211], v[10:13]
	v_mfma_f32_16x16x32_bf16 v[10:13], v[160:163], v[212:215], v[10:13]
	v_mfma_f32_16x16x32_bf16 v[26:29], v[156:159], v[180:183], v[26:29]
	v_mfma_f32_16x16x32_bf16 v[26:29], v[160:163], v[204:207], v[26:29]
	v_mfma_f32_16x16x32_bf16 v[42:45], v[156:159], v[172:175], v[42:45]
	v_mfma_f32_16x16x32_bf16 v[42:45], v[160:163], v[176:179], v[42:45]
	v_mfma_f32_16x16x32_bf16 v[58:61], v[156:159], v[164:167], v[58:61]
	v_mfma_f32_16x16x32_bf16 v[58:61], v[160:163], v[168:171], v[58:61]
	s_barrier
	s_add_i32 s4, s4, s21
	s_mov_b32 m0, s4
	s_nop 0
	global_load_lds_dwordx4 v132, s[76:77]
	s_add_i32 m0, s4, 0x2000
	s_nop 0
	global_load_lds_dwordx4 v136, s[76:77]
	s_add_u32 s0, s0, 0x100
	s_addc_u32 s1, s1, 0
	s_add_u32 s48, s48, 0x100
	s_addc_u32 s49, s49, 0
	s_cmp_ge_u32 s65, s27
	s_mov_b32 s4, s65
	s_waitcnt vmcnt(6)
	s_barrier
	v_mfma_f32_16x16x32_bf16 v[54:57], v[216:219], v[164:167], v[54:57]
	v_mfma_f32_16x16x32_bf16 v[54:57], v[220:223], v[168:171], v[54:57]
	v_mfma_f32_16x16x32_bf16 v[38:41], v[216:219], v[172:175], v[38:41]
	v_mfma_f32_16x16x32_bf16 v[38:41], v[220:223], v[176:179], v[38:41]
	v_mfma_f32_16x16x32_bf16 v[22:25], v[216:219], v[180:183], v[22:25]
	v_mfma_f32_16x16x32_bf16 v[22:25], v[220:223], v[204:207], v[22:25]
	v_mfma_f32_16x16x32_bf16 v[6:9], v[216:219], v[208:211], v[6:9]
	v_mfma_f32_16x16x32_bf16 v[6:9], v[220:223], v[212:215], v[6:9]
	v_mfma_f32_16x16x32_bf16 v[2:5], v[224:227], v[208:211], v[2:5]
	v_mfma_f32_16x16x32_bf16 v[2:5], v[228:231], v[212:215], v[2:5]
	v_mfma_f32_16x16x32_bf16 v[18:21], v[224:227], v[180:183], v[18:21]
	v_mfma_f32_16x16x32_bf16 v[18:21], v[228:231], v[204:207], v[18:21]
	v_mfma_f32_16x16x32_bf16 v[34:37], v[224:227], v[172:175], v[34:37]
	v_mfma_f32_16x16x32_bf16 v[34:37], v[228:231], v[176:179], v[34:37]
	v_mfma_f32_16x16x32_bf16 v[50:53], v[224:227], v[164:167], v[50:53]
	v_mfma_f32_16x16x32_bf16 v[50:53], v[228:231], v[168:171], v[50:53]
	s_barrier
	s_cbranch_scc1 .Lkexit_698
.LBB0_698:
	s_add_i32 s65, s4, 2
	s_add_u32 s18, s0, 0x80
	s_addc_u32 s5, s1, 0
	s_add_i32 s66, 0, 0x10000
	ds_read_b128 v[142:145], v248
	ds_read_b128 v[152:155], v248 offset:1024
	ds_read_b128 v[156:159], v248 offset:2048
	ds_read_b128 v[160:163], v248 offset:3072
	s_cmp_eq_u32 s34, s4
	s_cselect_b32 s4, s10, s18
	s_cselect_b32 s5, s11, s5
	s_cselect_b32 s19, s13, s49
	s_cselect_b32 s18, s12, s48
	s_add_i32 m0, s22, 0xc000
	ds_read_b128 v[164:167], v150
	ds_read_b128 v[168:171], v150 offset:1024
	ds_read_b128 v[172:175], v150 offset:2048
	ds_read_b128 v[176:179], v150 offset:3072
	ds_read_b128 v[180:183], v150 offset:4096
	ds_read_b128 v[204:207], v150 offset:5120
	ds_read_b128 v[208:211], v150 offset:6144
	ds_read_b128 v[212:215], v150 offset:7168
	global_load_lds_dwordx4 v138, s[0:1]
	s_add_i32 m0, s22, 0xe000
	s_nop 0
	global_load_lds_dwordx4 v140, s[0:1]
	s_waitcnt lgkmcnt(8)
	s_barrier
	s_waitcnt lgkmcnt(0)
	v_mfma_f32_16x16x32_bf16 v[126:129], v[142:145], v[164:167], v[126:129]
	v_mfma_f32_16x16x32_bf16 v[126:129], v[152:155], v[168:171], v[126:129]
	v_mfma_f32_16x16x32_bf16 v[110:113], v[142:145], v[172:175], v[110:113]
	v_mfma_f32_16x16x32_bf16 v[110:113], v[152:155], v[176:179], v[110:113]
	v_mfma_f32_16x16x32_bf16 v[94:97], v[142:145], v[180:183], v[94:97]
	v_mfma_f32_16x16x32_bf16 v[94:97], v[152:155], v[204:207], v[94:97]
	v_mfma_f32_16x16x32_bf16 v[78:81], v[142:145], v[208:211], v[78:81]
	v_mfma_f32_16x16x32_bf16 v[78:81], v[152:155], v[212:215], v[78:81]
	v_mfma_f32_16x16x32_bf16 v[74:77], v[156:159], v[208:211], v[74:77]
	v_mfma_f32_16x16x32_bf16 v[74:77], v[160:163], v[212:215], v[74:77]
	v_mfma_f32_16x16x32_bf16 v[90:93], v[156:159], v[180:183], v[90:93]
	v_mfma_f32_16x16x32_bf16 v[90:93], v[160:163], v[204:207], v[90:93]
	v_mfma_f32_16x16x32_bf16 v[106:109], v[156:159], v[172:175], v[106:109]
	v_mfma_f32_16x16x32_bf16 v[106:109], v[160:163], v[176:179], v[106:109]
	v_mfma_f32_16x16x32_bf16 v[122:125], v[156:159], v[164:167], v[122:125]
	v_mfma_f32_16x16x32_bf16 v[122:125], v[160:163], v[168:171], v[122:125]
	s_barrier
	s_add_i32 s67, 0, 0x14000
	s_add_i32 s66, s66, s21
	ds_read_b128 v[216:219], v248 offset:16384
	ds_read_b128 v[220:223], v248 offset:17408
	ds_read_b128 v[224:227], v248 offset:18432
	ds_read_b128 v[228:231], v248 offset:19456
	s_add_u32 s70, s18, s6
	s_addc_u32 s71, s19, s7
	s_mov_b32 m0, s66
	s_nop 0
	global_load_lds_dwordx4 v132, s[18:19]
	s_add_i32 m0, s66, 0x2000
	s_nop 0
	global_load_lds_dwordx4 v136, s[18:19]
	s_barrier
	s_waitcnt lgkmcnt(0)
	v_mfma_f32_16x16x32_bf16 v[118:121], v[216:219], v[164:167], v[118:121]
	v_mfma_f32_16x16x32_bf16 v[118:121], v[220:223], v[168:171], v[118:121]
	v_mfma_f32_16x16x32_bf16 v[102:105], v[216:219], v[172:175], v[102:105]
	v_mfma_f32_16x16x32_bf16 v[102:105], v[220:223], v[176:179], v[102:105]
	v_mfma_f32_16x16x32_bf16 v[86:89], v[216:219], v[180:183], v[86:89]
	v_mfma_f32_16x16x32_bf16 v[86:89], v[220:223], v[204:207], v[86:89]
	v_mfma_f32_16x16x32_bf16 v[70:73], v[216:219], v[208:211], v[70:73]
	v_mfma_f32_16x16x32_bf16 v[70:73], v[220:223], v[212:215], v[70:73]
	v_mfma_f32_16x16x32_bf16 v[66:69], v[224:227], v[208:211], v[66:69]
	v_mfma_f32_16x16x32_bf16 v[66:69], v[228:231], v[212:215], v[66:69]
	v_mfma_f32_16x16x32_bf16 v[82:85], v[224:227], v[180:183], v[82:85]
	v_mfma_f32_16x16x32_bf16 v[82:85], v[228:231], v[204:207], v[82:85]
	v_mfma_f32_16x16x32_bf16 v[98:101], v[224:227], v[172:175], v[98:101]
	v_mfma_f32_16x16x32_bf16 v[98:101], v[228:231], v[176:179], v[98:101]
	v_mfma_f32_16x16x32_bf16 v[114:117], v[224:227], v[164:167], v[114:117]
	v_mfma_f32_16x16x32_bf16 v[114:117], v[228:231], v[168:171], v[114:117]
	s_barrier
	s_mov_b32 m0, s22
	s_add_u32 s72, s4, s6
	s_addc_u32 s73, s5, s7
	ds_read_b128 v[164:167], v150 offset:16384
	ds_read_b128 v[168:171], v150 offset:17408
	ds_read_b128 v[172:175], v150 offset:18432
	ds_read_b128 v[176:179], v150 offset:19456
	ds_read_b128 v[180:183], v150 offset:20480
	ds_read_b128 v[204:207], v150 offset:21504
	ds_read_b128 v[208:211], v150 offset:22528
	ds_read_b128 v[212:215], v150 offset:23552
	global_load_lds_dwordx4 v130, s[4:5]
	s_mov_b32 m0, s23
	s_nop 0
	global_load_lds_dwordx4 v134, s[4:5]
	s_barrier
	s_waitcnt lgkmcnt(0)
	v_mfma_f32_16x16x32_bf16 v[62:65], v[142:145], v[164:167], v[62:65]
	v_mfma_f32_16x16x32_bf16 v[62:65], v[152:155], v[168:171], v[62:65]
	v_mfma_f32_16x16x32_bf16 v[46:49], v[142:145], v[172:175], v[46:49]
	v_mfma_f32_16x16x32_bf16 v[46:49], v[152:155], v[176:179], v[46:49]
	v_mfma_f32_16x16x32_bf16 v[30:33], v[142:145], v[180:183], v[30:33]
	v_mfma_f32_16x16x32_bf16 v[30:33], v[152:155], v[204:207], v[30:33]
	v_mfma_f32_16x16x32_bf16 v[14:17], v[142:145], v[208:211], v[14:17]
	v_mfma_f32_16x16x32_bf16 v[14:17], v[152:155], v[212:215], v[14:17]
	v_mfma_f32_16x16x32_bf16 v[10:13], v[156:159], v[208:211], v[10:13]
	v_mfma_f32_16x16x32_bf16 v[10:13], v[160:163], v[212:215], v[10:13]
	v_mfma_f32_16x16x32_bf16 v[26:29], v[156:159], v[180:183], v[26:29]
	v_mfma_f32_16x16x32_bf16 v[26:29], v[160:163], v[204:207], v[26:29]
	v_mfma_f32_16x16x32_bf16 v[42:45], v[156:159], v[172:175], v[42:45]
	v_mfma_f32_16x16x32_bf16 v[42:45], v[160:163], v[176:179], v[42:45]
	v_mfma_f32_16x16x32_bf16 v[58:61], v[156:159], v[164:167], v[58:61]
	v_mfma_f32_16x16x32_bf16 v[58:61], v[160:163], v[168:171], v[58:61]
	s_barrier
	s_add_u32 s18, s18, s2
	s_addc_u32 s19, s19, 0
	s_add_i32 s66, s67, s21
	s_add_u32 s76, s18, s6
	s_addc_u32 s77, s19, s7
	s_mov_b32 m0, s66
	s_nop 0
	global_load_lds_dwordx4 v132, s[18:19]
	s_add_i32 m0, s66, 0x2000
	s_nop 0
	global_load_lds_dwordx4 v136, s[18:19]
	s_waitcnt vmcnt(6)
	s_barrier
	v_mfma_f32_16x16x32_bf16 v[54:57], v[216:219], v[164:167], v[54:57]
	v_mfma_f32_16x16x32_bf16 v[54:57], v[220:223], v[168:171], v[54:57]
	v_mfma_f32_16x16x32_bf16 v[38:41], v[216:219], v[172:175], v[38:41]
	v_mfma_f32_16x16x32_bf16 v[38:41], v[220:223], v[176:179], v[38:41]
	v_mfma_f32_16x16x32_bf16 v[22:25], v[216:219], v[180:183], v[22:25]
	v_mfma_f32_16x16x32_bf16 v[22:25], v[220:223], v[204:207], v[22:25]
	v_mfma_f32_16x16x32_bf16 v[6:9], v[216:219], v[208:211], v[6:9]
	v_mfma_f32_16x16x32_bf16 v[6:9], v[220:223], v[212:215], v[6:9]
	v_mfma_f32_16x16x32_bf16 v[2:5], v[224:227], v[208:211], v[2:5]
	v_mfma_f32_16x16x32_bf16 v[2:5], v[228:231], v[212:215], v[2:5]
	v_mfma_f32_16x16x32_bf16 v[18:21], v[224:227], v[180:183], v[18:21]
	v_mfma_f32_16x16x32_bf16 v[18:21], v[228:231], v[204:207], v[18:21]
	v_mfma_f32_16x16x32_bf16 v[34:37], v[224:227], v[172:175], v[34:37]
	v_mfma_f32_16x16x32_bf16 v[34:37], v[228:231], v[176:179], v[34:37]
	v_mfma_f32_16x16x32_bf16 v[50:53], v[224:227], v[164:167], v[50:53]
	v_mfma_f32_16x16x32_bf16 v[50:53], v[228:231], v[168:171], v[50:53]
	s_barrier
	s_add_i32 s18, 0, 0x18000
	ds_read_b128 v[142:145], v248 offset:32768
	ds_read_b128 v[152:155], v248 offset:33792
	ds_read_b128 v[156:159], v248 offset:34816
	ds_read_b128 v[160:163], v248 offset:35840
	s_add_u32 s4, s4, s2
	s_addc_u32 s5, s5, 0
	s_mov_b32 m0, s24
	ds_read_b128 v[164:167], v150 offset:32768
	ds_read_b128 v[168:171], v150 offset:33792
	ds_read_b128 v[172:175], v150 offset:34816
	ds_read_b128 v[176:179], v150 offset:35840
	ds_read_b128 v[180:183], v150 offset:36864
	ds_read_b128 v[204:207], v150 offset:37888
	ds_read_b128 v[208:211], v150 offset:38912
	ds_read_b128 v[212:215], v150 offset:39936
	global_load_lds_dwordx4 v130, s[4:5]
	s_mov_b32 m0, s25
	s_nop 0
	global_load_lds_dwordx4 v134, s[4:5]
	s_waitcnt lgkmcnt(8)
	s_barrier
	s_waitcnt lgkmcnt(0)
	v_mfma_f32_16x16x32_bf16 v[126:129], v[142:145], v[164:167], v[126:129]
	v_mfma_f32_16x16x32_bf16 v[126:129], v[152:155], v[168:171], v[126:129]
	v_mfma_f32_16x16x32_bf16 v[110:113], v[142:145], v[172:175], v[110:113]
	v_mfma_f32_16x16x32_bf16 v[110:113], v[152:155], v[176:179], v[110:113]
	v_mfma_f32_16x16x32_bf16 v[94:97], v[142:145], v[180:183], v[94:97]
	v_mfma_f32_16x16x32_bf16 v[94:97], v[152:155], v[204:207], v[94:97]
	v_mfma_f32_16x16x32_bf16 v[78:81], v[142:145], v[208:211], v[78:81]
	v_mfma_f32_16x16x32_bf16 v[78:81], v[152:155], v[212:215], v[78:81]
	v_mfma_f32_16x16x32_bf16 v[74:77], v[156:159], v[208:211], v[74:77]
	v_mfma_f32_16x16x32_bf16 v[74:77], v[160:163], v[212:215], v[74:77]
	v_mfma_f32_16x16x32_bf16 v[90:93], v[156:159], v[180:183], v[90:93]
	v_mfma_f32_16x16x32_bf16 v[90:93], v[160:163], v[204:207], v[90:93]
	v_mfma_f32_16x16x32_bf16 v[106:109], v[156:159], v[172:175], v[106:109]
	v_mfma_f32_16x16x32_bf16 v[106:109], v[160:163], v[176:179], v[106:109]
	v_mfma_f32_16x16x32_bf16 v[122:125], v[156:159], v[164:167], v[122:125]
	v_mfma_f32_16x16x32_bf16 v[122:125], v[160:163], v[168:171], v[122:125]
	s_barrier
	s_add_i32 s4, 0, 0x1c000
	s_add_i32 s5, s18, s21
	s_mov_b32 m0, s5
	ds_read_b128 v[216:219], v248 offset:49152
	ds_read_b128 v[220:223], v248 offset:50176
	ds_read_b128 v[224:227], v248 offset:51200
	ds_read_b128 v[228:231], v248 offset:52224
	global_load_lds_dwordx4 v132, s[70:71]
	s_add_i32 m0, s5, 0x2000
	s_nop 0
	global_load_lds_dwordx4 v136, s[70:71]
	s_barrier
	s_waitcnt lgkmcnt(0)
	v_mfma_f32_16x16x32_bf16 v[118:121], v[216:219], v[164:167], v[118:121]
	v_mfma_f32_16x16x32_bf16 v[118:121], v[220:223], v[168:171], v[118:121]
	v_mfma_f32_16x16x32_bf16 v[102:105], v[216:219], v[172:175], v[102:105]
	v_mfma_f32_16x16x32_bf16 v[102:105], v[220:223], v[176:179], v[102:105]
	v_mfma_f32_16x16x32_bf16 v[86:89], v[216:219], v[180:183], v[86:89]
	v_mfma_f32_16x16x32_bf16 v[86:89], v[220:223], v[204:207], v[86:89]
	v_mfma_f32_16x16x32_bf16 v[70:73], v[216:219], v[208:211], v[70:73]
	v_mfma_f32_16x16x32_bf16 v[70:73], v[220:223], v[212:215], v[70:73]
	v_mfma_f32_16x16x32_bf16 v[66:69], v[224:227], v[208:211], v[66:69]
	v_mfma_f32_16x16x32_bf16 v[66:69], v[228:231], v[212:215], v[66:69]
	v_mfma_f32_16x16x32_bf16 v[82:85], v[224:227], v[180:183], v[82:85]
	v_mfma_f32_16x16x32_bf16 v[82:85], v[228:231], v[204:207], v[82:85]
	v_mfma_f32_16x16x32_bf16 v[98:101], v[224:227], v[172:175], v[98:101]
	v_mfma_f32_16x16x32_bf16 v[98:101], v[228:231], v[176:179], v[98:101]
	v_mfma_f32_16x16x32_bf16 v[114:117], v[224:227], v[164:167], v[114:117]
	v_mfma_f32_16x16x32_bf16 v[114:117], v[228:231], v[168:171], v[114:117]
	s_barrier
	s_mov_b32 m0, s30
	ds_read_b128 v[164:167], v150 offset:49152
	ds_read_b128 v[168:171], v150 offset:50176
	ds_read_b128 v[172:175], v150 offset:51200
	ds_read_b128 v[176:179], v150 offset:52224
	ds_read_b128 v[180:183], v150 offset:53248
	ds_read_b128 v[204:207], v150 offset:54272
	ds_read_b128 v[208:211], v150 offset:55296
	ds_read_b128 v[212:215], v150 offset:56320
	global_load_lds_dwordx4 v130, s[72:73]
	s_mov_b32 m0, s31
	s_nop 0
	global_load_lds_dwordx4 v134, s[72:73]
	s_barrier
	s_waitcnt lgkmcnt(0)
	v_mfma_f32_16x16x32_bf16 v[62:65], v[142:145], v[164:167], v[62:65]
	v_mfma_f32_16x16x32_bf16 v[62:65], v[152:155], v[168:171], v[62:65]
	v_mfma_f32_16x16x32_bf16 v[46:49], v[142:145], v[172:175], v[46:49]
	v_mfma_f32_16x16x32_bf16 v[46:49], v[152:155], v[176:179], v[46:49]
	v_mfma_f32_16x16x32_bf16 v[30:33], v[142:145], v[180:183], v[30:33]
	v_mfma_f32_16x16x32_bf16 v[30:33], v[152:155], v[204:207], v[30:33]
	v_mfma_f32_16x16x32_bf16 v[14:17], v[142:145], v[208:211], v[14:17]
	v_mfma_f32_16x16x32_bf16 v[14:17], v[152:155], v[212:215], v[14:17]
	v_mfma_f32_16x16x32_bf16 v[10:13], v[156:159], v[208:211], v[10:13]
	v_mfma_f32_16x16x32_bf16 v[10:13], v[160:163], v[212:215], v[10:13]
	v_mfma_f32_16x16x32_bf16 v[26:29], v[156:159], v[180:183], v[26:29]
	v_mfma_f32_16x16x32_bf16 v[26:29], v[160:163], v[204:207], v[26:29]
	v_mfma_f32_16x16x32_bf16 v[42:45], v[156:159], v[172:175], v[42:45]
	v_mfma_f32_16x16x32_bf16 v[42:45], v[160:163], v[176:179], v[42:45]
	v_mfma_f32_16x16x32_bf16 v[58:61], v[156:159], v[164:167], v[58:61]
	v_mfma_f32_16x16x32_bf16 v[58:61], v[160:163], v[168:171], v[58:61]
	s_barrier
	s_add_i32 s4, s4, s21
	s_mov_b32 m0, s4
	s_nop 0
	global_load_lds_dwordx4 v132, s[76:77]
	s_add_i32 m0, s4, 0x2000
	s_nop 0
	global_load_lds_dwordx4 v136, s[76:77]
	s_add_u32 s0, s0, 0x100
	s_addc_u32 s1, s1, 0
	s_add_u32 s48, s48, 0x100
	s_addc_u32 s49, s49, 0
	s_cmp_ge_u32 s65, s27
	s_mov_b32 s4, s65
	s_waitcnt vmcnt(6)
	s_barrier
	v_mfma_f32_16x16x32_bf16 v[54:57], v[216:219], v[164:167], v[54:57]
	v_mfma_f32_16x16x32_bf16 v[54:57], v[220:223], v[168:171], v[54:57]
	v_mfma_f32_16x16x32_bf16 v[38:41], v[216:219], v[172:175], v[38:41]
	v_mfma_f32_16x16x32_bf16 v[38:41], v[220:223], v[176:179], v[38:41]
	v_mfma_f32_16x16x32_bf16 v[22:25], v[216:219], v[180:183], v[22:25]
	v_mfma_f32_16x16x32_bf16 v[22:25], v[220:223], v[204:207], v[22:25]
	v_mfma_f32_16x16x32_bf16 v[6:9], v[216:219], v[208:211], v[6:9]
	v_mfma_f32_16x16x32_bf16 v[6:9], v[220:223], v[212:215], v[6:9]
	v_mfma_f32_16x16x32_bf16 v[2:5], v[224:227], v[208:211], v[2:5]
	v_mfma_f32_16x16x32_bf16 v[2:5], v[228:231], v[212:215], v[2:5]
	v_mfma_f32_16x16x32_bf16 v[18:21], v[224:227], v[180:183], v[18:21]
	v_mfma_f32_16x16x32_bf16 v[18:21], v[228:231], v[204:207], v[18:21]
	v_mfma_f32_16x16x32_bf16 v[34:37], v[224:227], v[172:175], v[34:37]
	v_mfma_f32_16x16x32_bf16 v[34:37], v[228:231], v[176:179], v[34:37]
	v_mfma_f32_16x16x32_bf16 v[50:53], v[224:227], v[164:167], v[50:53]
	v_mfma_f32_16x16x32_bf16 v[50:53], v[228:231], v[168:171], v[50:53]
	s_barrier
	s_cbranch_scc0 .LBB0_698

.LBB0_741:
	s_add_u32 s0, s0, 0x80
	s_addc_u32 s1, s1, 0
	s_add_u32 s65, s4, 0x100
	s_addc_u32 s66, s5, 0
	s_mov_b32 s4, 0
	s_add_i32 s70, s4, 2
	s_add_u32 s10, s0, 0x80
	s_addc_u32 s5, s1, 0
	s_add_i32 s71, 0, 0x10000
	ds_read_b128 v[142:145], v248
	ds_read_b128 v[146:149], v248 offset:1024
	ds_read_b128 v[150:153], v248 offset:2048
	ds_read_b128 v[154:157], v248 offset:3072
	s_cmp_eq_u32 s43, s4
	s_cselect_b32 s4, s22, s10
	s_cselect_b32 s5, s23, s5
	s_cselect_b32 s11, s13, s66
	s_cselect_b32 s10, s12, s65
	s_add_i32 m0, s29, 0xc000
	ds_read_b128 v[158:161], v166
	ds_read_b128 v[168:171], v166 offset:1024
	ds_read_b128 v[172:175], v166 offset:2048
	ds_read_b128 v[176:179], v166 offset:3072
	ds_read_b128 v[180:183], v166 offset:4096
	ds_read_b128 v[204:207], v166 offset:5120
	ds_read_b128 v[208:211], v166 offset:6144
	ds_read_b128 v[212:215], v166 offset:7168
	global_load_lds_dwordx4 v138, s[0:1]
	s_add_i32 m0, s29, 0xe000
	s_nop 0
	global_load_lds_dwordx4 v140, s[0:1]
	s_waitcnt lgkmcnt(8)
	s_barrier
	s_waitcnt lgkmcnt(0)
	v_mfma_f32_16x16x32_bf16 v[126:129], v[142:145], v[158:161], 0
	v_mfma_f32_16x16x32_bf16 v[126:129], v[146:149], v[168:171], v[126:129]
	v_mfma_f32_16x16x32_bf16 v[110:113], v[142:145], v[172:175], 0
	v_mfma_f32_16x16x32_bf16 v[110:113], v[146:149], v[176:179], v[110:113]
	v_mfma_f32_16x16x32_bf16 v[94:97], v[142:145], v[180:183], 0
	v_mfma_f32_16x16x32_bf16 v[94:97], v[146:149], v[204:207], v[94:97]
	v_mfma_f32_16x16x32_bf16 v[78:81], v[142:145], v[208:211], 0
	v_mfma_f32_16x16x32_bf16 v[78:81], v[146:149], v[212:215], v[78:81]
	v_mfma_f32_16x16x32_bf16 v[74:77], v[150:153], v[208:211], 0
	v_mfma_f32_16x16x32_bf16 v[74:77], v[154:157], v[212:215], v[74:77]
	v_mfma_f32_16x16x32_bf16 v[90:93], v[150:153], v[180:183], 0
	v_mfma_f32_16x16x32_bf16 v[90:93], v[154:157], v[204:207], v[90:93]
	v_mfma_f32_16x16x32_bf16 v[106:109], v[150:153], v[172:175], 0
	v_mfma_f32_16x16x32_bf16 v[106:109], v[154:157], v[176:179], v[106:109]
	v_mfma_f32_16x16x32_bf16 v[122:125], v[150:153], v[158:161], 0
	v_mfma_f32_16x16x32_bf16 v[122:125], v[154:157], v[168:171], v[122:125]
	s_barrier
	s_add_i32 s72, 0, 0x14000
	s_add_i32 s71, s71, s28
	ds_read_b128 v[216:219], v248 offset:16384
	ds_read_b128 v[220:223], v248 offset:17408
	ds_read_b128 v[224:227], v248 offset:18432
	ds_read_b128 v[228:231], v248 offset:19456
	s_add_u32 s76, s10, s6
	s_addc_u32 s77, s11, s7
	s_mov_b32 m0, s71
	s_nop 0
	global_load_lds_dwordx4 v132, s[10:11]
	s_add_i32 m0, s71, 0x2000
	s_nop 0
	global_load_lds_dwordx4 v136, s[10:11]
	s_barrier
	s_waitcnt lgkmcnt(0)
	v_mfma_f32_16x16x32_bf16 v[118:121], v[216:219], v[158:161], 0
	v_mfma_f32_16x16x32_bf16 v[118:121], v[220:223], v[168:171], v[118:121]
	v_mfma_f32_16x16x32_bf16 v[102:105], v[216:219], v[172:175], 0
	v_mfma_f32_16x16x32_bf16 v[102:105], v[220:223], v[176:179], v[102:105]
	v_mfma_f32_16x16x32_bf16 v[86:89], v[216:219], v[180:183], 0
	v_mfma_f32_16x16x32_bf16 v[86:89], v[220:223], v[204:207], v[86:89]
	v_mfma_f32_16x16x32_bf16 v[70:73], v[216:219], v[208:211], 0
	v_mfma_f32_16x16x32_bf16 v[70:73], v[220:223], v[212:215], v[70:73]
	v_mfma_f32_16x16x32_bf16 v[66:69], v[224:227], v[208:211], 0
	v_mfma_f32_16x16x32_bf16 v[66:69], v[228:231], v[212:215], v[66:69]
	v_mfma_f32_16x16x32_bf16 v[82:85], v[224:227], v[180:183], 0
	v_mfma_f32_16x16x32_bf16 v[82:85], v[228:231], v[204:207], v[82:85]
	v_mfma_f32_16x16x32_bf16 v[98:101], v[224:227], v[172:175], 0
	v_mfma_f32_16x16x32_bf16 v[98:101], v[228:231], v[176:179], v[98:101]
	v_mfma_f32_16x16x32_bf16 v[114:117], v[224:227], v[158:161], 0
	v_mfma_f32_16x16x32_bf16 v[114:117], v[228:231], v[168:171], v[114:117]
	s_barrier
	s_mov_b32 m0, s29
	s_add_u32 s78, s4, s6
	s_addc_u32 s79, s5, s7
	ds_read_b128 v[158:161], v166 offset:16384
	ds_read_b128 v[168:171], v166 offset:17408
	ds_read_b128 v[172:175], v166 offset:18432
	ds_read_b128 v[176:179], v166 offset:19456
	ds_read_b128 v[180:183], v166 offset:20480
	ds_read_b128 v[204:207], v166 offset:21504
	ds_read_b128 v[208:211], v166 offset:22528
	ds_read_b128 v[212:215], v166 offset:23552
	global_load_lds_dwordx4 v130, s[4:5]
	s_mov_b32 m0, s30
	s_nop 0
	global_load_lds_dwordx4 v134, s[4:5]
	s_barrier
	s_waitcnt lgkmcnt(0)
	v_mfma_f32_16x16x32_bf16 v[62:65], v[142:145], v[158:161], 0
	v_mfma_f32_16x16x32_bf16 v[62:65], v[146:149], v[168:171], v[62:65]
	v_mfma_f32_16x16x32_bf16 v[46:49], v[142:145], v[172:175], 0
	v_mfma_f32_16x16x32_bf16 v[46:49], v[146:149], v[176:179], v[46:49]
	v_mfma_f32_16x16x32_bf16 v[30:33], v[142:145], v[180:183], 0
	v_mfma_f32_16x16x32_bf16 v[30:33], v[146:149], v[204:207], v[30:33]
	v_mfma_f32_16x16x32_bf16 v[14:17], v[142:145], v[208:211], 0
	v_mfma_f32_16x16x32_bf16 v[14:17], v[146:149], v[212:215], v[14:17]
	v_mfma_f32_16x16x32_bf16 v[10:13], v[150:153], v[208:211], 0
	v_mfma_f32_16x16x32_bf16 v[10:13], v[154:157], v[212:215], v[10:13]
	v_mfma_f32_16x16x32_bf16 v[26:29], v[150:153], v[180:183], 0
	v_mfma_f32_16x16x32_bf16 v[26:29], v[154:157], v[204:207], v[26:29]
	v_mfma_f32_16x16x32_bf16 v[42:45], v[150:153], v[172:175], 0
	v_mfma_f32_16x16x32_bf16 v[42:45], v[154:157], v[176:179], v[42:45]
	v_mfma_f32_16x16x32_bf16 v[58:61], v[150:153], v[158:161], 0
	v_mfma_f32_16x16x32_bf16 v[58:61], v[154:157], v[168:171], v[58:61]
	s_barrier
	s_add_u32 s10, s10, s2
	s_addc_u32 s11, s11, 0
	s_add_i32 s71, s72, s28
	s_add_u32 s80, s10, s6
	s_addc_u32 s81, s11, s7
	s_mov_b32 m0, s71
	s_nop 0
	global_load_lds_dwordx4 v132, s[10:11]
	s_add_i32 m0, s71, 0x2000
	s_nop 0
	global_load_lds_dwordx4 v136, s[10:11]
	s_waitcnt vmcnt(6)
	s_barrier
	v_mfma_f32_16x16x32_bf16 v[54:57], v[216:219], v[158:161], 0
	v_mfma_f32_16x16x32_bf16 v[54:57], v[220:223], v[168:171], v[54:57]
	v_mfma_f32_16x16x32_bf16 v[38:41], v[216:219], v[172:175], 0
	v_mfma_f32_16x16x32_bf16 v[38:41], v[220:223], v[176:179], v[38:41]
	v_mfma_f32_16x16x32_bf16 v[22:25], v[216:219], v[180:183], 0
	v_mfma_f32_16x16x32_bf16 v[22:25], v[220:223], v[204:207], v[22:25]
	v_mfma_f32_16x16x32_bf16 v[6:9], v[216:219], v[208:211], 0
	v_mfma_f32_16x16x32_bf16 v[6:9], v[220:223], v[212:215], v[6:9]
	v_mfma_f32_16x16x32_bf16 v[2:5], v[224:227], v[208:211], 0
	v_mfma_f32_16x16x32_bf16 v[2:5], v[228:231], v[212:215], v[2:5]
	v_mfma_f32_16x16x32_bf16 v[18:21], v[224:227], v[180:183], 0
	v_mfma_f32_16x16x32_bf16 v[18:21], v[228:231], v[204:207], v[18:21]
	v_mfma_f32_16x16x32_bf16 v[34:37], v[224:227], v[172:175], 0
	v_mfma_f32_16x16x32_bf16 v[34:37], v[228:231], v[176:179], v[34:37]
	v_mfma_f32_16x16x32_bf16 v[50:53], v[224:227], v[158:161], 0
	v_mfma_f32_16x16x32_bf16 v[50:53], v[228:231], v[168:171], v[50:53]
	s_barrier
	s_add_i32 s10, 0, 0x18000
	ds_read_b128 v[142:145], v248 offset:32768
	ds_read_b128 v[146:149], v248 offset:33792
	ds_read_b128 v[150:153], v248 offset:34816
	ds_read_b128 v[154:157], v248 offset:35840
	s_add_u32 s4, s4, s2
	s_addc_u32 s5, s5, 0
	s_mov_b32 m0, s31
	ds_read_b128 v[158:161], v166 offset:32768
	ds_read_b128 v[168:171], v166 offset:33792
	ds_read_b128 v[172:175], v166 offset:34816
	ds_read_b128 v[176:179], v166 offset:35840
	ds_read_b128 v[180:183], v166 offset:36864
	ds_read_b128 v[204:207], v166 offset:37888
	ds_read_b128 v[208:211], v166 offset:38912
	ds_read_b128 v[212:215], v166 offset:39936
	global_load_lds_dwordx4 v130, s[4:5]
	s_mov_b32 m0, s34
	s_nop 0
	global_load_lds_dwordx4 v134, s[4:5]
	s_waitcnt lgkmcnt(8)
	s_barrier
	s_waitcnt lgkmcnt(0)
	v_mfma_f32_16x16x32_bf16 v[126:129], v[142:145], v[158:161], v[126:129]
	v_mfma_f32_16x16x32_bf16 v[126:129], v[146:149], v[168:171], v[126:129]
	v_mfma_f32_16x16x32_bf16 v[110:113], v[142:145], v[172:175], v[110:113]
	v_mfma_f32_16x16x32_bf16 v[110:113], v[146:149], v[176:179], v[110:113]
	v_mfma_f32_16x16x32_bf16 v[94:97], v[142:145], v[180:183], v[94:97]
	v_mfma_f32_16x16x32_bf16 v[94:97], v[146:149], v[204:207], v[94:97]
	v_mfma_f32_16x16x32_bf16 v[78:81], v[142:145], v[208:211], v[78:81]
	v_mfma_f32_16x16x32_bf16 v[78:81], v[146:149], v[212:215], v[78:81]
	v_mfma_f32_16x16x32_bf16 v[74:77], v[150:153], v[208:211], v[74:77]
	v_mfma_f32_16x16x32_bf16 v[74:77], v[154:157], v[212:215], v[74:77]
	v_mfma_f32_16x16x32_bf16 v[90:93], v[150:153], v[180:183], v[90:93]
	v_mfma_f32_16x16x32_bf16 v[90:93], v[154:157], v[204:207], v[90:93]
	v_mfma_f32_16x16x32_bf16 v[106:109], v[150:153], v[172:175], v[106:109]
	v_mfma_f32_16x16x32_bf16 v[106:109], v[154:157], v[176:179], v[106:109]
	v_mfma_f32_16x16x32_bf16 v[122:125], v[150:153], v[158:161], v[122:125]
	v_mfma_f32_16x16x32_bf16 v[122:125], v[154:157], v[168:171], v[122:125]
	s_barrier
	s_add_i32 s4, 0, 0x1c000
	s_add_i32 s5, s10, s28
	s_mov_b32 m0, s5
	ds_read_b128 v[216:219], v248 offset:49152
	ds_read_b128 v[220:223], v248 offset:50176
	ds_read_b128 v[224:227], v248 offset:51200
	ds_read_b128 v[228:231], v248 offset:52224
	global_load_lds_dwordx4 v132, s[76:77]
	s_add_i32 m0, s5, 0x2000
	s_nop 0
	global_load_lds_dwordx4 v136, s[76:77]
	s_barrier
	s_waitcnt lgkmcnt(0)
	v_mfma_f32_16x16x32_bf16 v[118:121], v[216:219], v[158:161], v[118:121]
	v_mfma_f32_16x16x32_bf16 v[118:121], v[220:223], v[168:171], v[118:121]
	v_mfma_f32_16x16x32_bf16 v[102:105], v[216:219], v[172:175], v[102:105]
	v_mfma_f32_16x16x32_bf16 v[102:105], v[220:223], v[176:179], v[102:105]
	v_mfma_f32_16x16x32_bf16 v[86:89], v[216:219], v[180:183], v[86:89]
	v_mfma_f32_16x16x32_bf16 v[86:89], v[220:223], v[204:207], v[86:89]
	v_mfma_f32_16x16x32_bf16 v[70:73], v[216:219], v[208:211], v[70:73]
	v_mfma_f32_16x16x32_bf16 v[70:73], v[220:223], v[212:215], v[70:73]
	v_mfma_f32_16x16x32_bf16 v[66:69], v[224:227], v[208:211], v[66:69]
	v_mfma_f32_16x16x32_bf16 v[66:69], v[228:231], v[212:215], v[66:69]
	v_mfma_f32_16x16x32_bf16 v[82:85], v[224:227], v[180:183], v[82:85]
	v_mfma_f32_16x16x32_bf16 v[82:85], v[228:231], v[204:207], v[82:85]
	v_mfma_f32_16x16x32_bf16 v[98:101], v[224:227], v[172:175], v[98:101]
	v_mfma_f32_16x16x32_bf16 v[98:101], v[228:231], v[176:179], v[98:101]
	v_mfma_f32_16x16x32_bf16 v[114:117], v[224:227], v[158:161], v[114:117]
	v_mfma_f32_16x16x32_bf16 v[114:117], v[228:231], v[168:171], v[114:117]
	s_barrier
	s_mov_b32 m0, s41
	ds_read_b128 v[158:161], v166 offset:49152
	ds_read_b128 v[168:171], v166 offset:50176
	ds_read_b128 v[172:175], v166 offset:51200
	ds_read_b128 v[176:179], v166 offset:52224
	ds_read_b128 v[180:183], v166 offset:53248
	ds_read_b128 v[204:207], v166 offset:54272
	ds_read_b128 v[208:211], v166 offset:55296
	ds_read_b128 v[212:215], v166 offset:56320
	global_load_lds_dwordx4 v130, s[78:79]
	s_mov_b32 m0, s42
	s_nop 0
	global_load_lds_dwordx4 v134, s[78:79]
	s_barrier
	s_waitcnt lgkmcnt(0)
	v_mfma_f32_16x16x32_bf16 v[62:65], v[142:145], v[158:161], v[62:65]
	v_mfma_f32_16x16x32_bf16 v[62:65], v[146:149], v[168:171], v[62:65]
	v_mfma_f32_16x16x32_bf16 v[46:49], v[142:145], v[172:175], v[46:49]
	v_mfma_f32_16x16x32_bf16 v[46:49], v[146:149], v[176:179], v[46:49]
	v_mfma_f32_16x16x32_bf16 v[30:33], v[142:145], v[180:183], v[30:33]
	v_mfma_f32_16x16x32_bf16 v[30:33], v[146:149], v[204:207], v[30:33]
	v_mfma_f32_16x16x32_bf16 v[14:17], v[142:145], v[208:211], v[14:17]
	v_mfma_f32_16x16x32_bf16 v[14:17], v[146:149], v[212:215], v[14:17]
	v_mfma_f32_16x16x32_bf16 v[10:13], v[150:153], v[208:211], v[10:13]
	v_mfma_f32_16x16x32_bf16 v[10:13], v[154:157], v[212:215], v[10:13]
	v_mfma_f32_16x16x32_bf16 v[26:29], v[150:153], v[180:183], v[26:29]
	v_mfma_f32_16x16x32_bf16 v[26:29], v[154:157], v[204:207], v[26:29]
	v_mfma_f32_16x16x32_bf16 v[42:45], v[150:153], v[172:175], v[42:45]
	v_mfma_f32_16x16x32_bf16 v[42:45], v[154:157], v[176:179], v[42:45]
	v_mfma_f32_16x16x32_bf16 v[58:61], v[150:153], v[158:161], v[58:61]
	v_mfma_f32_16x16x32_bf16 v[58:61], v[154:157], v[168:171], v[58:61]
	s_barrier
	s_add_i32 s4, s4, s28
	s_mov_b32 m0, s4
	s_nop 0
	global_load_lds_dwordx4 v132, s[80:81]
	s_add_i32 m0, s4, 0x2000
	s_nop 0
	global_load_lds_dwordx4 v136, s[80:81]
	s_add_u32 s0, s0, 0x100
	s_addc_u32 s1, s1, 0
	s_add_u32 s65, s65, 0x100
	s_addc_u32 s66, s66, 0
	s_cmp_ge_u32 s70, s35
	s_mov_b32 s4, s70
	s_waitcnt vmcnt(6)
	s_barrier
	v_mfma_f32_16x16x32_bf16 v[54:57], v[216:219], v[158:161], v[54:57]
	v_mfma_f32_16x16x32_bf16 v[54:57], v[220:223], v[168:171], v[54:57]
	v_mfma_f32_16x16x32_bf16 v[38:41], v[216:219], v[172:175], v[38:41]
	v_mfma_f32_16x16x32_bf16 v[38:41], v[220:223], v[176:179], v[38:41]
	v_mfma_f32_16x16x32_bf16 v[22:25], v[216:219], v[180:183], v[22:25]
	v_mfma_f32_16x16x32_bf16 v[22:25], v[220:223], v[204:207], v[22:25]
	v_mfma_f32_16x16x32_bf16 v[6:9], v[216:219], v[208:211], v[6:9]
	v_mfma_f32_16x16x32_bf16 v[6:9], v[220:223], v[212:215], v[6:9]
	v_mfma_f32_16x16x32_bf16 v[2:5], v[224:227], v[208:211], v[2:5]
	v_mfma_f32_16x16x32_bf16 v[2:5], v[228:231], v[212:215], v[2:5]
	v_mfma_f32_16x16x32_bf16 v[18:21], v[224:227], v[180:183], v[18:21]
	v_mfma_f32_16x16x32_bf16 v[18:21], v[228:231], v[204:207], v[18:21]
	v_mfma_f32_16x16x32_bf16 v[34:37], v[224:227], v[172:175], v[34:37]
	v_mfma_f32_16x16x32_bf16 v[34:37], v[228:231], v[176:179], v[34:37]
	v_mfma_f32_16x16x32_bf16 v[50:53], v[224:227], v[158:161], v[50:53]
	v_mfma_f32_16x16x32_bf16 v[50:53], v[228:231], v[168:171], v[50:53]
	s_barrier
	s_cbranch_scc1 .Lkexit_742
.LBB0_742:
	s_add_i32 s70, s4, 2
	s_add_u32 s10, s0, 0x80
	s_addc_u32 s5, s1, 0
	s_add_i32 s71, 0, 0x10000
	ds_read_b128 v[142:145], v248
	ds_read_b128 v[146:149], v248 offset:1024
	ds_read_b128 v[150:153], v248 offset:2048
	ds_read_b128 v[154:157], v248 offset:3072
	s_cmp_eq_u32 s43, s4
	s_cselect_b32 s4, s22, s10
	s_cselect_b32 s5, s23, s5
	s_cselect_b32 s11, s13, s66
	s_cselect_b32 s10, s12, s65
	s_add_i32 m0, s29, 0xc000
	ds_read_b128 v[158:161], v166
	ds_read_b128 v[168:171], v166 offset:1024
	ds_read_b128 v[172:175], v166 offset:2048
	ds_read_b128 v[176:179], v166 offset:3072
	ds_read_b128 v[180:183], v166 offset:4096
	ds_read_b128 v[204:207], v166 offset:5120
	ds_read_b128 v[208:211], v166 offset:6144
	ds_read_b128 v[212:215], v166 offset:7168
	global_load_lds_dwordx4 v138, s[0:1]
	s_add_i32 m0, s29, 0xe000
	s_nop 0
	global_load_lds_dwordx4 v140, s[0:1]
	s_waitcnt lgkmcnt(8)
	s_barrier
	s_waitcnt lgkmcnt(0)
	v_mfma_f32_16x16x32_bf16 v[126:129], v[142:145], v[158:161], v[126:129]
	v_mfma_f32_16x16x32_bf16 v[126:129], v[146:149], v[168:171], v[126:129]
	v_mfma_f32_16x16x32_bf16 v[110:113], v[142:145], v[172:175], v[110:113]
	v_mfma_f32_16x16x32_bf16 v[110:113], v[146:149], v[176:179], v[110:113]
	v_mfma_f32_16x16x32_bf16 v[94:97], v[142:145], v[180:183], v[94:97]
	v_mfma_f32_16x16x32_bf16 v[94:97], v[146:149], v[204:207], v[94:97]
	v_mfma_f32_16x16x32_bf16 v[78:81], v[142:145], v[208:211], v[78:81]
	v_mfma_f32_16x16x32_bf16 v[78:81], v[146:149], v[212:215], v[78:81]
	v_mfma_f32_16x16x32_bf16 v[74:77], v[150:153], v[208:211], v[74:77]
	v_mfma_f32_16x16x32_bf16 v[74:77], v[154:157], v[212:215], v[74:77]
	v_mfma_f32_16x16x32_bf16 v[90:93], v[150:153], v[180:183], v[90:93]
	v_mfma_f32_16x16x32_bf16 v[90:93], v[154:157], v[204:207], v[90:93]
	v_mfma_f32_16x16x32_bf16 v[106:109], v[150:153], v[172:175], v[106:109]
	v_mfma_f32_16x16x32_bf16 v[106:109], v[154:157], v[176:179], v[106:109]
	v_mfma_f32_16x16x32_bf16 v[122:125], v[150:153], v[158:161], v[122:125]
	v_mfma_f32_16x16x32_bf16 v[122:125], v[154:157], v[168:171], v[122:125]
	s_barrier
	s_add_i32 s72, 0, 0x14000
	s_add_i32 s71, s71, s28
	ds_read_b128 v[216:219], v248 offset:16384
	ds_read_b128 v[220:223], v248 offset:17408
	ds_read_b128 v[224:227], v248 offset:18432
	ds_read_b128 v[228:231], v248 offset:19456
	s_add_u32 s76, s10, s6
	s_addc_u32 s77, s11, s7
	s_mov_b32 m0, s71
	s_nop 0
	global_load_lds_dwordx4 v132, s[10:11]
	s_add_i32 m0, s71, 0x2000
	s_nop 0
	global_load_lds_dwordx4 v136, s[10:11]
	s_barrier
	s_waitcnt lgkmcnt(0)
	v_mfma_f32_16x16x32_bf16 v[118:121], v[216:219], v[158:161], v[118:121]
	v_mfma_f32_16x16x32_bf16 v[118:121], v[220:223], v[168:171], v[118:121]
	v_mfma_f32_16x16x32_bf16 v[102:105], v[216:219], v[172:175], v[102:105]
	v_mfma_f32_16x16x32_bf16 v[102:105], v[220:223], v[176:179], v[102:105]
	v_mfma_f32_16x16x32_bf16 v[86:89], v[216:219], v[180:183], v[86:89]
	v_mfma_f32_16x16x32_bf16 v[86:89], v[220:223], v[204:207], v[86:89]
	v_mfma_f32_16x16x32_bf16 v[70:73], v[216:219], v[208:211], v[70:73]
	v_mfma_f32_16x16x32_bf16 v[70:73], v[220:223], v[212:215], v[70:73]
	v_mfma_f32_16x16x32_bf16 v[66:69], v[224:227], v[208:211], v[66:69]
	v_mfma_f32_16x16x32_bf16 v[66:69], v[228:231], v[212:215], v[66:69]
	v_mfma_f32_16x16x32_bf16 v[82:85], v[224:227], v[180:183], v[82:85]
	v_mfma_f32_16x16x32_bf16 v[82:85], v[228:231], v[204:207], v[82:85]
	v_mfma_f32_16x16x32_bf16 v[98:101], v[224:227], v[172:175], v[98:101]
	v_mfma_f32_16x16x32_bf16 v[98:101], v[228:231], v[176:179], v[98:101]
	v_mfma_f32_16x16x32_bf16 v[114:117], v[224:227], v[158:161], v[114:117]
	v_mfma_f32_16x16x32_bf16 v[114:117], v[228:231], v[168:171], v[114:117]
	s_barrier
	s_mov_b32 m0, s29
	s_add_u32 s78, s4, s6
	s_addc_u32 s79, s5, s7
	ds_read_b128 v[158:161], v166 offset:16384
	ds_read_b128 v[168:171], v166 offset:17408
	ds_read_b128 v[172:175], v166 offset:18432
	ds_read_b128 v[176:179], v166 offset:19456
	ds_read_b128 v[180:183], v166 offset:20480
	ds_read_b128 v[204:207], v166 offset:21504
	ds_read_b128 v[208:211], v166 offset:22528
	ds_read_b128 v[212:215], v166 offset:23552
	global_load_lds_dwordx4 v130, s[4:5]
	s_mov_b32 m0, s30
	s_nop 0
	global_load_lds_dwordx4 v134, s[4:5]
	s_barrier
	s_waitcnt lgkmcnt(0)
	v_mfma_f32_16x16x32_bf16 v[62:65], v[142:145], v[158:161], v[62:65]
	v_mfma_f32_16x16x32_bf16 v[62:65], v[146:149], v[168:171], v[62:65]
	v_mfma_f32_16x16x32_bf16 v[46:49], v[142:145], v[172:175], v[46:49]
	v_mfma_f32_16x16x32_bf16 v[46:49], v[146:149], v[176:179], v[46:49]
	v_mfma_f32_16x16x32_bf16 v[30:33], v[142:145], v[180:183], v[30:33]
	v_mfma_f32_16x16x32_bf16 v[30:33], v[146:149], v[204:207], v[30:33]
	v_mfma_f32_16x16x32_bf16 v[14:17], v[142:145], v[208:211], v[14:17]
	v_mfma_f32_16x16x32_bf16 v[14:17], v[146:149], v[212:215], v[14:17]
	v_mfma_f32_16x16x32_bf16 v[10:13], v[150:153], v[208:211], v[10:13]
	v_mfma_f32_16x16x32_bf16 v[10:13], v[154:157], v[212:215], v[10:13]
	v_mfma_f32_16x16x32_bf16 v[26:29], v[150:153], v[180:183], v[26:29]
	v_mfma_f32_16x16x32_bf16 v[26:29], v[154:157], v[204:207], v[26:29]
	v_mfma_f32_16x16x32_bf16 v[42:45], v[150:153], v[172:175], v[42:45]
	v_mfma_f32_16x16x32_bf16 v[42:45], v[154:157], v[176:179], v[42:45]
	v_mfma_f32_16x16x32_bf16 v[58:61], v[150:153], v[158:161], v[58:61]
	v_mfma_f32_16x16x32_bf16 v[58:61], v[154:157], v[168:171], v[58:61]
	s_barrier
	s_add_u32 s10, s10, s2
	s_addc_u32 s11, s11, 0
	s_add_i32 s71, s72, s28
	s_add_u32 s80, s10, s6
	s_addc_u32 s81, s11, s7
	s_mov_b32 m0, s71
	s_nop 0
	global_load_lds_dwordx4 v132, s[10:11]
	s_add_i32 m0, s71, 0x2000
	s_nop 0
	global_load_lds_dwordx4 v136, s[10:11]
	s_waitcnt vmcnt(6)
	s_barrier
	v_mfma_f32_16x16x32_bf16 v[54:57], v[216:219], v[158:161], v[54:57]
	v_mfma_f32_16x16x32_bf16 v[54:57], v[220:223], v[168:171], v[54:57]
	v_mfma_f32_16x16x32_bf16 v[38:41], v[216:219], v[172:175], v[38:41]
	v_mfma_f32_16x16x32_bf16 v[38:41], v[220:223], v[176:179], v[38:41]
	v_mfma_f32_16x16x32_bf16 v[22:25], v[216:219], v[180:183], v[22:25]
	v_mfma_f32_16x16x32_bf16 v[22:25], v[220:223], v[204:207], v[22:25]
	v_mfma_f32_16x16x32_bf16 v[6:9], v[216:219], v[208:211], v[6:9]
	v_mfma_f32_16x16x32_bf16 v[6:9], v[220:223], v[212:215], v[6:9]
	v_mfma_f32_16x16x32_bf16 v[2:5], v[224:227], v[208:211], v[2:5]
	v_mfma_f32_16x16x32_bf16 v[2:5], v[228:231], v[212:215], v[2:5]
	v_mfma_f32_16x16x32_bf16 v[18:21], v[224:227], v[180:183], v[18:21]
	v_mfma_f32_16x16x32_bf16 v[18:21], v[228:231], v[204:207], v[18:21]
	v_mfma_f32_16x16x32_bf16 v[34:37], v[224:227], v[172:175], v[34:37]
	v_mfma_f32_16x16x32_bf16 v[34:37], v[228:231], v[176:179], v[34:37]
	v_mfma_f32_16x16x32_bf16 v[50:53], v[224:227], v[158:161], v[50:53]
	v_mfma_f32_16x16x32_bf16 v[50:53], v[228:231], v[168:171], v[50:53]
	s_barrier
	s_add_i32 s10, 0, 0x18000
	ds_read_b128 v[142:145], v248 offset:32768
	ds_read_b128 v[146:149], v248 offset:33792
	ds_read_b128 v[150:153], v248 offset:34816
	ds_read_b128 v[154:157], v248 offset:35840
	s_add_u32 s4, s4, s2
	s_addc_u32 s5, s5, 0
	s_mov_b32 m0, s31
	ds_read_b128 v[158:161], v166 offset:32768
	ds_read_b128 v[168:171], v166 offset:33792
	ds_read_b128 v[172:175], v166 offset:34816
	ds_read_b128 v[176:179], v166 offset:35840
	ds_read_b128 v[180:183], v166 offset:36864
	ds_read_b128 v[204:207], v166 offset:37888
	ds_read_b128 v[208:211], v166 offset:38912
	ds_read_b128 v[212:215], v166 offset:39936
	global_load_lds_dwordx4 v130, s[4:5]
	s_mov_b32 m0, s34
	s_nop 0
	global_load_lds_dwordx4 v134, s[4:5]
	s_waitcnt lgkmcnt(8)
	s_barrier
	s_waitcnt lgkmcnt(0)
	v_mfma_f32_16x16x32_bf16 v[126:129], v[142:145], v[158:161], v[126:129]
	v_mfma_f32_16x16x32_bf16 v[126:129], v[146:149], v[168:171], v[126:129]
	v_mfma_f32_16x16x32_bf16 v[110:113], v[142:145], v[172:175], v[110:113]
	v_mfma_f32_16x16x32_bf16 v[110:113], v[146:149], v[176:179], v[110:113]
	v_mfma_f32_16x16x32_bf16 v[94:97], v[142:145], v[180:183], v[94:97]
	v_mfma_f32_16x16x32_bf16 v[94:97], v[146:149], v[204:207], v[94:97]
	v_mfma_f32_16x16x32_bf16 v[78:81], v[142:145], v[208:211], v[78:81]
	v_mfma_f32_16x16x32_bf16 v[78:81], v[146:149], v[212:215], v[78:81]
	v_mfma_f32_16x16x32_bf16 v[74:77], v[150:153], v[208:211], v[74:77]
	v_mfma_f32_16x16x32_bf16 v[74:77], v[154:157], v[212:215], v[74:77]
	v_mfma_f32_16x16x32_bf16 v[90:93], v[150:153], v[180:183], v[90:93]
	v_mfma_f32_16x16x32_bf16 v[90:93], v[154:157], v[204:207], v[90:93]
	v_mfma_f32_16x16x32_bf16 v[106:109], v[150:153], v[172:175], v[106:109]
	v_mfma_f32_16x16x32_bf16 v[106:109], v[154:157], v[176:179], v[106:109]
	v_mfma_f32_16x16x32_bf16 v[122:125], v[150:153], v[158:161], v[122:125]
	v_mfma_f32_16x16x32_bf16 v[122:125], v[154:157], v[168:171], v[122:125]
	s_barrier
	s_add_i32 s4, 0, 0x1c000
	s_add_i32 s5, s10, s28
	s_mov_b32 m0, s5
	ds_read_b128 v[216:219], v248 offset:49152
	ds_read_b128 v[220:223], v248 offset:50176
	ds_read_b128 v[224:227], v248 offset:51200
	ds_read_b128 v[228:231], v248 offset:52224
	global_load_lds_dwordx4 v132, s[76:77]
	s_add_i32 m0, s5, 0x2000
	s_nop 0
	global_load_lds_dwordx4 v136, s[76:77]
	s_barrier
	s_waitcnt lgkmcnt(0)
	v_mfma_f32_16x16x32_bf16 v[118:121], v[216:219], v[158:161], v[118:121]
	v_mfma_f32_16x16x32_bf16 v[118:121], v[220:223], v[168:171], v[118:121]
	v_mfma_f32_16x16x32_bf16 v[102:105], v[216:219], v[172:175], v[102:105]
	v_mfma_f32_16x16x32_bf16 v[102:105], v[220:223], v[176:179], v[102:105]
	v_mfma_f32_16x16x32_bf16 v[86:89], v[216:219], v[180:183], v[86:89]
	v_mfma_f32_16x16x32_bf16 v[86:89], v[220:223], v[204:207], v[86:89]
	v_mfma_f32_16x16x32_bf16 v[70:73], v[216:219], v[208:211], v[70:73]
	v_mfma_f32_16x16x32_bf16 v[70:73], v[220:223], v[212:215], v[70:73]
	v_mfma_f32_16x16x32_bf16 v[66:69], v[224:227], v[208:211], v[66:69]
	v_mfma_f32_16x16x32_bf16 v[66:69], v[228:231], v[212:215], v[66:69]
	v_mfma_f32_16x16x32_bf16 v[82:85], v[224:227], v[180:183], v[82:85]
	v_mfma_f32_16x16x32_bf16 v[82:85], v[228:231], v[204:207], v[82:85]
	v_mfma_f32_16x16x32_bf16 v[98:101], v[224:227], v[172:175], v[98:101]
	v_mfma_f32_16x16x32_bf16 v[98:101], v[228:231], v[176:179], v[98:101]
	v_mfma_f32_16x16x32_bf16 v[114:117], v[224:227], v[158:161], v[114:117]
	v_mfma_f32_16x16x32_bf16 v[114:117], v[228:231], v[168:171], v[114:117]
	s_barrier
	s_mov_b32 m0, s41
	ds_read_b128 v[158:161], v166 offset:49152
	ds_read_b128 v[168:171], v166 offset:50176
	ds_read_b128 v[172:175], v166 offset:51200
	ds_read_b128 v[176:179], v166 offset:52224
	ds_read_b128 v[180:183], v166 offset:53248
	ds_read_b128 v[204:207], v166 offset:54272
	ds_read_b128 v[208:211], v166 offset:55296
	ds_read_b128 v[212:215], v166 offset:56320
	global_load_lds_dwordx4 v130, s[78:79]
	s_mov_b32 m0, s42
	s_nop 0
	global_load_lds_dwordx4 v134, s[78:79]
	s_barrier
	s_waitcnt lgkmcnt(0)
	v_mfma_f32_16x16x32_bf16 v[62:65], v[142:145], v[158:161], v[62:65]
	v_mfma_f32_16x16x32_bf16 v[62:65], v[146:149], v[168:171], v[62:65]
	v_mfma_f32_16x16x32_bf16 v[46:49], v[142:145], v[172:175], v[46:49]
	v_mfma_f32_16x16x32_bf16 v[46:49], v[146:149], v[176:179], v[46:49]
	v_mfma_f32_16x16x32_bf16 v[30:33], v[142:145], v[180:183], v[30:33]
	v_mfma_f32_16x16x32_bf16 v[30:33], v[146:149], v[204:207], v[30:33]
	v_mfma_f32_16x16x32_bf16 v[14:17], v[142:145], v[208:211], v[14:17]
	v_mfma_f32_16x16x32_bf16 v[14:17], v[146:149], v[212:215], v[14:17]
	v_mfma_f32_16x16x32_bf16 v[10:13], v[150:153], v[208:211], v[10:13]
	v_mfma_f32_16x16x32_bf16 v[10:13], v[154:157], v[212:215], v[10:13]
	v_mfma_f32_16x16x32_bf16 v[26:29], v[150:153], v[180:183], v[26:29]
	v_mfma_f32_16x16x32_bf16 v[26:29], v[154:157], v[204:207], v[26:29]
	v_mfma_f32_16x16x32_bf16 v[42:45], v[150:153], v[172:175], v[42:45]
	v_mfma_f32_16x16x32_bf16 v[42:45], v[154:157], v[176:179], v[42:45]
	v_mfma_f32_16x16x32_bf16 v[58:61], v[150:153], v[158:161], v[58:61]
	v_mfma_f32_16x16x32_bf16 v[58:61], v[154:157], v[168:171], v[58:61]
	s_barrier
	s_add_i32 s4, s4, s28
	s_mov_b32 m0, s4
	s_nop 0
	global_load_lds_dwordx4 v132, s[80:81]
	s_add_i32 m0, s4, 0x2000
	s_nop 0
	global_load_lds_dwordx4 v136, s[80:81]
	s_add_u32 s0, s0, 0x100
	s_addc_u32 s1, s1, 0
	s_add_u32 s65, s65, 0x100
	s_addc_u32 s66, s66, 0
	s_cmp_ge_u32 s70, s35
	s_mov_b32 s4, s70
	s_waitcnt vmcnt(6)
	s_barrier
	v_mfma_f32_16x16x32_bf16 v[54:57], v[216:219], v[158:161], v[54:57]
	v_mfma_f32_16x16x32_bf16 v[54:57], v[220:223], v[168:171], v[54:57]
	v_mfma_f32_16x16x32_bf16 v[38:41], v[216:219], v[172:175], v[38:41]
	v_mfma_f32_16x16x32_bf16 v[38:41], v[220:223], v[176:179], v[38:41]
	v_mfma_f32_16x16x32_bf16 v[22:25], v[216:219], v[180:183], v[22:25]
	v_mfma_f32_16x16x32_bf16 v[22:25], v[220:223], v[204:207], v[22:25]
	v_mfma_f32_16x16x32_bf16 v[6:9], v[216:219], v[208:211], v[6:9]
	v_mfma_f32_16x16x32_bf16 v[6:9], v[220:223], v[212:215], v[6:9]
	v_mfma_f32_16x16x32_bf16 v[2:5], v[224:227], v[208:211], v[2:5]
	v_mfma_f32_16x16x32_bf16 v[2:5], v[228:231], v[212:215], v[2:5]
	v_mfma_f32_16x16x32_bf16 v[18:21], v[224:227], v[180:183], v[18:21]
	v_mfma_f32_16x16x32_bf16 v[18:21], v[228:231], v[204:207], v[18:21]
	v_mfma_f32_16x16x32_bf16 v[34:37], v[224:227], v[172:175], v[34:37]
	v_mfma_f32_16x16x32_bf16 v[34:37], v[228:231], v[176:179], v[34:37]
	v_mfma_f32_16x16x32_bf16 v[50:53], v[224:227], v[158:161], v[50:53]
	v_mfma_f32_16x16x32_bf16 v[50:53], v[228:231], v[168:171], v[50:53]
	s_barrier
	s_cbranch_scc0 .LBB0_742

.LBB0_805:
	s_add_u32 s0, s0, 0x80
	s_addc_u32 s1, s1, 0
	s_add_u32 s12, s4, 0x100
	s_addc_u32 s13, s5, 0
	s_mov_b32 s4, 0
	s_waitcnt vmcnt(0)
	s_add_i32 s27, s4, 2
	s_add_u32 s10, s0, 0x80
	s_addc_u32 s5, s1, 0
	s_add_i32 s28, 0, 0x10000
	ds_read_b128 v[142:145], v248
	ds_read_b128 v[146:149], v248 offset:1024
	ds_read_b128 v[150:153], v248 offset:2048
	ds_read_b128 v[154:157], v248 offset:3072
	s_cmp_eq_u32 s48, s4
	s_cselect_b32 s4, s22, s10
	s_cselect_b32 s5, s23, s5
	s_cselect_b32 s11, s25, s13
	s_cselect_b32 s10, s24, s12
	s_add_i32 m0, s35, 0xc000
	ds_read_b128 v[158:161], v172
	ds_read_b128 v[162:165], v172 offset:1024
	ds_read_b128 v[166:169], v172 offset:2048
	ds_read_b128 v[174:177], v172 offset:3072
	ds_read_b128 v[178:181], v172 offset:4096
	ds_read_b128 v[182:185], v172 offset:5120
	ds_read_b128 v[204:207], v172 offset:6144
	ds_read_b128 v[208:211], v172 offset:7168
	global_load_lds_dwordx4 v138, s[0:1]
	s_add_i32 m0, s35, 0xe000
	s_nop 0
	global_load_lds_dwordx4 v140, s[0:1]
	s_waitcnt lgkmcnt(8)
	s_barrier
	s_waitcnt lgkmcnt(0)
	v_mfma_f32_16x16x32_bf16 v[126:129], v[142:145], v[158:161], 0
	v_mfma_f32_16x16x32_bf16 v[126:129], v[146:149], v[162:165], v[126:129]
	v_mfma_f32_16x16x32_bf16 v[110:113], v[142:145], v[166:169], 0
	v_mfma_f32_16x16x32_bf16 v[110:113], v[146:149], v[174:177], v[110:113]
	v_mfma_f32_16x16x32_bf16 v[94:97], v[142:145], v[178:181], 0
	v_mfma_f32_16x16x32_bf16 v[94:97], v[146:149], v[182:185], v[94:97]
	v_mfma_f32_16x16x32_bf16 v[78:81], v[142:145], v[204:207], 0
	v_mfma_f32_16x16x32_bf16 v[78:81], v[146:149], v[208:211], v[78:81]
	v_mfma_f32_16x16x32_bf16 v[74:77], v[150:153], v[204:207], 0
	v_mfma_f32_16x16x32_bf16 v[74:77], v[154:157], v[208:211], v[74:77]
	v_mfma_f32_16x16x32_bf16 v[90:93], v[150:153], v[178:181], 0
	v_mfma_f32_16x16x32_bf16 v[90:93], v[154:157], v[182:185], v[90:93]
	v_mfma_f32_16x16x32_bf16 v[106:109], v[150:153], v[166:169], 0
	v_mfma_f32_16x16x32_bf16 v[106:109], v[154:157], v[174:177], v[106:109]
	v_mfma_f32_16x16x32_bf16 v[122:125], v[150:153], v[158:161], 0
	v_mfma_f32_16x16x32_bf16 v[122:125], v[154:157], v[162:165], v[122:125]
	s_barrier
	s_add_i32 s29, 0, 0x14000
	s_add_i32 s28, s28, s34
	s_add_u32 s78, s10, s6
	s_addc_u32 s79, s11, s7
	s_mov_b32 m0, s28
	ds_read_b128 v[212:215], v248 offset:16384
	ds_read_b128 v[216:219], v248 offset:17408
	ds_read_b128 v[220:223], v248 offset:18432
	ds_read_b128 v[224:227], v248 offset:19456
	global_load_lds_dwordx4 v132, s[10:11]
	s_add_i32 m0, s28, 0x2000
	s_nop 0
	global_load_lds_dwordx4 v136, s[10:11]
	s_barrier
	s_waitcnt lgkmcnt(0)
	v_mfma_f32_16x16x32_bf16 v[118:121], v[212:215], v[158:161], 0
	v_mfma_f32_16x16x32_bf16 v[118:121], v[216:219], v[162:165], v[118:121]
	v_mfma_f32_16x16x32_bf16 v[102:105], v[212:215], v[166:169], 0
	v_mfma_f32_16x16x32_bf16 v[102:105], v[216:219], v[174:177], v[102:105]
	v_mfma_f32_16x16x32_bf16 v[86:89], v[212:215], v[178:181], 0
	v_mfma_f32_16x16x32_bf16 v[86:89], v[216:219], v[182:185], v[86:89]
	v_mfma_f32_16x16x32_bf16 v[70:73], v[212:215], v[204:207], 0
	v_mfma_f32_16x16x32_bf16 v[70:73], v[216:219], v[208:211], v[70:73]
	v_mfma_f32_16x16x32_bf16 v[66:69], v[220:223], v[204:207], 0
	v_mfma_f32_16x16x32_bf16 v[66:69], v[224:227], v[208:211], v[66:69]
	v_mfma_f32_16x16x32_bf16 v[82:85], v[220:223], v[178:181], 0
	v_mfma_f32_16x16x32_bf16 v[82:85], v[224:227], v[182:185], v[82:85]
	v_mfma_f32_16x16x32_bf16 v[98:101], v[220:223], v[166:169], 0
	v_mfma_f32_16x16x32_bf16 v[98:101], v[224:227], v[174:177], v[98:101]
	v_mfma_f32_16x16x32_bf16 v[114:117], v[220:223], v[158:161], 0
	v_mfma_f32_16x16x32_bf16 v[114:117], v[224:227], v[162:165], v[114:117]
	s_barrier
	s_mov_b32 m0, s35
	s_add_u32 s80, s4, s6
	s_addc_u32 s81, s5, s7
	ds_read_b128 v[158:161], v172 offset:16384
	ds_read_b128 v[162:165], v172 offset:17408
	ds_read_b128 v[166:169], v172 offset:18432
	ds_read_b128 v[174:177], v172 offset:19456
	ds_read_b128 v[178:181], v172 offset:20480
	ds_read_b128 v[182:185], v172 offset:21504
	ds_read_b128 v[204:207], v172 offset:22528
	ds_read_b128 v[208:211], v172 offset:23552
	global_load_lds_dwordx4 v130, s[4:5]
	s_mov_b32 m0, s40
	s_nop 0
	global_load_lds_dwordx4 v134, s[4:5]
	s_barrier
	s_waitcnt lgkmcnt(0)
	v_mfma_f32_16x16x32_bf16 v[62:65], v[142:145], v[158:161], 0
	v_mfma_f32_16x16x32_bf16 v[62:65], v[146:149], v[162:165], v[62:65]
	v_mfma_f32_16x16x32_bf16 v[46:49], v[142:145], v[166:169], 0
	v_mfma_f32_16x16x32_bf16 v[46:49], v[146:149], v[174:177], v[46:49]
	v_mfma_f32_16x16x32_bf16 v[30:33], v[142:145], v[178:181], 0
	v_mfma_f32_16x16x32_bf16 v[30:33], v[146:149], v[182:185], v[30:33]
	v_mfma_f32_16x16x32_bf16 v[14:17], v[142:145], v[204:207], 0
	v_mfma_f32_16x16x32_bf16 v[14:17], v[146:149], v[208:211], v[14:17]
	v_mfma_f32_16x16x32_bf16 v[10:13], v[150:153], v[204:207], 0
	v_mfma_f32_16x16x32_bf16 v[10:13], v[154:157], v[208:211], v[10:13]
	v_mfma_f32_16x16x32_bf16 v[26:29], v[150:153], v[178:181], 0
	v_mfma_f32_16x16x32_bf16 v[26:29], v[154:157], v[182:185], v[26:29]
	v_mfma_f32_16x16x32_bf16 v[42:45], v[150:153], v[166:169], 0
	v_mfma_f32_16x16x32_bf16 v[42:45], v[154:157], v[174:177], v[42:45]
	v_mfma_f32_16x16x32_bf16 v[58:61], v[150:153], v[158:161], 0
	v_mfma_f32_16x16x32_bf16 v[58:61], v[154:157], v[162:165], v[58:61]
	s_barrier
	s_add_u32 s10, s10, s92
	s_addc_u32 s11, s11, 0
	s_add_i32 s28, s29, s34
	s_add_u32 s58, s10, s6
	s_addc_u32 s59, s11, s7
	s_mov_b32 m0, s28
	s_nop 0
	global_load_lds_dwordx4 v132, s[10:11]
	s_add_i32 m0, s28, 0x2000
	s_nop 0
	global_load_lds_dwordx4 v136, s[10:11]
	s_waitcnt vmcnt(6)
	s_barrier
	v_mfma_f32_16x16x32_bf16 v[54:57], v[212:215], v[158:161], 0
	v_mfma_f32_16x16x32_bf16 v[54:57], v[216:219], v[162:165], v[54:57]
	v_mfma_f32_16x16x32_bf16 v[38:41], v[212:215], v[166:169], 0
	v_mfma_f32_16x16x32_bf16 v[38:41], v[216:219], v[174:177], v[38:41]
	v_mfma_f32_16x16x32_bf16 v[22:25], v[212:215], v[178:181], 0
	v_mfma_f32_16x16x32_bf16 v[22:25], v[216:219], v[182:185], v[22:25]
	v_mfma_f32_16x16x32_bf16 v[6:9], v[212:215], v[204:207], 0
	v_mfma_f32_16x16x32_bf16 v[6:9], v[216:219], v[208:211], v[6:9]
	v_mfma_f32_16x16x32_bf16 v[2:5], v[220:223], v[204:207], 0
	v_mfma_f32_16x16x32_bf16 v[2:5], v[224:227], v[208:211], v[2:5]
	v_mfma_f32_16x16x32_bf16 v[18:21], v[220:223], v[178:181], 0
	v_mfma_f32_16x16x32_bf16 v[18:21], v[224:227], v[182:185], v[18:21]
	v_mfma_f32_16x16x32_bf16 v[34:37], v[220:223], v[166:169], 0
	v_mfma_f32_16x16x32_bf16 v[34:37], v[224:227], v[174:177], v[34:37]
	v_mfma_f32_16x16x32_bf16 v[50:53], v[220:223], v[158:161], 0
	v_mfma_f32_16x16x32_bf16 v[50:53], v[224:227], v[162:165], v[50:53]
	s_barrier
	s_add_i32 s10, 0, 0x18000
	ds_read_b128 v[142:145], v248 offset:32768
	ds_read_b128 v[146:149], v248 offset:33792
	ds_read_b128 v[150:153], v248 offset:34816
	ds_read_b128 v[154:157], v248 offset:35840
	s_add_u32 s4, s4, s92
	s_addc_u32 s5, s5, 0
	s_mov_b32 m0, s41
	ds_read_b128 v[158:161], v172 offset:32768
	ds_read_b128 v[162:165], v172 offset:33792
	ds_read_b128 v[166:169], v172 offset:34816
	ds_read_b128 v[174:177], v172 offset:35840
	ds_read_b128 v[178:181], v172 offset:36864
	ds_read_b128 v[182:185], v172 offset:37888
	ds_read_b128 v[204:207], v172 offset:38912
	ds_read_b128 v[208:211], v172 offset:39936
	global_load_lds_dwordx4 v130, s[4:5]
	s_mov_b32 m0, s42
	s_nop 0
	global_load_lds_dwordx4 v134, s[4:5]
	s_waitcnt lgkmcnt(8)
	s_barrier
	s_waitcnt lgkmcnt(0)
	v_mfma_f32_16x16x32_bf16 v[126:129], v[142:145], v[158:161], v[126:129]
	v_mfma_f32_16x16x32_bf16 v[126:129], v[146:149], v[162:165], v[126:129]
	v_mfma_f32_16x16x32_bf16 v[110:113], v[142:145], v[166:169], v[110:113]
	v_mfma_f32_16x16x32_bf16 v[110:113], v[146:149], v[174:177], v[110:113]
	v_mfma_f32_16x16x32_bf16 v[94:97], v[142:145], v[178:181], v[94:97]
	v_mfma_f32_16x16x32_bf16 v[94:97], v[146:149], v[182:185], v[94:97]
	v_mfma_f32_16x16x32_bf16 v[78:81], v[142:145], v[204:207], v[78:81]
	v_mfma_f32_16x16x32_bf16 v[78:81], v[146:149], v[208:211], v[78:81]
	v_mfma_f32_16x16x32_bf16 v[74:77], v[150:153], v[204:207], v[74:77]
	v_mfma_f32_16x16x32_bf16 v[74:77], v[154:157], v[208:211], v[74:77]
	v_mfma_f32_16x16x32_bf16 v[90:93], v[150:153], v[178:181], v[90:93]
	v_mfma_f32_16x16x32_bf16 v[90:93], v[154:157], v[182:185], v[90:93]
	v_mfma_f32_16x16x32_bf16 v[106:109], v[150:153], v[166:169], v[106:109]
	v_mfma_f32_16x16x32_bf16 v[106:109], v[154:157], v[174:177], v[106:109]
	v_mfma_f32_16x16x32_bf16 v[122:125], v[150:153], v[158:161], v[122:125]
	v_mfma_f32_16x16x32_bf16 v[122:125], v[154:157], v[162:165], v[122:125]
	s_barrier
	s_add_i32 s4, 0, 0x1c000
	s_add_i32 s5, s10, s34
	s_mov_b32 m0, s5
	ds_read_b128 v[212:215], v248 offset:49152
	ds_read_b128 v[216:219], v248 offset:50176
	ds_read_b128 v[220:223], v248 offset:51200
	ds_read_b128 v[224:227], v248 offset:52224
	global_load_lds_dwordx4 v132, s[78:79]
	s_add_i32 m0, s5, 0x2000
	s_nop 0
	global_load_lds_dwordx4 v136, s[78:79]
	s_barrier
	s_waitcnt lgkmcnt(0)
	v_mfma_f32_16x16x32_bf16 v[118:121], v[212:215], v[158:161], v[118:121]
	v_mfma_f32_16x16x32_bf16 v[118:121], v[216:219], v[162:165], v[118:121]
	v_mfma_f32_16x16x32_bf16 v[102:105], v[212:215], v[166:169], v[102:105]
	v_mfma_f32_16x16x32_bf16 v[102:105], v[216:219], v[174:177], v[102:105]
	v_mfma_f32_16x16x32_bf16 v[86:89], v[212:215], v[178:181], v[86:89]
	v_mfma_f32_16x16x32_bf16 v[86:89], v[216:219], v[182:185], v[86:89]
	v_mfma_f32_16x16x32_bf16 v[70:73], v[212:215], v[204:207], v[70:73]
	v_mfma_f32_16x16x32_bf16 v[70:73], v[216:219], v[208:211], v[70:73]
	v_mfma_f32_16x16x32_bf16 v[66:69], v[220:223], v[204:207], v[66:69]
	v_mfma_f32_16x16x32_bf16 v[66:69], v[224:227], v[208:211], v[66:69]
	v_mfma_f32_16x16x32_bf16 v[82:85], v[220:223], v[178:181], v[82:85]
	v_mfma_f32_16x16x32_bf16 v[82:85], v[224:227], v[182:185], v[82:85]
	v_mfma_f32_16x16x32_bf16 v[98:101], v[220:223], v[166:169], v[98:101]
	v_mfma_f32_16x16x32_bf16 v[98:101], v[224:227], v[174:177], v[98:101]
	v_mfma_f32_16x16x32_bf16 v[114:117], v[220:223], v[158:161], v[114:117]
	v_mfma_f32_16x16x32_bf16 v[114:117], v[224:227], v[162:165], v[114:117]
	s_barrier
	s_mov_b32 m0, s46
	ds_read_b128 v[158:161], v172 offset:49152
	ds_read_b128 v[162:165], v172 offset:50176
	ds_read_b128 v[166:169], v172 offset:51200
	ds_read_b128 v[174:177], v172 offset:52224
	ds_read_b128 v[178:181], v172 offset:53248
	ds_read_b128 v[182:185], v172 offset:54272
	ds_read_b128 v[204:207], v172 offset:55296
	ds_read_b128 v[208:211], v172 offset:56320
	global_load_lds_dwordx4 v130, s[80:81]
	s_mov_b32 m0, s47
	s_nop 0
	global_load_lds_dwordx4 v134, s[80:81]
	s_barrier
	s_waitcnt lgkmcnt(0)
	v_mfma_f32_16x16x32_bf16 v[62:65], v[142:145], v[158:161], v[62:65]
	v_mfma_f32_16x16x32_bf16 v[62:65], v[146:149], v[162:165], v[62:65]
	v_mfma_f32_16x16x32_bf16 v[46:49], v[142:145], v[166:169], v[46:49]
	v_mfma_f32_16x16x32_bf16 v[46:49], v[146:149], v[174:177], v[46:49]
	v_mfma_f32_16x16x32_bf16 v[30:33], v[142:145], v[178:181], v[30:33]
	v_mfma_f32_16x16x32_bf16 v[30:33], v[146:149], v[182:185], v[30:33]
	v_mfma_f32_16x16x32_bf16 v[14:17], v[142:145], v[204:207], v[14:17]
	v_mfma_f32_16x16x32_bf16 v[14:17], v[146:149], v[208:211], v[14:17]
	v_mfma_f32_16x16x32_bf16 v[10:13], v[150:153], v[204:207], v[10:13]
	v_mfma_f32_16x16x32_bf16 v[10:13], v[154:157], v[208:211], v[10:13]
	v_mfma_f32_16x16x32_bf16 v[26:29], v[150:153], v[178:181], v[26:29]
	v_mfma_f32_16x16x32_bf16 v[26:29], v[154:157], v[182:185], v[26:29]
	v_mfma_f32_16x16x32_bf16 v[42:45], v[150:153], v[166:169], v[42:45]
	v_mfma_f32_16x16x32_bf16 v[42:45], v[154:157], v[174:177], v[42:45]
	v_mfma_f32_16x16x32_bf16 v[58:61], v[150:153], v[158:161], v[58:61]
	v_mfma_f32_16x16x32_bf16 v[58:61], v[154:157], v[162:165], v[58:61]
	s_barrier
	s_add_i32 s4, s4, s34
	s_mov_b32 m0, s4
	s_nop 0
	global_load_lds_dwordx4 v132, s[58:59]
	s_add_i32 m0, s4, 0x2000
	s_nop 0
	global_load_lds_dwordx4 v136, s[58:59]
	s_add_u32 s0, s0, 0x100
	s_addc_u32 s1, s1, 0
	s_add_u32 s12, s12, 0x100
	s_addc_u32 s13, s13, 0
	s_cmp_ge_u32 s27, s43
	s_mov_b32 s4, s27
	s_waitcnt vmcnt(6)
	s_barrier
	v_mfma_f32_16x16x32_bf16 v[54:57], v[212:215], v[158:161], v[54:57]
	v_mfma_f32_16x16x32_bf16 v[54:57], v[216:219], v[162:165], v[54:57]
	v_mfma_f32_16x16x32_bf16 v[38:41], v[212:215], v[166:169], v[38:41]
	v_mfma_f32_16x16x32_bf16 v[38:41], v[216:219], v[174:177], v[38:41]
	v_mfma_f32_16x16x32_bf16 v[22:25], v[212:215], v[178:181], v[22:25]
	v_mfma_f32_16x16x32_bf16 v[22:25], v[216:219], v[182:185], v[22:25]
	v_mfma_f32_16x16x32_bf16 v[6:9], v[212:215], v[204:207], v[6:9]
	v_mfma_f32_16x16x32_bf16 v[6:9], v[216:219], v[208:211], v[6:9]
	v_mfma_f32_16x16x32_bf16 v[2:5], v[220:223], v[204:207], v[2:5]
	v_mfma_f32_16x16x32_bf16 v[2:5], v[224:227], v[208:211], v[2:5]
	v_mfma_f32_16x16x32_bf16 v[18:21], v[220:223], v[178:181], v[18:21]
	v_mfma_f32_16x16x32_bf16 v[18:21], v[224:227], v[182:185], v[18:21]
	v_mfma_f32_16x16x32_bf16 v[34:37], v[220:223], v[166:169], v[34:37]
	v_mfma_f32_16x16x32_bf16 v[34:37], v[224:227], v[174:177], v[34:37]
	v_mfma_f32_16x16x32_bf16 v[50:53], v[220:223], v[158:161], v[50:53]
	v_mfma_f32_16x16x32_bf16 v[50:53], v[224:227], v[162:165], v[50:53]
	s_barrier
	s_cbranch_scc1 .Lkexit_806
.LBB0_806:
	s_add_i32 s27, s4, 2
	s_add_u32 s10, s0, 0x80
	s_addc_u32 s5, s1, 0
	s_add_i32 s28, 0, 0x10000
	ds_read_b128 v[142:145], v248
	ds_read_b128 v[146:149], v248 offset:1024
	ds_read_b128 v[150:153], v248 offset:2048
	ds_read_b128 v[154:157], v248 offset:3072
	s_cmp_eq_u32 s48, s4
	s_cselect_b32 s4, s22, s10
	s_cselect_b32 s5, s23, s5
	s_cselect_b32 s11, s25, s13
	s_cselect_b32 s10, s24, s12
	s_add_i32 m0, s35, 0xc000
	ds_read_b128 v[158:161], v172
	ds_read_b128 v[162:165], v172 offset:1024
	ds_read_b128 v[166:169], v172 offset:2048
	ds_read_b128 v[174:177], v172 offset:3072
	ds_read_b128 v[178:181], v172 offset:4096
	ds_read_b128 v[182:185], v172 offset:5120
	ds_read_b128 v[204:207], v172 offset:6144
	ds_read_b128 v[208:211], v172 offset:7168
	global_load_lds_dwordx4 v138, s[0:1]
	s_add_i32 m0, s35, 0xe000
	s_nop 0
	global_load_lds_dwordx4 v140, s[0:1]
	s_waitcnt lgkmcnt(8)
	s_barrier
	s_waitcnt lgkmcnt(0)
	v_mfma_f32_16x16x32_bf16 v[126:129], v[142:145], v[158:161], v[126:129]
	v_mfma_f32_16x16x32_bf16 v[126:129], v[146:149], v[162:165], v[126:129]
	v_mfma_f32_16x16x32_bf16 v[110:113], v[142:145], v[166:169], v[110:113]
	v_mfma_f32_16x16x32_bf16 v[110:113], v[146:149], v[174:177], v[110:113]
	v_mfma_f32_16x16x32_bf16 v[94:97], v[142:145], v[178:181], v[94:97]
	v_mfma_f32_16x16x32_bf16 v[94:97], v[146:149], v[182:185], v[94:97]
	v_mfma_f32_16x16x32_bf16 v[78:81], v[142:145], v[204:207], v[78:81]
	v_mfma_f32_16x16x32_bf16 v[78:81], v[146:149], v[208:211], v[78:81]
	v_mfma_f32_16x16x32_bf16 v[74:77], v[150:153], v[204:207], v[74:77]
	v_mfma_f32_16x16x32_bf16 v[74:77], v[154:157], v[208:211], v[74:77]
	v_mfma_f32_16x16x32_bf16 v[90:93], v[150:153], v[178:181], v[90:93]
	v_mfma_f32_16x16x32_bf16 v[90:93], v[154:157], v[182:185], v[90:93]
	v_mfma_f32_16x16x32_bf16 v[106:109], v[150:153], v[166:169], v[106:109]
	v_mfma_f32_16x16x32_bf16 v[106:109], v[154:157], v[174:177], v[106:109]
	v_mfma_f32_16x16x32_bf16 v[122:125], v[150:153], v[158:161], v[122:125]
	v_mfma_f32_16x16x32_bf16 v[122:125], v[154:157], v[162:165], v[122:125]
	s_barrier
	s_add_i32 s29, 0, 0x14000
	s_add_i32 s28, s28, s34
	s_add_u32 s78, s10, s6
	s_addc_u32 s79, s11, s7
	s_mov_b32 m0, s28
	ds_read_b128 v[212:215], v248 offset:16384
	ds_read_b128 v[216:219], v248 offset:17408
	ds_read_b128 v[220:223], v248 offset:18432
	ds_read_b128 v[224:227], v248 offset:19456
	global_load_lds_dwordx4 v132, s[10:11]
	s_add_i32 m0, s28, 0x2000
	s_nop 0
	global_load_lds_dwordx4 v136, s[10:11]
	s_barrier
	s_waitcnt lgkmcnt(0)
	v_mfma_f32_16x16x32_bf16 v[118:121], v[212:215], v[158:161], v[118:121]
	v_mfma_f32_16x16x32_bf16 v[118:121], v[216:219], v[162:165], v[118:121]
	v_mfma_f32_16x16x32_bf16 v[102:105], v[212:215], v[166:169], v[102:105]
	v_mfma_f32_16x16x32_bf16 v[102:105], v[216:219], v[174:177], v[102:105]
	v_mfma_f32_16x16x32_bf16 v[86:89], v[212:215], v[178:181], v[86:89]
	v_mfma_f32_16x16x32_bf16 v[86:89], v[216:219], v[182:185], v[86:89]
	v_mfma_f32_16x16x32_bf16 v[70:73], v[212:215], v[204:207], v[70:73]
	v_mfma_f32_16x16x32_bf16 v[70:73], v[216:219], v[208:211], v[70:73]
	v_mfma_f32_16x16x32_bf16 v[66:69], v[220:223], v[204:207], v[66:69]
	v_mfma_f32_16x16x32_bf16 v[66:69], v[224:227], v[208:211], v[66:69]
	v_mfma_f32_16x16x32_bf16 v[82:85], v[220:223], v[178:181], v[82:85]
	v_mfma_f32_16x16x32_bf16 v[82:85], v[224:227], v[182:185], v[82:85]
	v_mfma_f32_16x16x32_bf16 v[98:101], v[220:223], v[166:169], v[98:101]
	v_mfma_f32_16x16x32_bf16 v[98:101], v[224:227], v[174:177], v[98:101]
	v_mfma_f32_16x16x32_bf16 v[114:117], v[220:223], v[158:161], v[114:117]
	v_mfma_f32_16x16x32_bf16 v[114:117], v[224:227], v[162:165], v[114:117]
	s_barrier
	s_mov_b32 m0, s35
	s_add_u32 s80, s4, s6
	s_addc_u32 s81, s5, s7
	ds_read_b128 v[158:161], v172 offset:16384
	ds_read_b128 v[162:165], v172 offset:17408
	ds_read_b128 v[166:169], v172 offset:18432
	ds_read_b128 v[174:177], v172 offset:19456
	ds_read_b128 v[178:181], v172 offset:20480
	ds_read_b128 v[182:185], v172 offset:21504
	ds_read_b128 v[204:207], v172 offset:22528
	ds_read_b128 v[208:211], v172 offset:23552
	global_load_lds_dwordx4 v130, s[4:5]
	s_mov_b32 m0, s40
	s_nop 0
	global_load_lds_dwordx4 v134, s[4:5]
	s_barrier
	s_waitcnt lgkmcnt(0)
	v_mfma_f32_16x16x32_bf16 v[62:65], v[142:145], v[158:161], v[62:65]
	v_mfma_f32_16x16x32_bf16 v[62:65], v[146:149], v[162:165], v[62:65]
	v_mfma_f32_16x16x32_bf16 v[46:49], v[142:145], v[166:169], v[46:49]
	v_mfma_f32_16x16x32_bf16 v[46:49], v[146:149], v[174:177], v[46:49]
	v_mfma_f32_16x16x32_bf16 v[30:33], v[142:145], v[178:181], v[30:33]
	v_mfma_f32_16x16x32_bf16 v[30:33], v[146:149], v[182:185], v[30:33]
	v_mfma_f32_16x16x32_bf16 v[14:17], v[142:145], v[204:207], v[14:17]
	v_mfma_f32_16x16x32_bf16 v[14:17], v[146:149], v[208:211], v[14:17]
	v_mfma_f32_16x16x32_bf16 v[10:13], v[150:153], v[204:207], v[10:13]
	v_mfma_f32_16x16x32_bf16 v[10:13], v[154:157], v[208:211], v[10:13]
	v_mfma_f32_16x16x32_bf16 v[26:29], v[150:153], v[178:181], v[26:29]
	v_mfma_f32_16x16x32_bf16 v[26:29], v[154:157], v[182:185], v[26:29]
	v_mfma_f32_16x16x32_bf16 v[42:45], v[150:153], v[166:169], v[42:45]
	v_mfma_f32_16x16x32_bf16 v[42:45], v[154:157], v[174:177], v[42:45]
	v_mfma_f32_16x16x32_bf16 v[58:61], v[150:153], v[158:161], v[58:61]
	v_mfma_f32_16x16x32_bf16 v[58:61], v[154:157], v[162:165], v[58:61]
	s_barrier
	s_add_u32 s10, s10, s92
	s_addc_u32 s11, s11, 0
	s_add_i32 s28, s29, s34
	s_add_u32 s58, s10, s6
	s_addc_u32 s59, s11, s7
	s_mov_b32 m0, s28
	s_nop 0
	global_load_lds_dwordx4 v132, s[10:11]
	s_add_i32 m0, s28, 0x2000
	s_nop 0
	global_load_lds_dwordx4 v136, s[10:11]
	s_waitcnt vmcnt(6)
	s_barrier
	v_mfma_f32_16x16x32_bf16 v[54:57], v[212:215], v[158:161], v[54:57]
	v_mfma_f32_16x16x32_bf16 v[54:57], v[216:219], v[162:165], v[54:57]
	v_mfma_f32_16x16x32_bf16 v[38:41], v[212:215], v[166:169], v[38:41]
	v_mfma_f32_16x16x32_bf16 v[38:41], v[216:219], v[174:177], v[38:41]
	v_mfma_f32_16x16x32_bf16 v[22:25], v[212:215], v[178:181], v[22:25]
	v_mfma_f32_16x16x32_bf16 v[22:25], v[216:219], v[182:185], v[22:25]
	v_mfma_f32_16x16x32_bf16 v[6:9], v[212:215], v[204:207], v[6:9]
	v_mfma_f32_16x16x32_bf16 v[6:9], v[216:219], v[208:211], v[6:9]
	v_mfma_f32_16x16x32_bf16 v[2:5], v[220:223], v[204:207], v[2:5]
	v_mfma_f32_16x16x32_bf16 v[2:5], v[224:227], v[208:211], v[2:5]
	v_mfma_f32_16x16x32_bf16 v[18:21], v[220:223], v[178:181], v[18:21]
	v_mfma_f32_16x16x32_bf16 v[18:21], v[224:227], v[182:185], v[18:21]
	v_mfma_f32_16x16x32_bf16 v[34:37], v[220:223], v[166:169], v[34:37]
	v_mfma_f32_16x16x32_bf16 v[34:37], v[224:227], v[174:177], v[34:37]
	v_mfma_f32_16x16x32_bf16 v[50:53], v[220:223], v[158:161], v[50:53]
	v_mfma_f32_16x16x32_bf16 v[50:53], v[224:227], v[162:165], v[50:53]
	s_barrier
	s_add_i32 s10, 0, 0x18000
	ds_read_b128 v[142:145], v248 offset:32768
	ds_read_b128 v[146:149], v248 offset:33792
	ds_read_b128 v[150:153], v248 offset:34816
	ds_read_b128 v[154:157], v248 offset:35840
	s_add_u32 s4, s4, s92
	s_addc_u32 s5, s5, 0
	s_mov_b32 m0, s41
	ds_read_b128 v[158:161], v172 offset:32768
	ds_read_b128 v[162:165], v172 offset:33792
	ds_read_b128 v[166:169], v172 offset:34816
	ds_read_b128 v[174:177], v172 offset:35840
	ds_read_b128 v[178:181], v172 offset:36864
	ds_read_b128 v[182:185], v172 offset:37888
	ds_read_b128 v[204:207], v172 offset:38912
	ds_read_b128 v[208:211], v172 offset:39936
	global_load_lds_dwordx4 v130, s[4:5]
	s_mov_b32 m0, s42
	s_nop 0
	global_load_lds_dwordx4 v134, s[4:5]
	s_waitcnt lgkmcnt(8)
	s_barrier
	s_waitcnt lgkmcnt(0)
	v_mfma_f32_16x16x32_bf16 v[126:129], v[142:145], v[158:161], v[126:129]
	v_mfma_f32_16x16x32_bf16 v[126:129], v[146:149], v[162:165], v[126:129]
	v_mfma_f32_16x16x32_bf16 v[110:113], v[142:145], v[166:169], v[110:113]
	v_mfma_f32_16x16x32_bf16 v[110:113], v[146:149], v[174:177], v[110:113]
	v_mfma_f32_16x16x32_bf16 v[94:97], v[142:145], v[178:181], v[94:97]
	v_mfma_f32_16x16x32_bf16 v[94:97], v[146:149], v[182:185], v[94:97]
	v_mfma_f32_16x16x32_bf16 v[78:81], v[142:145], v[204:207], v[78:81]
	v_mfma_f32_16x16x32_bf16 v[78:81], v[146:149], v[208:211], v[78:81]
	v_mfma_f32_16x16x32_bf16 v[74:77], v[150:153], v[204:207], v[74:77]
	v_mfma_f32_16x16x32_bf16 v[74:77], v[154:157], v[208:211], v[74:77]
	v_mfma_f32_16x16x32_bf16 v[90:93], v[150:153], v[178:181], v[90:93]
	v_mfma_f32_16x16x32_bf16 v[90:93], v[154:157], v[182:185], v[90:93]
	v_mfma_f32_16x16x32_bf16 v[106:109], v[150:153], v[166:169], v[106:109]
	v_mfma_f32_16x16x32_bf16 v[106:109], v[154:157], v[174:177], v[106:109]
	v_mfma_f32_16x16x32_bf16 v[122:125], v[150:153], v[158:161], v[122:125]
	v_mfma_f32_16x16x32_bf16 v[122:125], v[154:157], v[162:165], v[122:125]
	s_barrier
	s_add_i32 s4, 0, 0x1c000
	s_add_i32 s5, s10, s34
	s_mov_b32 m0, s5
	ds_read_b128 v[212:215], v248 offset:49152
	ds_read_b128 v[216:219], v248 offset:50176
	ds_read_b128 v[220:223], v248 offset:51200
	ds_read_b128 v[224:227], v248 offset:52224
	global_load_lds_dwordx4 v132, s[78:79]
	s_add_i32 m0, s5, 0x2000
	s_nop 0
	global_load_lds_dwordx4 v136, s[78:79]
	s_barrier
	s_waitcnt lgkmcnt(0)
	v_mfma_f32_16x16x32_bf16 v[118:121], v[212:215], v[158:161], v[118:121]
	v_mfma_f32_16x16x32_bf16 v[118:121], v[216:219], v[162:165], v[118:121]
	v_mfma_f32_16x16x32_bf16 v[102:105], v[212:215], v[166:169], v[102:105]
	v_mfma_f32_16x16x32_bf16 v[102:105], v[216:219], v[174:177], v[102:105]
	v_mfma_f32_16x16x32_bf16 v[86:89], v[212:215], v[178:181], v[86:89]
	v_mfma_f32_16x16x32_bf16 v[86:89], v[216:219], v[182:185], v[86:89]
	v_mfma_f32_16x16x32_bf16 v[70:73], v[212:215], v[204:207], v[70:73]
	v_mfma_f32_16x16x32_bf16 v[70:73], v[216:219], v[208:211], v[70:73]
	v_mfma_f32_16x16x32_bf16 v[66:69], v[220:223], v[204:207], v[66:69]
	v_mfma_f32_16x16x32_bf16 v[66:69], v[224:227], v[208:211], v[66:69]
	v_mfma_f32_16x16x32_bf16 v[82:85], v[220:223], v[178:181], v[82:85]
	v_mfma_f32_16x16x32_bf16 v[82:85], v[224:227], v[182:185], v[82:85]
	v_mfma_f32_16x16x32_bf16 v[98:101], v[220:223], v[166:169], v[98:101]
	v_mfma_f32_16x16x32_bf16 v[98:101], v[224:227], v[174:177], v[98:101]
	v_mfma_f32_16x16x32_bf16 v[114:117], v[220:223], v[158:161], v[114:117]
	v_mfma_f32_16x16x32_bf16 v[114:117], v[224:227], v[162:165], v[114:117]
	s_barrier
	s_mov_b32 m0, s46
	ds_read_b128 v[158:161], v172 offset:49152
	ds_read_b128 v[162:165], v172 offset:50176
	ds_read_b128 v[166:169], v172 offset:51200
	ds_read_b128 v[174:177], v172 offset:52224
	ds_read_b128 v[178:181], v172 offset:53248
	ds_read_b128 v[182:185], v172 offset:54272
	ds_read_b128 v[204:207], v172 offset:55296
	ds_read_b128 v[208:211], v172 offset:56320
	global_load_lds_dwordx4 v130, s[80:81]
	s_mov_b32 m0, s47
	s_nop 0
	global_load_lds_dwordx4 v134, s[80:81]
	s_barrier
	s_waitcnt lgkmcnt(0)
	v_mfma_f32_16x16x32_bf16 v[62:65], v[142:145], v[158:161], v[62:65]
	v_mfma_f32_16x16x32_bf16 v[62:65], v[146:149], v[162:165], v[62:65]
	v_mfma_f32_16x16x32_bf16 v[46:49], v[142:145], v[166:169], v[46:49]
	v_mfma_f32_16x16x32_bf16 v[46:49], v[146:149], v[174:177], v[46:49]
	v_mfma_f32_16x16x32_bf16 v[30:33], v[142:145], v[178:181], v[30:33]
	v_mfma_f32_16x16x32_bf16 v[30:33], v[146:149], v[182:185], v[30:33]
	v_mfma_f32_16x16x32_bf16 v[14:17], v[142:145], v[204:207], v[14:17]
	v_mfma_f32_16x16x32_bf16 v[14:17], v[146:149], v[208:211], v[14:17]
	v_mfma_f32_16x16x32_bf16 v[10:13], v[150:153], v[204:207], v[10:13]
	v_mfma_f32_16x16x32_bf16 v[10:13], v[154:157], v[208:211], v[10:13]
	v_mfma_f32_16x16x32_bf16 v[26:29], v[150:153], v[178:181], v[26:29]
	v_mfma_f32_16x16x32_bf16 v[26:29], v[154:157], v[182:185], v[26:29]
	v_mfma_f32_16x16x32_bf16 v[42:45], v[150:153], v[166:169], v[42:45]
	v_mfma_f32_16x16x32_bf16 v[42:45], v[154:157], v[174:177], v[42:45]
	v_mfma_f32_16x16x32_bf16 v[58:61], v[150:153], v[158:161], v[58:61]
	v_mfma_f32_16x16x32_bf16 v[58:61], v[154:157], v[162:165], v[58:61]
	s_barrier
	s_add_i32 s4, s4, s34
	s_mov_b32 m0, s4
	s_nop 0
	global_load_lds_dwordx4 v132, s[58:59]
	s_add_i32 m0, s4, 0x2000
	s_nop 0
	global_load_lds_dwordx4 v136, s[58:59]
	s_add_u32 s0, s0, 0x100
	s_addc_u32 s1, s1, 0
	s_add_u32 s12, s12, 0x100
	s_addc_u32 s13, s13, 0
	s_cmp_ge_u32 s27, s43
	s_mov_b32 s4, s27
	s_waitcnt vmcnt(6)
	s_barrier
	v_mfma_f32_16x16x32_bf16 v[54:57], v[212:215], v[158:161], v[54:57]
	v_mfma_f32_16x16x32_bf16 v[54:57], v[216:219], v[162:165], v[54:57]
	v_mfma_f32_16x16x32_bf16 v[38:41], v[212:215], v[166:169], v[38:41]
	v_mfma_f32_16x16x32_bf16 v[38:41], v[216:219], v[174:177], v[38:41]
	v_mfma_f32_16x16x32_bf16 v[22:25], v[212:215], v[178:181], v[22:25]
	v_mfma_f32_16x16x32_bf16 v[22:25], v[216:219], v[182:185], v[22:25]
	v_mfma_f32_16x16x32_bf16 v[6:9], v[212:215], v[204:207], v[6:9]
	v_mfma_f32_16x16x32_bf16 v[6:9], v[216:219], v[208:211], v[6:9]
	v_mfma_f32_16x16x32_bf16 v[2:5], v[220:223], v[204:207], v[2:5]
	v_mfma_f32_16x16x32_bf16 v[2:5], v[224:227], v[208:211], v[2:5]
	v_mfma_f32_16x16x32_bf16 v[18:21], v[220:223], v[178:181], v[18:21]
	v_mfma_f32_16x16x32_bf16 v[18:21], v[224:227], v[182:185], v[18:21]
	v_mfma_f32_16x16x32_bf16 v[34:37], v[220:223], v[166:169], v[34:37]
	v_mfma_f32_16x16x32_bf16 v[34:37], v[224:227], v[174:177], v[34:37]
	v_mfma_f32_16x16x32_bf16 v[50:53], v[220:223], v[158:161], v[50:53]
	v_mfma_f32_16x16x32_bf16 v[50:53], v[224:227], v[162:165], v[50:53]
	s_barrier
	s_cbranch_scc0 .LBB0_806
